# expert tables interleaved: each expert's int4 U row and fp4 V row stored as one contiguous 2-KB record (P3 conversion writers and P8 gathers changed together)
# baseline (speedup 1.0000x reference)
.LBB0_439:
	s_or_b64 exec, exec, s[4:5]
	s_add_u32 s20, s94, 0x8008000
	s_addc_u32 s21, s95, 0
	s_add_u32 s24, s94, 0x13288000
	s_addc_u32 s25, s95, 0
	s_add_u32 s33, s94, 0x1c708000
	s_addc_u32 s62, s95, 0
	s_add_u32 s63, s94, 0x1c508000
	s_addc_u32 s52, s95, 0
	s_add_u32 s53, s94, 0x19f08000
	s_load_dwordx16 s[36:51], s[0:1], 0xc0
	s_addc_u32 s54, s95, 0
	s_add_u32 s55, s94, 0x1b008000
	v_and_b32_e32 v2, 32, v204
	s_addc_u32 s60, s95, 0
	v_cmp_eq_u32_e64 s[4:5], 0, v2
	v_and_b32_e32 v2, 63, v204
	s_add_u32 s26, s94, 0x8400
	v_mov_b32_e32 v1, 0
	v_cmp_eq_u32_e64 s[6:7], 0, v0
	v_lshlrev_b32_e32 v0, 6, v2
	s_waitcnt lgkmcnt(0)
	s_mov_b64 s[28:29], s[48:49]
	s_addc_u32 s27, s95, 0
	v_lshl_add_u64 v[172:173], s[28:29], 0, v[0:1]
	s_add_u32 s28, s94, 0x1cb08000
	s_mov_b64 s[30:31], s[50:51]
	s_addc_u32 s29, s95, 0
	s_waitcnt vmcnt(63) expcnt(7) lgkmcnt(15)
	s_barrier
	ds_read_b32 v166, v1 offset:20
	v_lshl_add_u64 v[170:171], s[30:31], 0, v[0:1]
	s_add_u32 s30, s94, 0x8000
	s_addc_u32 s31, s95, 0
	s_add_u32 s34, s94, 0x1cb18000
	s_addc_u32 s35, s95, 0
	s_add_u32 s61, s94, 0x8255000
	s_mov_b32 s19, 0
	v_lshrrev_b32_e32 v180, 6, v204
	v_cmp_eq_u32_e64 s[8:9], 0, v2
	v_lshlrev_b32_e32 v168, 3, v2
	v_mov_b32_e32 v169, v1
	s_waitcnt lgkmcnt(0)
	v_mov_b32_e32 v167, v166
	s_addc_u32 s64, s95, 0
	s_movk_i32 s65, 0x5400
	s_movk_i32 s66, 0x110
	s_mov_b64 s[40:41], 0x1000
	s_movk_i32 s67, 0x1000
	s_mov_b32 s68, 0x54000
	s_mov_b32 s69, 0x55000
	s_mov_b32 s70, 0xa8000
	s_mov_b32 s71, 0xa9000
	s_mov_b32 s72, 0xfc000
	s_mov_b32 s73, 0xfd000
	s_movk_i32 s74, 0x120
	s_movk_i32 s75, 0x80
	v_mov_b32_e32 v181, 0x358637bd
	s_mov_b32 s78, 0x800000
	s_mov_b32 s23, 0x13288000
	s_movk_i32 s80, 0x2000
	s_movk_i32 s81, 0x4000
	s_movk_i32 s86, 0x6000
	s_mov_b32 s87, 0x8000
	s_mov_b32 s88, 0xa000
	s_mov_b32 s89, 0xc000
	s_mov_b32 s90, 0xe000
	s_mov_b32 s91, 0x10000
	s_mov_b32 s79, 0x18000
	s_mov_b32 s3, 0xc0e00000
	v_mov_b32_e32 v182, 0x5400
	v_mov_b32_e32 v183, 0x40e00000
	s_branch .LBB0_442

.LBB0_561:
	s_or_b64 exec, exec, s[10:11]
	v_div_scale_f32 v36, s[10:11], v0, v0, 1.0
	v_rcp_f32_e32 v37, v36
	v_div_scale_f32 v38, vcc, 1.0, v0, 1.0
	v_fma_f32 v39, -v36, v37, 1.0
	v_fmac_f32_e32 v37, v39, v37
	v_mul_f32_e32 v39, v38, v37
	v_fma_f32 v40, -v36, v39, v38
	v_fmac_f32_e32 v39, v40, v37
	v_fma_f32 v36, -v36, v39, v38
	v_div_fmas_f32 v36, v36, v37, v39
	v_div_fixup_f32 v0, v36, v0, 1.0
	v_mul_f32_e32 v30, v30, v0
	v_mul_f32_e32 v31, v31, v0
	v_mul_f32_e32 v32, v32, v0
	v_mul_f32_e32 v14, v14, v0
	v_mul_f32_e32 v15, v15, v0
	v_mul_f32_e32 v16, v16, v0
	v_rndne_f32_e32 v30, v30
	v_rndne_f32_e32 v31, v31
	v_rndne_f32_e32 v32, v32
	v_mul_f32_e32 v33, v33, v0
	v_mul_f32_e32 v29, v29, v0
	v_rndne_f32_e32 v14, v14
	v_rndne_f32_e32 v15, v15
	v_rndne_f32_e32 v16, v16
	v_mul_f32_e32 v17, v17, v0
	v_mul_f32_e32 v9, v9, v0
	v_med3_f32 v30, v30, s3, v183
	v_med3_f32 v31, v31, s3, v183
	v_med3_f32 v32, v32, s3, v183
	v_rndne_f32_e32 v33, v33
	v_mul_f32_e32 v26, v26, v0
	v_mul_f32_e32 v27, v27, v0
	v_rndne_f32_e32 v29, v29
	v_med3_f32 v14, v14, s3, v183
	v_med3_f32 v15, v15, s3, v183
	v_med3_f32 v16, v16, s3, v183
	v_rndne_f32_e32 v17, v17
	v_mul_f32_e32 v6, v6, v0
	v_mul_f32_e32 v7, v7, v0
	v_rndne_f32_e32 v9, v9
	v_cvt_i32_f32_e32 v30, v30
	v_cvt_i32_f32_e32 v31, v31
	v_cvt_i32_f32_e32 v32, v32
	v_med3_f32 v33, v33, s3, v183
	v_rndne_f32_e32 v26, v26
	v_rndne_f32_e32 v27, v27
	v_mul_f32_e32 v28, v28, v0
	v_med3_f32 v29, v29, s3, v183
	v_cvt_i32_f32_e32 v14, v14
	v_cvt_i32_f32_e32 v15, v15
	v_cvt_i32_f32_e32 v16, v16
	v_med3_f32 v17, v17, s3, v183
	v_rndne_f32_e32 v6, v6
	v_rndne_f32_e32 v7, v7
	v_mul_f32_e32 v8, v8, v0
	v_med3_f32 v9, v9, s3, v183
	v_cvt_i32_f32_e32 v33, v33
	v_med3_f32 v26, v26, s3, v183
	v_med3_f32 v27, v27, s3, v183
	v_rndne_f32_e32 v28, v28
	v_cvt_i32_f32_e32 v29, v29
	v_cvt_i32_f32_e32 v17, v17
	v_med3_f32 v6, v6, s3, v183
	v_med3_f32 v7, v7, s3, v183
	v_rndne_f32_e32 v8, v8
	v_cvt_i32_f32_e32 v9, v9
	v_cvt_i32_f32_sdwa v26, v26 dst_sel:WORD_1 dst_unused:UNUSED_PAD src0_sel:DWORD
	v_cvt_i32_f32_e32 v27, v27
	v_med3_f32 v28, v28, s3, v183
	v_cvt_i32_f32_sdwa v6, v6 dst_sel:WORD_1 dst_unused:UNUSED_PAD src0_sel:DWORD
	v_cvt_i32_f32_e32 v7, v7
	v_med3_f32 v8, v8, s3, v183
	v_cvt_i32_f32_sdwa v28, v28 dst_sel:BYTE_3 dst_unused:UNUSED_PAD src0_sel:DWORD
	v_cvt_i32_f32_sdwa v8, v8 dst_sel:BYTE_3 dst_unused:UNUSED_PAD src0_sel:DWORD
	v_and_b32_e32 v30, 15, v30
	v_lshlrev_b32_e32 v31, 4, v31
	v_lshlrev_b32_e32 v32, 8, v32
	v_and_b32_e32 v14, 15, v14
	v_lshlrev_b32_e32 v15, 4, v15
	v_lshlrev_b32_e32 v16, 8, v16
	v_and_b32_e32 v31, 0xf0, v31
	v_and_b32_e32 v32, 0xf00, v32
	v_lshlrev_b32_e32 v33, 12, v33
	v_lshl_or_b32 v29, v29, 28, v30
	v_and_b32_e32 v15, 0xf0, v15
	v_and_b32_e32 v16, 0xf00, v16
	v_lshlrev_b32_e32 v17, 12, v17
	v_lshl_or_b32 v9, v9, 28, v14
	v_and_b32_e32 v33, 0xf000, v33
	v_and_b32_e32 v26, 0xf0000, v26
	v_lshlrev_b32_e32 v27, 20, v27
	v_or3_b32 v29, v29, v31, v32
	v_and_b32_e32 v17, 0xf000, v17
	v_and_b32_e32 v6, 0xf0000, v6
	v_lshlrev_b32_e32 v7, 20, v7
	v_or3_b32 v9, v9, v15, v16
	v_and_b32_e32 v27, 0xf00000, v27
	v_and_b32_e32 v28, 0xf000000, v28
	v_or3_b32 v26, v29, v33, v26
	v_and_b32_e32 v7, 0xf00000, v7
	v_and_b32_e32 v8, 0xf000000, v8
	v_or3_b32 v6, v9, v17, v6
	v_or3_b32 v26, v26, v27, v28
	v_or3_b32 v27, v6, v7, v8
	v_mul_f32_e32 v6, v18, v0
	v_mul_f32_e32 v7, v19, v0
	v_mul_f32_e32 v8, v20, v0
	v_rndne_f32_e32 v6, v6
	v_rndne_f32_e32 v7, v7
	v_rndne_f32_e32 v8, v8
	v_mul_f32_e32 v9, v21, v0
	v_mul_f32_e32 v17, v25, v0
	v_med3_f32 v6, v6, s3, v183
	v_med3_f32 v7, v7, s3, v183
	v_med3_f32 v8, v8, s3, v183
	v_rndne_f32_e32 v9, v9
	v_mul_f32_e32 v14, v22, v0
	v_rndne_f32_e32 v17, v17
	v_cvt_i32_f32_e32 v6, v6
	v_cvt_i32_f32_e32 v7, v7
	v_cvt_i32_f32_e32 v8, v8
	v_med3_f32 v9, v9, s3, v183
	v_rndne_f32_e32 v14, v14
	v_med3_f32 v17, v17, s3, v183
	v_cvt_i32_f32_e32 v9, v9
	v_med3_f32 v14, v14, s3, v183
	v_cvt_i32_f32_e32 v17, v17
	v_cvt_i32_f32_sdwa v14, v14 dst_sel:WORD_1 dst_unused:UNUSED_PAD src0_sel:DWORD
	v_and_b32_e32 v6, 15, v6
	v_lshlrev_b32_e32 v7, 4, v7
	v_lshlrev_b32_e32 v8, 8, v8
	v_and_b32_e32 v7, 0xf0, v7
	v_and_b32_e32 v8, 0xf00, v8
	v_lshlrev_b32_e32 v9, 12, v9
	v_lshl_or_b32 v6, v17, 28, v6
	v_and_b32_e32 v9, 0xf000, v9
	v_and_b32_e32 v14, 0xf0000, v14
	v_or3_b32 v6, v6, v7, v8
	v_or3_b32 v6, v6, v9, v14
	v_mul_f32_e32 v7, v10, v0
	v_mul_f32_e32 v8, v11, v0
	v_mul_f32_e32 v9, v12, v0
	v_mul_f32_e32 v15, v23, v0
	v_mul_f32_e32 v16, v24, v0
	v_rndne_f32_e32 v7, v7
	v_rndne_f32_e32 v8, v8
	v_rndne_f32_e32 v9, v9
	v_mul_f32_e32 v10, v13, v0
	v_mul_f32_e32 v2, v2, v0
	v_mul_f32_e32 v3, v3, v0
	v_mul_f32_e32 v4, v4, v0
	v_mul_f32_e32 v0, v5, v0
	v_med3_f32 v7, v7, s3, v183
	v_med3_f32 v8, v8, s3, v183
	v_med3_f32 v9, v9, s3, v183
	v_rndne_f32_e32 v10, v10
	v_rndne_f32_e32 v0, v0
	v_rndne_f32_e32 v15, v15
	v_cvt_i32_f32_e32 v7, v7
	v_cvt_i32_f32_e32 v8, v8
	v_cvt_i32_f32_e32 v9, v9
	v_med3_f32 v10, v10, s3, v183
	v_rndne_f32_e32 v2, v2
	v_rndne_f32_e32 v3, v3
	v_med3_f32 v0, v0, s3, v183
	v_med3_f32 v15, v15, s3, v183
	v_rndne_f32_e32 v16, v16
	v_cvt_i32_f32_e32 v10, v10
	v_med3_f32 v2, v2, s3, v183
	v_med3_f32 v3, v3, s3, v183
	v_rndne_f32_e32 v4, v4
	v_cvt_i32_f32_e32 v0, v0
	v_cvt_i32_f32_e32 v15, v15
	v_med3_f32 v16, v16, s3, v183
	v_cvt_i32_f32_sdwa v2, v2 dst_sel:WORD_1 dst_unused:UNUSED_PAD src0_sel:DWORD
	v_cvt_i32_f32_e32 v3, v3
	v_med3_f32 v4, v4, s3, v183
	v_cvt_i32_f32_sdwa v16, v16 dst_sel:BYTE_3 dst_unused:UNUSED_PAD src0_sel:DWORD
	v_cvt_i32_f32_sdwa v4, v4 dst_sel:BYTE_3 dst_unused:UNUSED_PAD src0_sel:DWORD
	v_and_b32_e32 v7, 15, v7
	v_lshlrev_b32_e32 v8, 4, v8
	v_lshlrev_b32_e32 v9, 8, v9
	v_lshlrev_b64 v[36:37], 11, v[34:35]
	v_and_b32_e32 v8, 0xf0, v8
	v_and_b32_e32 v9, 0xf00, v9
	v_lshlrev_b32_e32 v10, 12, v10
	v_lshl_or_b32 v0, v0, 28, v7
	v_lshl_add_u64 v[36:37], s[30:31], 0, v[36:37]
	v_lshlrev_b32_e32 v15, 20, v15
	v_and_b32_e32 v10, 0xf000, v10
	v_and_b32_e32 v2, 0xf0000, v2
	v_lshlrev_b32_e32 v3, 20, v3
	v_or3_b32 v0, v0, v8, v9
	v_lshl_add_u64 v[38:39], v[36:37], 0, v[168:169]
	v_and_b32_e32 v15, 0xf00000, v15
	v_and_b32_e32 v16, 0xf000000, v16
	v_and_b32_e32 v3, 0xf00000, v3
	v_and_b32_e32 v4, 0xf000000, v4
	v_or3_b32 v0, v0, v10, v2
	global_store_dwordx2 v[38:39], v[26:27], off
	v_or3_b32 v6, v6, v15, v16
	v_or3_b32 v7, v0, v3, v4

.LBB0_566:
	s_or_b64 exec, exec, s[10:11]
	v_div_scale_f32 v36, s[10:11], v35, v35, 1.0
	v_rcp_f32_e32 v37, v36
	v_div_scale_f32 v38, vcc, 1.0, v35, 1.0
	s_mov_b64 s[10:11], 0
	v_fma_f32 v39, -v36, v37, 1.0
	v_fmac_f32_e32 v37, v39, v37
	v_mul_f32_e32 v39, v38, v37
	v_fma_f32 v40, -v36, v39, v38
	v_fmac_f32_e32 v39, v40, v37
	v_fma_f32 v36, -v36, v39, v38
	v_div_fmas_f32 v36, v36, v37, v39
	v_div_fixup_f32 v35, v36, v35, 1.0
	v_lshlrev_b64 v[36:37], 11, v[0:1]
	v_mul_f32_e32 v0, v14, v35
	v_mul_f32_e32 v15, v15, v35
	v_mov_b32_e32 v14, v1
	v_cvt_scalef32_pk_fp4_f32 v14, v0, v15, 1.0
	v_mul_f32_e32 v0, v16, v35
	v_mul_f32_e32 v15, v17, v35
	v_cvt_scalef32_pk_fp4_f32 v14, v0, v15, 1.0 op_sel:[0,0,1,0]
	v_mul_f32_e32 v0, v10, v35
	v_mul_f32_e32 v10, v11, v35
	v_cvt_scalef32_pk_fp4_f32 v14, v0, v10, 1.0 op_sel:[0,0,0,1]
	v_mul_f32_e32 v0, v12, v35
	v_mul_f32_e32 v10, v13, v35
	v_cvt_scalef32_pk_fp4_f32 v14, v0, v10, 1.0 op_sel:[0,0,1,1]
	v_mul_f32_e32 v0, v6, v35
	v_mul_f32_e32 v6, v7, v35
	v_mov_b32_e32 v15, v1
	v_cvt_scalef32_pk_fp4_f32 v15, v0, v6, 1.0
	v_mul_f32_e32 v0, v8, v35
	v_mul_f32_e32 v6, v9, v35
	v_cvt_scalef32_pk_fp4_f32 v15, v0, v6, 1.0 op_sel:[0,0,1,0]
	v_mul_f32_e32 v0, v2, v35
	v_mul_f32_e32 v2, v3, v35
	v_cvt_scalef32_pk_fp4_f32 v15, v0, v2, 1.0 op_sel:[0,0,0,1]
	v_mul_f32_e32 v0, v4, v35
	v_mul_f32_e32 v2, v5, v35
	v_cvt_scalef32_pk_fp4_f32 v15, v0, v2, 1.0 op_sel:[0,0,1,1]
	v_mul_f32_e32 v0, v18, v35
	v_mul_f32_e32 v2, v19, v35
	v_mov_b32_e32 v6, v1
	v_cvt_scalef32_pk_fp4_f32 v6, v0, v2, 1.0
	v_mul_f32_e32 v0, v20, v35
	v_mul_f32_e32 v2, v21, v35
	v_cvt_scalef32_pk_fp4_f32 v6, v0, v2, 1.0 op_sel:[0,0,1,0]
	v_mul_f32_e32 v0, v30, v35
	v_mul_f32_e32 v2, v31, v35
	v_cvt_scalef32_pk_fp4_f32 v6, v0, v2, 1.0 op_sel:[0,0,0,1]
	v_mul_f32_e32 v0, v32, v35
	v_mul_f32_e32 v2, v33, v35
	v_cvt_scalef32_pk_fp4_f32 v6, v0, v2, 1.0 op_sel:[0,0,1,1]
	v_mul_f32_e32 v0, v26, v35
	v_mul_f32_e32 v2, v27, v35
	v_mov_b32_e32 v7, v1
	v_cvt_scalef32_pk_fp4_f32 v7, v0, v2, 1.0
	v_mul_f32_e32 v0, v28, v35
	v_mul_f32_e32 v2, v29, v35
	v_lshl_add_u64 v[36:37], s[26:27], 0, v[36:37]
	v_cvt_scalef32_pk_fp4_f32 v7, v0, v2, 1.0 op_sel:[0,0,1,0]
	v_mul_f32_e32 v0, v22, v35
	v_mul_f32_e32 v2, v23, v35
	v_lshl_add_u64 v[38:39], v[36:37], 0, v[168:169]
	v_cvt_scalef32_pk_fp4_f32 v7, v0, v2, 1.0 op_sel:[0,0,0,1]
	v_mul_f32_e32 v0, v24, v35
	v_mul_f32_e32 v2, v25, v35
	global_store_dwordx2 v[38:39], v[14:15], off
	v_cvt_scalef32_pk_fp4_f32 v7, v0, v2, 1.0 op_sel:[0,0,1,1]

.LBB0_926:
	s_waitcnt lgkmcnt(0)
	v_and_b32_e32 v0, 63, v204
	v_lshlrev_b32_e32 v1, 12, v4
	v_lshl_add_u32 v1, v0, 5, v1
	v_add_u32_e32 v1, 0x13288000, v1
	global_load_dwordx4 v[64:67], v1, s[94:95]
	global_load_dwordx4 v[68:71], v1, s[94:95] offset:16
	global_load_dwordx4 v[72:75], v1, s[94:95] offset:2048
	global_load_dwordx4 v[76:79], v1, s[94:95] offset:2064
	ds_read_b32 v80, v170
	ds_read_b32 v81, v170 offset:256
	ds_read_b32 v82, v170 offset:512
	ds_read_b32 v83, v170 offset:768
	v_lshlrev_b32_e32 v28, 3, v0
	v_add_u32_e32 v29, 0x4008000, v28
	v_add_u32_e32 v28, 0x8000, v28
	s_waitcnt lgkmcnt(0)
	v_lshlrev_b32_e32 v2, 2, v80
	v_lshlrev_b32_e32 v3, 2, v81
	global_load_dword v84, v2, s[74:75]
	global_load_dword v85, v3, s[74:75]
	global_load_dword v86, v2, s[76:77]
	global_load_dword v87, v3, s[76:77]
	v_mov_b32_e32 v32, 0
	v_mov_b32_e32 v33, 0
	v_mov_b32_e32 v34, 0
	v_mov_b32_e32 v35, 0
	v_mov_b32_e32 v36, 0
	v_mov_b32_e32 v37, 0
	v_mov_b32_e32 v38, 0
	v_mov_b32_e32 v39, 0
	v_mov_b32_e32 v40, 0
	v_mov_b32_e32 v41, 0
	v_mov_b32_e32 v42, 0
	v_mov_b32_e32 v43, 0
	v_mov_b32_e32 v44, 0
	v_mov_b32_e32 v45, 0
	v_mov_b32_e32 v46, 0
	v_mov_b32_e32 v47, 0
	v_mov_b32_e32 v48, 0
	v_mov_b32_e32 v49, 0
	v_mov_b32_e32 v50, 0
	v_mov_b32_e32 v51, 0
	v_mov_b32_e32 v52, 0
	v_mov_b32_e32 v53, 0
	v_mov_b32_e32 v54, 0
	v_mov_b32_e32 v55, 0
	v_mov_b32_e32 v56, 0
	v_mov_b32_e32 v57, 0
	v_mov_b32_e32 v58, 0
	v_mov_b32_e32 v59, 0
	v_mov_b32_e32 v60, 0
	v_mov_b32_e32 v61, 0
	v_mov_b32_e32 v62, 0
	v_mov_b32_e32 v63, 0
	v_lshlrev_b32_e32 v2, 2, v0
	v_sub_u32_e32 v25, v170, v2
	v_add_u32_e32 v5, 0x1000, v170
	v_lshrrev_b32_e32 v2, 4, v0
	v_lshrrev_b32_e32 v3, 5, v0
	v_and_b32_e32 v2, 1, v2
	v_lshl_or_b32 v2, v2, 1, v3
	v_add_u32_e32 v3, 0x1000, v25
	v_lshl_add_u32 v26, v2, 2, v3
	v_add_u32_e32 v27, 16, v26
	s_waitcnt vmcnt(4)
	v_lshlrev_b32_e32 v128, 16, v64
	v_and_b32_e32 v129, 0xffff0000, v64
	v_lshlrev_b32_e32 v130, 16, v65
	v_and_b32_e32 v131, 0xffff0000, v65
	v_lshlrev_b32_e32 v132, 16, v66
	v_and_b32_e32 v133, 0xffff0000, v66
	v_lshlrev_b32_e32 v134, 16, v67
	v_and_b32_e32 v135, 0xffff0000, v67
	v_lshlrev_b32_e32 v136, 16, v68
	v_and_b32_e32 v137, 0xffff0000, v68
	v_lshlrev_b32_e32 v138, 16, v69
	v_and_b32_e32 v139, 0xffff0000, v69
	v_lshlrev_b32_e32 v140, 16, v70
	v_and_b32_e32 v141, 0xffff0000, v70
	v_lshlrev_b32_e32 v142, 16, v71
	v_and_b32_e32 v143, 0xffff0000, v71
	v_lshlrev_b32_e32 v144, 16, v72
	v_and_b32_e32 v145, 0xffff0000, v72
	v_lshlrev_b32_e32 v146, 16, v73
	v_and_b32_e32 v147, 0xffff0000, v73
	v_lshlrev_b32_e32 v148, 16, v74
	v_and_b32_e32 v149, 0xffff0000, v74
	v_lshlrev_b32_e32 v150, 16, v75
	v_and_b32_e32 v151, 0xffff0000, v75
	v_lshlrev_b32_e32 v152, 16, v76
	v_and_b32_e32 v153, 0xffff0000, v76
	v_lshlrev_b32_e32 v154, 16, v77
	v_and_b32_e32 v155, 0xffff0000, v77
	v_lshlrev_b32_e32 v156, 16, v78
	v_and_b32_e32 v157, 0xffff0000, v78
	v_lshlrev_b32_e32 v158, 16, v79
	v_and_b32_e32 v159, 0xffff0000, v79
	v_max3_f32 v6, |v128|, |v129|, |v130|
	v_max3_f32 v6, v6, |v131|, |v132|
	v_max3_f32 v6, v6, |v133|, |v134|
	v_max3_f32 v6, v6, |v135|, |v136|
	v_max3_f32 v6, v6, |v137|, |v138|
	v_max3_f32 v6, v6, |v139|, |v140|
	v_max3_f32 v6, v6, |v141|, |v142|
	v_max3_f32 v6, v6, |v143|, |v144|
	v_max3_f32 v6, v6, |v145|, |v146|
	v_max3_f32 v6, v6, |v147|, |v148|
	v_max3_f32 v6, v6, |v149|, |v150|
	v_max3_f32 v6, v6, |v151|, |v152|
	v_max3_f32 v6, v6, |v153|, |v154|
	v_max3_f32 v6, v6, |v155|, |v156|
	v_max3_f32 v6, v6, |v157|, |v158|
	v_max_f32_e64 v6, v6, |v159|
	v_mov_b32_e32 v2, v6
	v_mov_b32_e32 v3, v6
	s_nop 1
	v_permlane32_swap_b32_e32 v2, v3
	v_max_f32_e32 v6, v2, v3
	v_mov_b32_e32 v2, v6
	v_mov_b32_e32 v3, v6
	s_nop 1
	v_permlane16_swap_b32_e32 v2, v3
	v_max_f32_e32 v6, v2, v3
	s_nop 1
	v_max_f32_dpp v6, v6, v6 row_ror:8 row_mask:0xf bank_mask:0xf
	s_nop 1
	v_max_f32_dpp v6, v6, v6 row_ror:4 row_mask:0xf bank_mask:0xf
	s_nop 1
	v_max_f32_dpp v6, v6, v6 row_ror:2 row_mask:0xf bank_mask:0xf
	s_nop 1
	v_max_f32_dpp v6, v6, v6 row_ror:1 row_mask:0xf bank_mask:0xf
	v_mul_f32_e32 v7, 0x3e124925, v6
	v_cmp_lt_f32_e32 vcc, 0, v6
	s_nop 1
	v_cndmask_b32_e32 v7, 1.0, v7, vcc
	v_mul_f32_e32 v10, 0x3d924925, v7
	v_rcp_f32_e32 v11, v7
	v_rcp_f32_e32 v12, v10
	s_mov_b32 s33, 0xc0e00000
	v_mov_b32_e32 v13, 0x40e00000
	v_mul_f32_e32 v21, v128, v11
	v_rndne_f32_e32 v21, v21
	v_med3_f32 v21, v21, s33, v13
	v_fma_f32 v22, -v7, v21, v128
	v_mul_f32_e32 v22, v22, v12
	v_rndne_f32_e32 v22, v22
	v_med3_f32 v22, v22, s33, v13
	v_cvt_i32_f32_e32 v21, v21
	v_cvt_i32_f32_e32 v22, v22
	v_and_b32_e32 v208, 15, v21
	v_and_b32_e32 v212, 15, v22
	v_mul_f32_e32 v23, v129, v11
	v_rndne_f32_e32 v23, v23
	v_med3_f32 v23, v23, s33, v13
	v_fma_f32 v30, -v7, v23, v129
	v_mul_f32_e32 v30, v30, v12
	v_rndne_f32_e32 v30, v30
	v_med3_f32 v30, v30, s33, v13
	v_cvt_i32_f32_e32 v23, v23
	v_cvt_i32_f32_e32 v30, v30
	v_and_b32_e32 v23, 15, v23
	v_and_b32_e32 v30, 15, v30
	v_lshl_or_b32 v208, v23, 4, v208
	v_lshl_or_b32 v212, v30, 4, v212
	v_mul_f32_e32 v21, v130, v11
	v_rndne_f32_e32 v21, v21
	v_med3_f32 v21, v21, s33, v13
	v_fma_f32 v22, -v7, v21, v130
	v_mul_f32_e32 v22, v22, v12
	v_rndne_f32_e32 v22, v22
	v_med3_f32 v22, v22, s33, v13
	v_cvt_i32_f32_e32 v21, v21
	v_cvt_i32_f32_e32 v22, v22
	v_and_b32_e32 v21, 15, v21
	v_and_b32_e32 v22, 15, v22
	v_lshl_or_b32 v208, v21, 8, v208
	v_lshl_or_b32 v212, v22, 8, v212
	v_mul_f32_e32 v23, v131, v11
	v_rndne_f32_e32 v23, v23
	v_med3_f32 v23, v23, s33, v13
	v_fma_f32 v30, -v7, v23, v131
	v_mul_f32_e32 v30, v30, v12
	v_rndne_f32_e32 v30, v30
	v_med3_f32 v30, v30, s33, v13
	v_cvt_i32_f32_e32 v23, v23
	v_cvt_i32_f32_e32 v30, v30
	v_and_b32_e32 v23, 15, v23
	v_and_b32_e32 v30, 15, v30
	v_lshl_or_b32 v208, v23, 12, v208
	v_lshl_or_b32 v212, v30, 12, v212
	v_mul_f32_e32 v21, v132, v11
	v_rndne_f32_e32 v21, v21
	v_med3_f32 v21, v21, s33, v13
	v_fma_f32 v22, -v7, v21, v132
	v_mul_f32_e32 v22, v22, v12
	v_rndne_f32_e32 v22, v22
	v_med3_f32 v22, v22, s33, v13
	v_cvt_i32_f32_e32 v21, v21
	v_cvt_i32_f32_e32 v22, v22
	v_and_b32_e32 v21, 15, v21
	v_and_b32_e32 v22, 15, v22
	v_lshl_or_b32 v208, v21, 16, v208
	v_lshl_or_b32 v212, v22, 16, v212
	v_mul_f32_e32 v23, v133, v11
	v_rndne_f32_e32 v23, v23
	v_med3_f32 v23, v23, s33, v13
	v_fma_f32 v30, -v7, v23, v133
	v_mul_f32_e32 v30, v30, v12
	v_rndne_f32_e32 v30, v30
	v_med3_f32 v30, v30, s33, v13
	v_cvt_i32_f32_e32 v23, v23
	v_cvt_i32_f32_e32 v30, v30
	v_and_b32_e32 v23, 15, v23
	v_and_b32_e32 v30, 15, v30
	v_lshl_or_b32 v208, v23, 20, v208
	v_lshl_or_b32 v212, v30, 20, v212
	v_mul_f32_e32 v21, v134, v11
	v_rndne_f32_e32 v21, v21
	v_med3_f32 v21, v21, s33, v13
	v_fma_f32 v22, -v7, v21, v134
	v_mul_f32_e32 v22, v22, v12
	v_rndne_f32_e32 v22, v22
	v_med3_f32 v22, v22, s33, v13
	v_cvt_i32_f32_e32 v21, v21
	v_cvt_i32_f32_e32 v22, v22
	v_and_b32_e32 v21, 15, v21
	v_and_b32_e32 v22, 15, v22
	v_lshl_or_b32 v208, v21, 24, v208
	v_lshl_or_b32 v212, v22, 24, v212
	v_mul_f32_e32 v23, v135, v11
	v_rndne_f32_e32 v23, v23
	v_med3_f32 v23, v23, s33, v13
	v_fma_f32 v30, -v7, v23, v135
	v_mul_f32_e32 v30, v30, v12
	v_rndne_f32_e32 v30, v30
	v_med3_f32 v30, v30, s33, v13
	v_cvt_i32_f32_e32 v23, v23
	v_cvt_i32_f32_e32 v30, v30
	v_lshl_or_b32 v208, v23, 28, v208
	v_lshl_or_b32 v212, v30, 28, v212
	v_mul_f32_e32 v21, v136, v11
	v_rndne_f32_e32 v21, v21
	v_med3_f32 v21, v21, s33, v13
	v_fma_f32 v22, -v7, v21, v136
	v_mul_f32_e32 v22, v22, v12
	v_rndne_f32_e32 v22, v22
	v_med3_f32 v22, v22, s33, v13
	v_cvt_i32_f32_e32 v21, v21
	v_cvt_i32_f32_e32 v22, v22
	v_and_b32_e32 v209, 15, v21
	v_and_b32_e32 v213, 15, v22
	v_mul_f32_e32 v23, v137, v11
	v_rndne_f32_e32 v23, v23
	v_med3_f32 v23, v23, s33, v13
	v_fma_f32 v30, -v7, v23, v137
	v_mul_f32_e32 v30, v30, v12
	v_rndne_f32_e32 v30, v30
	v_med3_f32 v30, v30, s33, v13
	v_cvt_i32_f32_e32 v23, v23
	v_cvt_i32_f32_e32 v30, v30
	v_and_b32_e32 v23, 15, v23
	v_and_b32_e32 v30, 15, v30
	v_lshl_or_b32 v209, v23, 4, v209
	v_lshl_or_b32 v213, v30, 4, v213
	v_mul_f32_e32 v21, v138, v11
	v_rndne_f32_e32 v21, v21
	v_med3_f32 v21, v21, s33, v13
	v_fma_f32 v22, -v7, v21, v138
	v_mul_f32_e32 v22, v22, v12
	v_rndne_f32_e32 v22, v22
	v_med3_f32 v22, v22, s33, v13
	v_cvt_i32_f32_e32 v21, v21
	v_cvt_i32_f32_e32 v22, v22
	v_and_b32_e32 v21, 15, v21
	v_and_b32_e32 v22, 15, v22
	v_lshl_or_b32 v209, v21, 8, v209
	v_lshl_or_b32 v213, v22, 8, v213
	v_mul_f32_e32 v23, v139, v11
	v_rndne_f32_e32 v23, v23
	v_med3_f32 v23, v23, s33, v13
	v_fma_f32 v30, -v7, v23, v139
	v_mul_f32_e32 v30, v30, v12
	v_rndne_f32_e32 v30, v30
	v_med3_f32 v30, v30, s33, v13
	v_cvt_i32_f32_e32 v23, v23
	v_cvt_i32_f32_e32 v30, v30
	v_and_b32_e32 v23, 15, v23
	v_and_b32_e32 v30, 15, v30
	v_lshl_or_b32 v209, v23, 12, v209
	v_lshl_or_b32 v213, v30, 12, v213
	v_mul_f32_e32 v21, v140, v11
	v_rndne_f32_e32 v21, v21
	v_med3_f32 v21, v21, s33, v13
	v_fma_f32 v22, -v7, v21, v140
	v_mul_f32_e32 v22, v22, v12
	v_rndne_f32_e32 v22, v22
	v_med3_f32 v22, v22, s33, v13
	v_cvt_i32_f32_e32 v21, v21
	v_cvt_i32_f32_e32 v22, v22
	v_and_b32_e32 v21, 15, v21
	v_and_b32_e32 v22, 15, v22
	v_lshl_or_b32 v209, v21, 16, v209
	v_lshl_or_b32 v213, v22, 16, v213
	v_mul_f32_e32 v23, v141, v11
	v_rndne_f32_e32 v23, v23
	v_med3_f32 v23, v23, s33, v13
	v_fma_f32 v30, -v7, v23, v141
	v_mul_f32_e32 v30, v30, v12
	v_rndne_f32_e32 v30, v30
	v_med3_f32 v30, v30, s33, v13
	v_cvt_i32_f32_e32 v23, v23
	v_cvt_i32_f32_e32 v30, v30
	v_and_b32_e32 v23, 15, v23
	v_and_b32_e32 v30, 15, v30
	v_lshl_or_b32 v209, v23, 20, v209
	v_lshl_or_b32 v213, v30, 20, v213
	v_mul_f32_e32 v21, v142, v11
	v_rndne_f32_e32 v21, v21
	v_med3_f32 v21, v21, s33, v13
	v_fma_f32 v22, -v7, v21, v142
	v_mul_f32_e32 v22, v22, v12
	v_rndne_f32_e32 v22, v22
	v_med3_f32 v22, v22, s33, v13
	v_cvt_i32_f32_e32 v21, v21
	v_cvt_i32_f32_e32 v22, v22
	v_and_b32_e32 v21, 15, v21
	v_and_b32_e32 v22, 15, v22
	v_lshl_or_b32 v209, v21, 24, v209
	v_lshl_or_b32 v213, v22, 24, v213
	v_mul_f32_e32 v23, v143, v11
	v_rndne_f32_e32 v23, v23
	v_med3_f32 v23, v23, s33, v13
	v_fma_f32 v30, -v7, v23, v143
	v_mul_f32_e32 v30, v30, v12
	v_rndne_f32_e32 v30, v30
	v_med3_f32 v30, v30, s33, v13
	v_cvt_i32_f32_e32 v23, v23
	v_cvt_i32_f32_e32 v30, v30
	v_lshl_or_b32 v209, v23, 28, v209
	v_lshl_or_b32 v213, v30, 28, v213
	v_mul_f32_e32 v21, v144, v11
	v_rndne_f32_e32 v21, v21
	v_med3_f32 v21, v21, s33, v13
	v_fma_f32 v22, -v7, v21, v144
	v_mul_f32_e32 v22, v22, v12
	v_rndne_f32_e32 v22, v22
	v_med3_f32 v22, v22, s33, v13
	v_cvt_i32_f32_e32 v21, v21
	v_cvt_i32_f32_e32 v22, v22
	v_and_b32_e32 v210, 15, v21
	v_and_b32_e32 v214, 15, v22
	v_mul_f32_e32 v23, v145, v11
	v_rndne_f32_e32 v23, v23
	v_med3_f32 v23, v23, s33, v13
	v_fma_f32 v30, -v7, v23, v145
	v_mul_f32_e32 v30, v30, v12
	v_rndne_f32_e32 v30, v30
	v_med3_f32 v30, v30, s33, v13
	v_cvt_i32_f32_e32 v23, v23
	v_cvt_i32_f32_e32 v30, v30
	v_and_b32_e32 v23, 15, v23
	v_and_b32_e32 v30, 15, v30
	v_lshl_or_b32 v210, v23, 4, v210
	v_lshl_or_b32 v214, v30, 4, v214
	v_mul_f32_e32 v21, v146, v11
	v_rndne_f32_e32 v21, v21
	v_med3_f32 v21, v21, s33, v13
	v_fma_f32 v22, -v7, v21, v146
	v_mul_f32_e32 v22, v22, v12
	v_rndne_f32_e32 v22, v22
	v_med3_f32 v22, v22, s33, v13
	v_cvt_i32_f32_e32 v21, v21
	v_cvt_i32_f32_e32 v22, v22
	v_and_b32_e32 v21, 15, v21
	v_and_b32_e32 v22, 15, v22
	v_lshl_or_b32 v210, v21, 8, v210
	v_lshl_or_b32 v214, v22, 8, v214
	v_mul_f32_e32 v23, v147, v11
	v_rndne_f32_e32 v23, v23
	v_med3_f32 v23, v23, s33, v13
	v_fma_f32 v30, -v7, v23, v147
	v_mul_f32_e32 v30, v30, v12
	v_rndne_f32_e32 v30, v30
	v_med3_f32 v30, v30, s33, v13
	v_cvt_i32_f32_e32 v23, v23
	v_cvt_i32_f32_e32 v30, v30
	v_and_b32_e32 v23, 15, v23
	v_and_b32_e32 v30, 15, v30
	v_lshl_or_b32 v210, v23, 12, v210
	v_lshl_or_b32 v214, v30, 12, v214
	v_mul_f32_e32 v21, v148, v11
	v_rndne_f32_e32 v21, v21
	v_med3_f32 v21, v21, s33, v13
	v_fma_f32 v22, -v7, v21, v148
	v_mul_f32_e32 v22, v22, v12
	v_rndne_f32_e32 v22, v22
	v_med3_f32 v22, v22, s33, v13
	v_cvt_i32_f32_e32 v21, v21
	v_cvt_i32_f32_e32 v22, v22
	v_and_b32_e32 v21, 15, v21
	v_and_b32_e32 v22, 15, v22
	v_lshl_or_b32 v210, v21, 16, v210
	v_lshl_or_b32 v214, v22, 16, v214
	v_mul_f32_e32 v23, v149, v11
	v_rndne_f32_e32 v23, v23
	v_med3_f32 v23, v23, s33, v13
	v_fma_f32 v30, -v7, v23, v149
	v_mul_f32_e32 v30, v30, v12
	v_rndne_f32_e32 v30, v30
	v_med3_f32 v30, v30, s33, v13
	v_cvt_i32_f32_e32 v23, v23
	v_cvt_i32_f32_e32 v30, v30
	v_and_b32_e32 v23, 15, v23
	v_and_b32_e32 v30, 15, v30
	v_lshl_or_b32 v210, v23, 20, v210
	v_lshl_or_b32 v214, v30, 20, v214
	v_mul_f32_e32 v21, v150, v11
	v_rndne_f32_e32 v21, v21
	v_med3_f32 v21, v21, s33, v13
	v_fma_f32 v22, -v7, v21, v150
	v_mul_f32_e32 v22, v22, v12
	v_rndne_f32_e32 v22, v22
	v_med3_f32 v22, v22, s33, v13
	v_cvt_i32_f32_e32 v21, v21
	v_cvt_i32_f32_e32 v22, v22
	v_and_b32_e32 v21, 15, v21
	v_and_b32_e32 v22, 15, v22
	v_lshl_or_b32 v210, v21, 24, v210
	v_lshl_or_b32 v214, v22, 24, v214
	v_mul_f32_e32 v23, v151, v11
	v_rndne_f32_e32 v23, v23
	v_med3_f32 v23, v23, s33, v13
	v_fma_f32 v30, -v7, v23, v151
	v_mul_f32_e32 v30, v30, v12
	v_rndne_f32_e32 v30, v30
	v_med3_f32 v30, v30, s33, v13
	v_cvt_i32_f32_e32 v23, v23
	v_cvt_i32_f32_e32 v30, v30
	v_lshl_or_b32 v210, v23, 28, v210
	v_lshl_or_b32 v214, v30, 28, v214
	v_mul_f32_e32 v21, v152, v11
	v_rndne_f32_e32 v21, v21
	v_med3_f32 v21, v21, s33, v13
	v_fma_f32 v22, -v7, v21, v152
	v_mul_f32_e32 v22, v22, v12
	v_rndne_f32_e32 v22, v22
	v_med3_f32 v22, v22, s33, v13
	v_cvt_i32_f32_e32 v21, v21
	v_cvt_i32_f32_e32 v22, v22
	v_and_b32_e32 v211, 15, v21
	v_and_b32_e32 v215, 15, v22
	v_mul_f32_e32 v23, v153, v11
	v_rndne_f32_e32 v23, v23
	v_med3_f32 v23, v23, s33, v13
	v_fma_f32 v30, -v7, v23, v153
	v_mul_f32_e32 v30, v30, v12
	v_rndne_f32_e32 v30, v30
	v_med3_f32 v30, v30, s33, v13
	v_cvt_i32_f32_e32 v23, v23
	v_cvt_i32_f32_e32 v30, v30
	v_and_b32_e32 v23, 15, v23
	v_and_b32_e32 v30, 15, v30
	v_lshl_or_b32 v211, v23, 4, v211
	v_lshl_or_b32 v215, v30, 4, v215
	v_mul_f32_e32 v21, v154, v11
	v_rndne_f32_e32 v21, v21
	v_med3_f32 v21, v21, s33, v13
	v_fma_f32 v22, -v7, v21, v154
	v_mul_f32_e32 v22, v22, v12
	v_rndne_f32_e32 v22, v22
	v_med3_f32 v22, v22, s33, v13
	v_cvt_i32_f32_e32 v21, v21
	v_cvt_i32_f32_e32 v22, v22
	v_and_b32_e32 v21, 15, v21
	v_and_b32_e32 v22, 15, v22
	v_lshl_or_b32 v211, v21, 8, v211
	v_lshl_or_b32 v215, v22, 8, v215
	v_mul_f32_e32 v23, v155, v11
	v_rndne_f32_e32 v23, v23
	v_med3_f32 v23, v23, s33, v13
	v_fma_f32 v30, -v7, v23, v155
	v_mul_f32_e32 v30, v30, v12
	v_rndne_f32_e32 v30, v30
	v_med3_f32 v30, v30, s33, v13
	v_cvt_i32_f32_e32 v23, v23
	v_cvt_i32_f32_e32 v30, v30
	v_and_b32_e32 v23, 15, v23
	v_and_b32_e32 v30, 15, v30
	v_lshl_or_b32 v211, v23, 12, v211
	v_lshl_or_b32 v215, v30, 12, v215
	v_mul_f32_e32 v21, v156, v11
	v_rndne_f32_e32 v21, v21
	v_med3_f32 v21, v21, s33, v13
	v_fma_f32 v22, -v7, v21, v156
	v_mul_f32_e32 v22, v22, v12
	v_rndne_f32_e32 v22, v22
	v_med3_f32 v22, v22, s33, v13
	v_cvt_i32_f32_e32 v21, v21
	v_cvt_i32_f32_e32 v22, v22
	v_and_b32_e32 v21, 15, v21
	v_and_b32_e32 v22, 15, v22
	v_lshl_or_b32 v211, v21, 16, v211
	v_lshl_or_b32 v215, v22, 16, v215
	v_mul_f32_e32 v23, v157, v11
	v_rndne_f32_e32 v23, v23
	v_med3_f32 v23, v23, s33, v13
	v_fma_f32 v30, -v7, v23, v157
	v_mul_f32_e32 v30, v30, v12
	v_rndne_f32_e32 v30, v30
	v_med3_f32 v30, v30, s33, v13
	v_cvt_i32_f32_e32 v23, v23
	v_cvt_i32_f32_e32 v30, v30
	v_and_b32_e32 v23, 15, v23
	v_and_b32_e32 v30, 15, v30
	v_lshl_or_b32 v211, v23, 20, v211
	v_lshl_or_b32 v215, v30, 20, v215
	v_mul_f32_e32 v21, v158, v11
	v_rndne_f32_e32 v21, v21
	v_med3_f32 v21, v21, s33, v13
	v_fma_f32 v22, -v7, v21, v158
	v_mul_f32_e32 v22, v22, v12
	v_rndne_f32_e32 v22, v22
	v_med3_f32 v22, v22, s33, v13
	v_cvt_i32_f32_e32 v21, v21
	v_cvt_i32_f32_e32 v22, v22
	v_and_b32_e32 v21, 15, v21
	v_and_b32_e32 v22, 15, v22
	v_lshl_or_b32 v211, v21, 24, v211
	v_lshl_or_b32 v215, v22, 24, v215
	v_mul_f32_e32 v23, v159, v11
	v_rndne_f32_e32 v23, v23
	v_med3_f32 v23, v23, s33, v13
	v_fma_f32 v30, -v7, v23, v159
	v_mul_f32_e32 v30, v30, v12
	v_rndne_f32_e32 v30, v30
	v_med3_f32 v30, v30, s33, v13
	v_cvt_i32_f32_e32 v23, v23
	v_cvt_i32_f32_e32 v30, v30
	v_lshl_or_b32 v211, v23, 28, v211
	v_lshl_or_b32 v215, v30, 28, v215
	s_waitcnt vmcnt(0)
	v_mul_f32_e32 v2, v24, v10
	v_mul_f32_e32 v84, v84, v2
	v_mul_f32_e32 v85, v85, v2
	v_mul_f32_e32 v86, v86, v82
	v_mul_f32_e32 v87, v87, v83
	ds_write_b32 v5, v84
	ds_write_b32 v5, v85 offset:256
	ds_write_b32 v5, v86 offset:512
	ds_write_b32 v5, v87 offset:768
	ds_read_b128 v[10:13], v25
	ds_read_b128 v[18:21], v25 offset:16
	v_add_u32_e32 v25, 32, v25
	s_waitcnt lgkmcnt(0)
	v_readfirstlane_b32 s33, v10
	s_lshl_b32 s33, s33, 11
	s_add_u32 s72, s94, s33
	s_addc_u32 s73, s95, 0
	global_load_dwordx2 v[64:65], v28, s[72:73]
	global_load_dwordx2 v[66:67], v28, s[72:73] offset:512
	global_load_dwordx2 v[96:97], v28, s[72:73] offset:1024
	global_load_dwordx2 v[98:99], v28, s[72:73] offset:1536
	v_readfirstlane_b32 s33, v11
	s_lshl_b32 s33, s33, 11
	s_add_u32 s72, s94, s33
	s_addc_u32 s73, s95, 0
	global_load_dwordx2 v[68:69], v28, s[72:73]
	global_load_dwordx2 v[70:71], v28, s[72:73] offset:512
	global_load_dwordx2 v[100:101], v28, s[72:73] offset:1024
	global_load_dwordx2 v[102:103], v28, s[72:73] offset:1536
	v_readfirstlane_b32 s33, v12
	s_lshl_b32 s33, s33, 11
	s_add_u32 s72, s94, s33
	s_addc_u32 s73, s95, 0
	global_load_dwordx2 v[72:73], v28, s[72:73]
	global_load_dwordx2 v[74:75], v28, s[72:73] offset:512
	global_load_dwordx2 v[104:105], v28, s[72:73] offset:1024
	global_load_dwordx2 v[106:107], v28, s[72:73] offset:1536
	v_readfirstlane_b32 s33, v13
	s_lshl_b32 s33, s33, 11
	s_add_u32 s72, s94, s33
	s_addc_u32 s73, s95, 0
	global_load_dwordx2 v[76:77], v28, s[72:73]
	global_load_dwordx2 v[78:79], v28, s[72:73] offset:512
	global_load_dwordx2 v[108:109], v28, s[72:73] offset:1024
	global_load_dwordx2 v[110:111], v28, s[72:73] offset:1536
	v_readfirstlane_b32 s33, v18
	s_lshl_b32 s33, s33, 11
	s_add_u32 s72, s94, s33
	s_addc_u32 s73, s95, 0
	global_load_dwordx2 v[80:81], v28, s[72:73]
	global_load_dwordx2 v[82:83], v28, s[72:73] offset:512
	global_load_dwordx2 v[112:113], v28, s[72:73] offset:1024
	global_load_dwordx2 v[114:115], v28, s[72:73] offset:1536
	v_readfirstlane_b32 s33, v19
	s_lshl_b32 s33, s33, 11
	s_add_u32 s72, s94, s33
	s_addc_u32 s73, s95, 0
	global_load_dwordx2 v[84:85], v28, s[72:73]
	global_load_dwordx2 v[86:87], v28, s[72:73] offset:512
	global_load_dwordx2 v[116:117], v28, s[72:73] offset:1024
	global_load_dwordx2 v[118:119], v28, s[72:73] offset:1536
	v_readfirstlane_b32 s33, v20
	s_lshl_b32 s33, s33, 11
	s_add_u32 s72, s94, s33
	s_addc_u32 s73, s95, 0
	global_load_dwordx2 v[88:89], v28, s[72:73]
	global_load_dwordx2 v[90:91], v28, s[72:73] offset:512
	global_load_dwordx2 v[120:121], v28, s[72:73] offset:1024
	global_load_dwordx2 v[122:123], v28, s[72:73] offset:1536
	v_readfirstlane_b32 s33, v21
	s_lshl_b32 s33, s33, 11
	s_add_u32 s72, s94, s33
	s_addc_u32 s73, s95, 0
	global_load_dwordx2 v[92:93], v28, s[72:73]
	global_load_dwordx2 v[94:95], v28, s[72:73] offset:512
	global_load_dwordx2 v[124:125], v28, s[72:73] offset:1024
	global_load_dwordx2 v[126:127], v28, s[72:73] offset:1536
	s_mov_b32 s86, 7
.Lp8_eloop:
	ds_read_b128 v[10:13], v25
	ds_read_b128 v[18:21], v25 offset:16
	v_add_u32_e32 v25, 32, v25
	ds_read_b32 v232, v26
	ds_read_b32 v233, v27
	ds_read_b32 v234, v26 offset:512
	ds_read_b32 v235, v27 offset:512
	v_add_u32_e32 v26, 32, v26
	v_add_u32_e32 v27, 32, v27
	s_waitcnt vmcnt(30)
	v_mov_b32_e32 v216, 0
	v_mov_b32_e32 v224, 0
	v_dot8c_i32_i4_e32 v216, v64, v208
	v_dot8c_i32_i4_e32 v224, v64, v212
	v_dot8c_i32_i4_e32 v216, v65, v209
	v_dot8c_i32_i4_e32 v224, v65, v213
	v_dot8c_i32_i4_e32 v216, v66, v210
	v_dot8c_i32_i4_e32 v224, v66, v214
	v_dot8c_i32_i4_e32 v216, v67, v211
	v_dot8c_i32_i4_e32 v224, v67, v215
	s_waitcnt vmcnt(26)
	v_mov_b32_e32 v217, 0
	v_mov_b32_e32 v225, 0
	v_dot8c_i32_i4_e32 v217, v68, v208
	v_dot8c_i32_i4_e32 v225, v68, v212
	v_dot8c_i32_i4_e32 v217, v69, v209
	v_dot8c_i32_i4_e32 v225, v69, v213
	v_dot8c_i32_i4_e32 v217, v70, v210
	v_dot8c_i32_i4_e32 v225, v70, v214
	v_dot8c_i32_i4_e32 v217, v71, v211
	v_dot8c_i32_i4_e32 v225, v71, v215
	s_waitcnt vmcnt(22)
	v_mov_b32_e32 v218, 0
	v_mov_b32_e32 v226, 0
	v_dot8c_i32_i4_e32 v218, v72, v208
	v_dot8c_i32_i4_e32 v226, v72, v212
	v_dot8c_i32_i4_e32 v218, v73, v209
	v_dot8c_i32_i4_e32 v226, v73, v213
	v_dot8c_i32_i4_e32 v218, v74, v210
	v_dot8c_i32_i4_e32 v226, v74, v214
	v_dot8c_i32_i4_e32 v218, v75, v211
	v_dot8c_i32_i4_e32 v226, v75, v215
	s_waitcnt vmcnt(18)
	v_mov_b32_e32 v219, 0
	v_mov_b32_e32 v227, 0
	v_dot8c_i32_i4_e32 v219, v76, v208
	v_dot8c_i32_i4_e32 v227, v76, v212
	v_dot8c_i32_i4_e32 v219, v77, v209
	v_dot8c_i32_i4_e32 v227, v77, v213
	v_dot8c_i32_i4_e32 v219, v78, v210
	v_dot8c_i32_i4_e32 v227, v78, v214
	v_dot8c_i32_i4_e32 v219, v79, v211
	v_dot8c_i32_i4_e32 v227, v79, v215
	s_waitcnt vmcnt(14)
	v_mov_b32_e32 v220, 0
	v_mov_b32_e32 v228, 0
	v_dot8c_i32_i4_e32 v220, v80, v208
	v_dot8c_i32_i4_e32 v228, v80, v212
	v_dot8c_i32_i4_e32 v220, v81, v209
	v_dot8c_i32_i4_e32 v228, v81, v213
	v_dot8c_i32_i4_e32 v220, v82, v210
	v_dot8c_i32_i4_e32 v228, v82, v214
	v_dot8c_i32_i4_e32 v220, v83, v211
	v_dot8c_i32_i4_e32 v228, v83, v215
	s_waitcnt vmcnt(10)
	v_mov_b32_e32 v221, 0
	v_mov_b32_e32 v229, 0
	v_dot8c_i32_i4_e32 v221, v84, v208
	v_dot8c_i32_i4_e32 v229, v84, v212
	v_dot8c_i32_i4_e32 v221, v85, v209
	v_dot8c_i32_i4_e32 v229, v85, v213
	v_dot8c_i32_i4_e32 v221, v86, v210
	v_dot8c_i32_i4_e32 v229, v86, v214
	v_dot8c_i32_i4_e32 v221, v87, v211
	v_dot8c_i32_i4_e32 v229, v87, v215
	s_waitcnt vmcnt(6)
	v_mov_b32_e32 v222, 0
	v_mov_b32_e32 v230, 0
	v_dot8c_i32_i4_e32 v222, v88, v208
	v_dot8c_i32_i4_e32 v230, v88, v212
	v_dot8c_i32_i4_e32 v222, v89, v209
	v_dot8c_i32_i4_e32 v230, v89, v213
	v_dot8c_i32_i4_e32 v222, v90, v210
	v_dot8c_i32_i4_e32 v230, v90, v214
	v_dot8c_i32_i4_e32 v222, v91, v211
	v_dot8c_i32_i4_e32 v230, v91, v215
	s_waitcnt vmcnt(2)
	v_mov_b32_e32 v223, 0
	v_mov_b32_e32 v231, 0
	v_dot8c_i32_i4_e32 v223, v92, v208
	v_dot8c_i32_i4_e32 v231, v92, v212
	v_dot8c_i32_i4_e32 v223, v93, v209
	v_dot8c_i32_i4_e32 v231, v93, v213
	v_dot8c_i32_i4_e32 v223, v94, v210
	v_dot8c_i32_i4_e32 v231, v94, v214
	v_dot8c_i32_i4_e32 v223, v95, v211
	v_dot8c_i32_i4_e32 v231, v95, v215
	s_nop 2
	v_mad_i32_i24 v216, v216, 14, v224
	v_mad_i32_i24 v217, v217, 14, v225
	v_mad_i32_i24 v218, v218, 14, v226
	v_mad_i32_i24 v219, v219, 14, v227
	v_mad_i32_i24 v220, v220, 14, v228
	v_mad_i32_i24 v221, v221, 14, v229
	v_mad_i32_i24 v222, v222, 14, v230
	v_mad_i32_i24 v223, v223, 14, v231
	s_waitcnt lgkmcnt(4)
	v_readfirstlane_b32 s33, v10
	s_lshl_b32 s33, s33, 11
	s_add_u32 s72, s94, s33
	s_addc_u32 s73, s95, 0
	global_load_dwordx2 v[128:129], v28, s[72:73]
	global_load_dwordx2 v[130:131], v28, s[72:73] offset:512
	global_load_dwordx2 v[176:177], v28, s[72:73] offset:1024
	global_load_dwordx2 v[178:179], v28, s[72:73] offset:1536
	v_readfirstlane_b32 s33, v11
	s_lshl_b32 s33, s33, 11
	s_add_u32 s72, s94, s33
	s_addc_u32 s73, s95, 0
	global_load_dwordx2 v[132:133], v28, s[72:73]
	global_load_dwordx2 v[134:135], v28, s[72:73] offset:512
	global_load_dwordx2 v[180:181], v28, s[72:73] offset:1024
	global_load_dwordx2 v[182:183], v28, s[72:73] offset:1536
	v_readfirstlane_b32 s33, v12
	s_lshl_b32 s33, s33, 11
	s_add_u32 s72, s94, s33
	s_addc_u32 s73, s95, 0
	global_load_dwordx2 v[136:137], v28, s[72:73]
	global_load_dwordx2 v[138:139], v28, s[72:73] offset:512
	global_load_dwordx2 v[184:185], v28, s[72:73] offset:1024
	global_load_dwordx2 v[186:187], v28, s[72:73] offset:1536
	v_readfirstlane_b32 s33, v13
	s_lshl_b32 s33, s33, 11
	s_add_u32 s72, s94, s33
	s_addc_u32 s73, s95, 0
	global_load_dwordx2 v[140:141], v28, s[72:73]
	global_load_dwordx2 v[142:143], v28, s[72:73] offset:512
	global_load_dwordx2 v[188:189], v28, s[72:73] offset:1024
	global_load_dwordx2 v[190:191], v28, s[72:73] offset:1536
	v_readfirstlane_b32 s33, v18
	s_lshl_b32 s33, s33, 11
	s_add_u32 s72, s94, s33
	s_addc_u32 s73, s95, 0
	global_load_dwordx2 v[144:145], v28, s[72:73]
	global_load_dwordx2 v[146:147], v28, s[72:73] offset:512
	global_load_dwordx2 v[192:193], v28, s[72:73] offset:1024
	global_load_dwordx2 v[194:195], v28, s[72:73] offset:1536
	v_readfirstlane_b32 s33, v19
	s_lshl_b32 s33, s33, 11
	s_add_u32 s72, s94, s33
	s_addc_u32 s73, s95, 0
	global_load_dwordx2 v[148:149], v28, s[72:73]
	global_load_dwordx2 v[150:151], v28, s[72:73] offset:512
	global_load_dwordx2 v[196:197], v28, s[72:73] offset:1024
	global_load_dwordx2 v[198:199], v28, s[72:73] offset:1536
	v_readfirstlane_b32 s33, v20
	s_lshl_b32 s33, s33, 11
	s_add_u32 s72, s94, s33
	s_addc_u32 s73, s95, 0
	global_load_dwordx2 v[152:153], v28, s[72:73]
	global_load_dwordx2 v[154:155], v28, s[72:73] offset:512
	global_load_dwordx2 v[200:201], v28, s[72:73] offset:1024
	global_load_dwordx2 v[202:203], v28, s[72:73] offset:1536
	v_readfirstlane_b32 s33, v21
	s_lshl_b32 s33, s33, 11
	s_add_u32 s72, s94, s33
	s_addc_u32 s73, s95, 0
	global_load_dwordx2 v[156:157], v28, s[72:73]
	global_load_dwordx2 v[158:159], v28, s[72:73] offset:512
	global_load_dwordx2 v[240:241], v28, s[72:73] offset:1024
	global_load_dwordx2 v[242:243], v28, s[72:73] offset:1536
	s_nop 1
	v_permlane32_swap_b32_e32 v216, v217
	v_permlane32_swap_b32_e32 v218, v219
	v_permlane32_swap_b32_e32 v220, v221
	v_permlane32_swap_b32_e32 v222, v223
	v_add_u32_e32 v216, v216, v217
	v_add_u32_e32 v218, v218, v219
	v_add_u32_e32 v220, v220, v221
	v_add_u32_e32 v222, v222, v223
	s_nop 1
	v_permlane16_swap_b32_e32 v216, v218
	v_permlane16_swap_b32_e32 v220, v222
	v_add_u32_e32 v216, v216, v218
	v_add_u32_e32 v220, v220, v222
	s_nop 1
	v_add_u32_dpp v216, v216, v216 row_ror:8 row_mask:0xf bank_mask:0xf
	v_add_u32_dpp v220, v220, v220 row_ror:8 row_mask:0xf bank_mask:0xf
	s_nop 1
	v_add_u32_dpp v216, v216, v216 row_ror:4 row_mask:0xf bank_mask:0xf
	v_add_u32_dpp v220, v220, v220 row_ror:4 row_mask:0xf bank_mask:0xf
	s_nop 1
	v_add_u32_dpp v216, v216, v216 row_ror:2 row_mask:0xf bank_mask:0xf
	v_add_u32_dpp v220, v220, v220 row_ror:2 row_mask:0xf bank_mask:0xf
	s_nop 1
	v_add_u32_dpp v216, v216, v216 row_ror:1 row_mask:0xf bank_mask:0xf
	v_add_u32_dpp v220, v220, v220 row_ror:1 row_mask:0xf bank_mask:0xf
	s_waitcnt lgkmcnt(0)
	v_cvt_f32_i32_e32 v216, v216
	v_cvt_f32_i32_e32 v220, v220
	v_mul_f32_e32 v216, v216, v232
	v_mul_f32_e32 v220, v220, v233
	v_fma_f32 v2, |v216|, s83, 1.0
	v_fma_f32 v7, |v220|, s83, 1.0
	v_rcp_f32_e32 v2, v2
	v_rcp_f32_e32 v7, v7
	v_mul_f32_e32 v5, v216, v216
	v_mul_f32_e32 v11, v220, v220
	v_mul_f32_e32 v5, 0xbf38aa3b, v5
	v_mul_f32_e32 v11, 0xbf38aa3b, v11
	v_exp_f32_e32 v5, v5
	v_exp_f32_e32 v11, v11
	v_fmamk_f32 v3, v2, 0x3f07dc22, v172
	v_fmamk_f32 v10, v7, 0x3f07dc22, v172
	v_fmaak_f32 v3, v2, v3, 0x3f35f0e3
	v_fmaak_f32 v10, v7, v10, 0x3f35f0e3
	v_fmaak_f32 v3, v2, v3, 0xbe11a98e
	v_fmaak_f32 v10, v7, v10, 0xbe11a98e
	v_fmaak_f32 v3, v2, v3, 0x3e027906
	v_fmaak_f32 v10, v7, v10, 0x3e027906
	v_mul_f32_e32 v3, v2, v3
	v_mul_f32_e32 v10, v7, v10
	v_mul_f32_e32 v3, v5, v3
	v_mul_f32_e32 v10, v11, v10
	v_mul_f32_e32 v6, v216, v3
	v_mul_f32_e32 v12, v220, v10
	v_fma_f32 v3, -v216, v3, v216
	v_fma_f32 v10, -v220, v10, v220
	v_cmp_gt_f32_e32 vcc, 0, v216
	v_cmp_gt_f32_e64 s[96:97], 0, v220
	s_nop 1
	v_cndmask_b32_e32 v216, v3, v6, vcc
	v_cndmask_b32_e64 v220, v10, v12, s[96:97]
	v_mul_f32_e32 v216, v216, v234
	v_mul_f32_e32 v220, v220, v235
	s_nop 0
	v_readlane_b32 s64, v216, 0
	v_readlane_b32 s65, v216, 32
	v_readlane_b32 s66, v216, 16
	v_readlane_b32 s67, v216, 48
	v_readlane_b32 s68, v220, 0
	v_readlane_b32 s69, v220, 32
	v_readlane_b32 s70, v220, 16
	v_readlane_b32 s71, v220, 48
	s_waitcnt vmcnt(60)
	v_cvt_scalef32_pk_f32_fp4 v[160:161], v96, 1.0
	v_cvt_scalef32_pk_f32_fp4 v[162:163], v96, 1.0 op_sel:[1,0,0]
	v_cvt_scalef32_pk_f32_fp4 v[18:19], v96, 1.0 op_sel:[0,1,0]
	v_pk_fma_f32 v[32:33], v[160:161], s[64:65], v[32:33] op_sel_hi:[1,0,1]
	v_cvt_scalef32_pk_f32_fp4 v[20:21], v96, 1.0 op_sel:[1,1,0]
	v_pk_fma_f32 v[34:35], v[162:163], s[64:65], v[34:35] op_sel_hi:[1,0,1]
	v_cvt_scalef32_pk_f32_fp4 v[22:23], v97, 1.0
	v_pk_fma_f32 v[36:37], v[18:19], s[64:65], v[36:37] op_sel_hi:[1,0,1]
	v_cvt_scalef32_pk_f32_fp4 v[30:31], v97, 1.0 op_sel:[1,0,0]
	v_pk_fma_f32 v[38:39], v[20:21], s[64:65], v[38:39] op_sel_hi:[1,0,1]
	v_cvt_scalef32_pk_f32_fp4 v[2:3], v97, 1.0 op_sel:[0,1,0]
	v_pk_fma_f32 v[40:41], v[22:23], s[64:65], v[40:41] op_sel_hi:[1,0,1]
	v_cvt_scalef32_pk_f32_fp4 v[6:7], v97, 1.0 op_sel:[1,1,0]
	v_pk_fma_f32 v[42:43], v[30:31], s[64:65], v[42:43] op_sel_hi:[1,0,1]
	v_cvt_scalef32_pk_f32_fp4 v[160:161], v98, 1.0
	v_pk_fma_f32 v[44:45], v[2:3], s[64:65], v[44:45] op_sel_hi:[1,0,1]
	v_cvt_scalef32_pk_f32_fp4 v[162:163], v98, 1.0 op_sel:[1,0,0]
	v_pk_fma_f32 v[46:47], v[6:7], s[64:65], v[46:47] op_sel_hi:[1,0,1]
	v_cvt_scalef32_pk_f32_fp4 v[18:19], v98, 1.0 op_sel:[0,1,0]
	v_pk_fma_f32 v[48:49], v[160:161], s[64:65], v[48:49] op_sel_hi:[1,0,1]
	v_cvt_scalef32_pk_f32_fp4 v[20:21], v98, 1.0 op_sel:[1,1,0]
	v_pk_fma_f32 v[50:51], v[162:163], s[64:65], v[50:51] op_sel_hi:[1,0,1]
	v_cvt_scalef32_pk_f32_fp4 v[22:23], v99, 1.0
	v_pk_fma_f32 v[52:53], v[18:19], s[64:65], v[52:53] op_sel_hi:[1,0,1]
	v_cvt_scalef32_pk_f32_fp4 v[30:31], v99, 1.0 op_sel:[1,0,0]
	v_pk_fma_f32 v[54:55], v[20:21], s[64:65], v[54:55] op_sel_hi:[1,0,1]
	v_cvt_scalef32_pk_f32_fp4 v[2:3], v99, 1.0 op_sel:[0,1,0]
	v_pk_fma_f32 v[56:57], v[22:23], s[64:65], v[56:57] op_sel_hi:[1,0,1]
	v_cvt_scalef32_pk_f32_fp4 v[6:7], v99, 1.0 op_sel:[1,1,0]
	v_pk_fma_f32 v[58:59], v[30:31], s[64:65], v[58:59] op_sel_hi:[1,0,1]
	v_pk_fma_f32 v[60:61], v[2:3], s[64:65], v[60:61] op_sel_hi:[1,0,1]
	v_pk_fma_f32 v[62:63], v[6:7], s[64:65], v[62:63] op_sel_hi:[1,0,1]
	s_waitcnt vmcnt(56)
	v_cvt_scalef32_pk_f32_fp4 v[160:161], v100, 1.0
	v_cvt_scalef32_pk_f32_fp4 v[162:163], v100, 1.0 op_sel:[1,0,0]
	v_cvt_scalef32_pk_f32_fp4 v[18:19], v100, 1.0 op_sel:[0,1,0]
	v_pk_fma_f32 v[32:33], v[160:161], s[64:65], v[32:33] op_sel:[0,1,0] op_sel_hi:[1,1,1]
	v_cvt_scalef32_pk_f32_fp4 v[20:21], v100, 1.0 op_sel:[1,1,0]
	v_pk_fma_f32 v[34:35], v[162:163], s[64:65], v[34:35] op_sel:[0,1,0] op_sel_hi:[1,1,1]
	v_cvt_scalef32_pk_f32_fp4 v[22:23], v101, 1.0
	v_pk_fma_f32 v[36:37], v[18:19], s[64:65], v[36:37] op_sel:[0,1,0] op_sel_hi:[1,1,1]
	v_cvt_scalef32_pk_f32_fp4 v[30:31], v101, 1.0 op_sel:[1,0,0]
	v_pk_fma_f32 v[38:39], v[20:21], s[64:65], v[38:39] op_sel:[0,1,0] op_sel_hi:[1,1,1]
	v_cvt_scalef32_pk_f32_fp4 v[2:3], v101, 1.0 op_sel:[0,1,0]
	v_pk_fma_f32 v[40:41], v[22:23], s[64:65], v[40:41] op_sel:[0,1,0] op_sel_hi:[1,1,1]
	v_cvt_scalef32_pk_f32_fp4 v[6:7], v101, 1.0 op_sel:[1,1,0]
	v_pk_fma_f32 v[42:43], v[30:31], s[64:65], v[42:43] op_sel:[0,1,0] op_sel_hi:[1,1,1]
	v_cvt_scalef32_pk_f32_fp4 v[160:161], v102, 1.0
	v_pk_fma_f32 v[44:45], v[2:3], s[64:65], v[44:45] op_sel:[0,1,0] op_sel_hi:[1,1,1]
	v_cvt_scalef32_pk_f32_fp4 v[162:163], v102, 1.0 op_sel:[1,0,0]
	v_pk_fma_f32 v[46:47], v[6:7], s[64:65], v[46:47] op_sel:[0,1,0] op_sel_hi:[1,1,1]
	v_cvt_scalef32_pk_f32_fp4 v[18:19], v102, 1.0 op_sel:[0,1,0]
	v_pk_fma_f32 v[48:49], v[160:161], s[64:65], v[48:49] op_sel:[0,1,0] op_sel_hi:[1,1,1]
	v_cvt_scalef32_pk_f32_fp4 v[20:21], v102, 1.0 op_sel:[1,1,0]
	v_pk_fma_f32 v[50:51], v[162:163], s[64:65], v[50:51] op_sel:[0,1,0] op_sel_hi:[1,1,1]
	v_cvt_scalef32_pk_f32_fp4 v[22:23], v103, 1.0
	v_pk_fma_f32 v[52:53], v[18:19], s[64:65], v[52:53] op_sel:[0,1,0] op_sel_hi:[1,1,1]
	v_cvt_scalef32_pk_f32_fp4 v[30:31], v103, 1.0 op_sel:[1,0,0]
	v_pk_fma_f32 v[54:55], v[20:21], s[64:65], v[54:55] op_sel:[0,1,0] op_sel_hi:[1,1,1]
	v_cvt_scalef32_pk_f32_fp4 v[2:3], v103, 1.0 op_sel:[0,1,0]
	v_pk_fma_f32 v[56:57], v[22:23], s[64:65], v[56:57] op_sel:[0,1,0] op_sel_hi:[1,1,1]
	v_cvt_scalef32_pk_f32_fp4 v[6:7], v103, 1.0 op_sel:[1,1,0]
	v_pk_fma_f32 v[58:59], v[30:31], s[64:65], v[58:59] op_sel:[0,1,0] op_sel_hi:[1,1,1]
	v_pk_fma_f32 v[60:61], v[2:3], s[64:65], v[60:61] op_sel:[0,1,0] op_sel_hi:[1,1,1]
	v_pk_fma_f32 v[62:63], v[6:7], s[64:65], v[62:63] op_sel:[0,1,0] op_sel_hi:[1,1,1]
	s_waitcnt vmcnt(52)
	v_cvt_scalef32_pk_f32_fp4 v[160:161], v104, 1.0
	v_cvt_scalef32_pk_f32_fp4 v[162:163], v104, 1.0 op_sel:[1,0,0]
	v_cvt_scalef32_pk_f32_fp4 v[18:19], v104, 1.0 op_sel:[0,1,0]
	v_pk_fma_f32 v[32:33], v[160:161], s[66:67], v[32:33] op_sel_hi:[1,0,1]
	v_cvt_scalef32_pk_f32_fp4 v[20:21], v104, 1.0 op_sel:[1,1,0]
	v_pk_fma_f32 v[34:35], v[162:163], s[66:67], v[34:35] op_sel_hi:[1,0,1]
	v_cvt_scalef32_pk_f32_fp4 v[22:23], v105, 1.0
	v_pk_fma_f32 v[36:37], v[18:19], s[66:67], v[36:37] op_sel_hi:[1,0,1]
	v_cvt_scalef32_pk_f32_fp4 v[30:31], v105, 1.0 op_sel:[1,0,0]
	v_pk_fma_f32 v[38:39], v[20:21], s[66:67], v[38:39] op_sel_hi:[1,0,1]
	v_cvt_scalef32_pk_f32_fp4 v[2:3], v105, 1.0 op_sel:[0,1,0]
	v_pk_fma_f32 v[40:41], v[22:23], s[66:67], v[40:41] op_sel_hi:[1,0,1]
	v_cvt_scalef32_pk_f32_fp4 v[6:7], v105, 1.0 op_sel:[1,1,0]
	v_pk_fma_f32 v[42:43], v[30:31], s[66:67], v[42:43] op_sel_hi:[1,0,1]
	v_cvt_scalef32_pk_f32_fp4 v[160:161], v106, 1.0
	v_pk_fma_f32 v[44:45], v[2:3], s[66:67], v[44:45] op_sel_hi:[1,0,1]
	v_cvt_scalef32_pk_f32_fp4 v[162:163], v106, 1.0 op_sel:[1,0,0]
	v_pk_fma_f32 v[46:47], v[6:7], s[66:67], v[46:47] op_sel_hi:[1,0,1]
	v_cvt_scalef32_pk_f32_fp4 v[18:19], v106, 1.0 op_sel:[0,1,0]
	v_pk_fma_f32 v[48:49], v[160:161], s[66:67], v[48:49] op_sel_hi:[1,0,1]
	v_cvt_scalef32_pk_f32_fp4 v[20:21], v106, 1.0 op_sel:[1,1,0]
	v_pk_fma_f32 v[50:51], v[162:163], s[66:67], v[50:51] op_sel_hi:[1,0,1]
	v_cvt_scalef32_pk_f32_fp4 v[22:23], v107, 1.0
	v_pk_fma_f32 v[52:53], v[18:19], s[66:67], v[52:53] op_sel_hi:[1,0,1]
	v_cvt_scalef32_pk_f32_fp4 v[30:31], v107, 1.0 op_sel:[1,0,0]
	v_pk_fma_f32 v[54:55], v[20:21], s[66:67], v[54:55] op_sel_hi:[1,0,1]
	v_cvt_scalef32_pk_f32_fp4 v[2:3], v107, 1.0 op_sel:[0,1,0]
	v_pk_fma_f32 v[56:57], v[22:23], s[66:67], v[56:57] op_sel_hi:[1,0,1]
	v_cvt_scalef32_pk_f32_fp4 v[6:7], v107, 1.0 op_sel:[1,1,0]
	v_pk_fma_f32 v[58:59], v[30:31], s[66:67], v[58:59] op_sel_hi:[1,0,1]
	v_pk_fma_f32 v[60:61], v[2:3], s[66:67], v[60:61] op_sel_hi:[1,0,1]
	v_pk_fma_f32 v[62:63], v[6:7], s[66:67], v[62:63] op_sel_hi:[1,0,1]
	s_waitcnt vmcnt(48)
	v_cvt_scalef32_pk_f32_fp4 v[160:161], v108, 1.0
	v_cvt_scalef32_pk_f32_fp4 v[162:163], v108, 1.0 op_sel:[1,0,0]
	v_cvt_scalef32_pk_f32_fp4 v[18:19], v108, 1.0 op_sel:[0,1,0]
	v_pk_fma_f32 v[32:33], v[160:161], s[66:67], v[32:33] op_sel:[0,1,0] op_sel_hi:[1,1,1]
	v_cvt_scalef32_pk_f32_fp4 v[20:21], v108, 1.0 op_sel:[1,1,0]
	v_pk_fma_f32 v[34:35], v[162:163], s[66:67], v[34:35] op_sel:[0,1,0] op_sel_hi:[1,1,1]
	v_cvt_scalef32_pk_f32_fp4 v[22:23], v109, 1.0
	v_pk_fma_f32 v[36:37], v[18:19], s[66:67], v[36:37] op_sel:[0,1,0] op_sel_hi:[1,1,1]
	v_cvt_scalef32_pk_f32_fp4 v[30:31], v109, 1.0 op_sel:[1,0,0]
	v_pk_fma_f32 v[38:39], v[20:21], s[66:67], v[38:39] op_sel:[0,1,0] op_sel_hi:[1,1,1]
	v_cvt_scalef32_pk_f32_fp4 v[2:3], v109, 1.0 op_sel:[0,1,0]
	v_pk_fma_f32 v[40:41], v[22:23], s[66:67], v[40:41] op_sel:[0,1,0] op_sel_hi:[1,1,1]
	v_cvt_scalef32_pk_f32_fp4 v[6:7], v109, 1.0 op_sel:[1,1,0]
	v_pk_fma_f32 v[42:43], v[30:31], s[66:67], v[42:43] op_sel:[0,1,0] op_sel_hi:[1,1,1]
	v_cvt_scalef32_pk_f32_fp4 v[160:161], v110, 1.0
	v_pk_fma_f32 v[44:45], v[2:3], s[66:67], v[44:45] op_sel:[0,1,0] op_sel_hi:[1,1,1]
	v_cvt_scalef32_pk_f32_fp4 v[162:163], v110, 1.0 op_sel:[1,0,0]
	v_pk_fma_f32 v[46:47], v[6:7], s[66:67], v[46:47] op_sel:[0,1,0] op_sel_hi:[1,1,1]
	v_cvt_scalef32_pk_f32_fp4 v[18:19], v110, 1.0 op_sel:[0,1,0]
	v_pk_fma_f32 v[48:49], v[160:161], s[66:67], v[48:49] op_sel:[0,1,0] op_sel_hi:[1,1,1]
	v_cvt_scalef32_pk_f32_fp4 v[20:21], v110, 1.0 op_sel:[1,1,0]
	v_pk_fma_f32 v[50:51], v[162:163], s[66:67], v[50:51] op_sel:[0,1,0] op_sel_hi:[1,1,1]
	v_cvt_scalef32_pk_f32_fp4 v[22:23], v111, 1.0
	v_pk_fma_f32 v[52:53], v[18:19], s[66:67], v[52:53] op_sel:[0,1,0] op_sel_hi:[1,1,1]
	v_cvt_scalef32_pk_f32_fp4 v[30:31], v111, 1.0 op_sel:[1,0,0]
	v_pk_fma_f32 v[54:55], v[20:21], s[66:67], v[54:55] op_sel:[0,1,0] op_sel_hi:[1,1,1]
	v_cvt_scalef32_pk_f32_fp4 v[2:3], v111, 1.0 op_sel:[0,1,0]
	v_pk_fma_f32 v[56:57], v[22:23], s[66:67], v[56:57] op_sel:[0,1,0] op_sel_hi:[1,1,1]
	v_cvt_scalef32_pk_f32_fp4 v[6:7], v111, 1.0 op_sel:[1,1,0]
	v_pk_fma_f32 v[58:59], v[30:31], s[66:67], v[58:59] op_sel:[0,1,0] op_sel_hi:[1,1,1]
	v_pk_fma_f32 v[60:61], v[2:3], s[66:67], v[60:61] op_sel:[0,1,0] op_sel_hi:[1,1,1]
	v_pk_fma_f32 v[62:63], v[6:7], s[66:67], v[62:63] op_sel:[0,1,0] op_sel_hi:[1,1,1]
	s_waitcnt vmcnt(44)
	v_cvt_scalef32_pk_f32_fp4 v[160:161], v112, 1.0
	v_cvt_scalef32_pk_f32_fp4 v[162:163], v112, 1.0 op_sel:[1,0,0]
	v_cvt_scalef32_pk_f32_fp4 v[18:19], v112, 1.0 op_sel:[0,1,0]
	v_pk_fma_f32 v[32:33], v[160:161], s[68:69], v[32:33] op_sel_hi:[1,0,1]
	v_cvt_scalef32_pk_f32_fp4 v[20:21], v112, 1.0 op_sel:[1,1,0]
	v_pk_fma_f32 v[34:35], v[162:163], s[68:69], v[34:35] op_sel_hi:[1,0,1]
	v_cvt_scalef32_pk_f32_fp4 v[22:23], v113, 1.0
	v_pk_fma_f32 v[36:37], v[18:19], s[68:69], v[36:37] op_sel_hi:[1,0,1]
	v_cvt_scalef32_pk_f32_fp4 v[30:31], v113, 1.0 op_sel:[1,0,0]
	v_pk_fma_f32 v[38:39], v[20:21], s[68:69], v[38:39] op_sel_hi:[1,0,1]
	v_cvt_scalef32_pk_f32_fp4 v[2:3], v113, 1.0 op_sel:[0,1,0]
	v_pk_fma_f32 v[40:41], v[22:23], s[68:69], v[40:41] op_sel_hi:[1,0,1]
	v_cvt_scalef32_pk_f32_fp4 v[6:7], v113, 1.0 op_sel:[1,1,0]
	v_pk_fma_f32 v[42:43], v[30:31], s[68:69], v[42:43] op_sel_hi:[1,0,1]
	v_cvt_scalef32_pk_f32_fp4 v[160:161], v114, 1.0
	v_pk_fma_f32 v[44:45], v[2:3], s[68:69], v[44:45] op_sel_hi:[1,0,1]
	v_cvt_scalef32_pk_f32_fp4 v[162:163], v114, 1.0 op_sel:[1,0,0]
	v_pk_fma_f32 v[46:47], v[6:7], s[68:69], v[46:47] op_sel_hi:[1,0,1]
	v_cvt_scalef32_pk_f32_fp4 v[18:19], v114, 1.0 op_sel:[0,1,0]
	v_pk_fma_f32 v[48:49], v[160:161], s[68:69], v[48:49] op_sel_hi:[1,0,1]
	v_cvt_scalef32_pk_f32_fp4 v[20:21], v114, 1.0 op_sel:[1,1,0]
	v_pk_fma_f32 v[50:51], v[162:163], s[68:69], v[50:51] op_sel_hi:[1,0,1]
	v_cvt_scalef32_pk_f32_fp4 v[22:23], v115, 1.0
	v_pk_fma_f32 v[52:53], v[18:19], s[68:69], v[52:53] op_sel_hi:[1,0,1]
	v_cvt_scalef32_pk_f32_fp4 v[30:31], v115, 1.0 op_sel:[1,0,0]
	v_pk_fma_f32 v[54:55], v[20:21], s[68:69], v[54:55] op_sel_hi:[1,0,1]
	v_cvt_scalef32_pk_f32_fp4 v[2:3], v115, 1.0 op_sel:[0,1,0]
	v_pk_fma_f32 v[56:57], v[22:23], s[68:69], v[56:57] op_sel_hi:[1,0,1]
	v_cvt_scalef32_pk_f32_fp4 v[6:7], v115, 1.0 op_sel:[1,1,0]
	v_pk_fma_f32 v[58:59], v[30:31], s[68:69], v[58:59] op_sel_hi:[1,0,1]
	v_pk_fma_f32 v[60:61], v[2:3], s[68:69], v[60:61] op_sel_hi:[1,0,1]
	v_pk_fma_f32 v[62:63], v[6:7], s[68:69], v[62:63] op_sel_hi:[1,0,1]
	s_waitcnt vmcnt(40)
	v_cvt_scalef32_pk_f32_fp4 v[160:161], v116, 1.0
	v_cvt_scalef32_pk_f32_fp4 v[162:163], v116, 1.0 op_sel:[1,0,0]
	v_cvt_scalef32_pk_f32_fp4 v[18:19], v116, 1.0 op_sel:[0,1,0]
	v_pk_fma_f32 v[32:33], v[160:161], s[68:69], v[32:33] op_sel:[0,1,0] op_sel_hi:[1,1,1]
	v_cvt_scalef32_pk_f32_fp4 v[20:21], v116, 1.0 op_sel:[1,1,0]
	v_pk_fma_f32 v[34:35], v[162:163], s[68:69], v[34:35] op_sel:[0,1,0] op_sel_hi:[1,1,1]
	v_cvt_scalef32_pk_f32_fp4 v[22:23], v117, 1.0
	v_pk_fma_f32 v[36:37], v[18:19], s[68:69], v[36:37] op_sel:[0,1,0] op_sel_hi:[1,1,1]
	v_cvt_scalef32_pk_f32_fp4 v[30:31], v117, 1.0 op_sel:[1,0,0]
	v_pk_fma_f32 v[38:39], v[20:21], s[68:69], v[38:39] op_sel:[0,1,0] op_sel_hi:[1,1,1]
	v_cvt_scalef32_pk_f32_fp4 v[2:3], v117, 1.0 op_sel:[0,1,0]
	v_pk_fma_f32 v[40:41], v[22:23], s[68:69], v[40:41] op_sel:[0,1,0] op_sel_hi:[1,1,1]
	v_cvt_scalef32_pk_f32_fp4 v[6:7], v117, 1.0 op_sel:[1,1,0]
	v_pk_fma_f32 v[42:43], v[30:31], s[68:69], v[42:43] op_sel:[0,1,0] op_sel_hi:[1,1,1]
	v_cvt_scalef32_pk_f32_fp4 v[160:161], v118, 1.0
	v_pk_fma_f32 v[44:45], v[2:3], s[68:69], v[44:45] op_sel:[0,1,0] op_sel_hi:[1,1,1]
	v_cvt_scalef32_pk_f32_fp4 v[162:163], v118, 1.0 op_sel:[1,0,0]
	v_pk_fma_f32 v[46:47], v[6:7], s[68:69], v[46:47] op_sel:[0,1,0] op_sel_hi:[1,1,1]
	v_cvt_scalef32_pk_f32_fp4 v[18:19], v118, 1.0 op_sel:[0,1,0]
	v_pk_fma_f32 v[48:49], v[160:161], s[68:69], v[48:49] op_sel:[0,1,0] op_sel_hi:[1,1,1]
	v_cvt_scalef32_pk_f32_fp4 v[20:21], v118, 1.0 op_sel:[1,1,0]
	v_pk_fma_f32 v[50:51], v[162:163], s[68:69], v[50:51] op_sel:[0,1,0] op_sel_hi:[1,1,1]
	v_cvt_scalef32_pk_f32_fp4 v[22:23], v119, 1.0
	v_pk_fma_f32 v[52:53], v[18:19], s[68:69], v[52:53] op_sel:[0,1,0] op_sel_hi:[1,1,1]
	v_cvt_scalef32_pk_f32_fp4 v[30:31], v119, 1.0 op_sel:[1,0,0]
	v_pk_fma_f32 v[54:55], v[20:21], s[68:69], v[54:55] op_sel:[0,1,0] op_sel_hi:[1,1,1]
	v_cvt_scalef32_pk_f32_fp4 v[2:3], v119, 1.0 op_sel:[0,1,0]
	v_pk_fma_f32 v[56:57], v[22:23], s[68:69], v[56:57] op_sel:[0,1,0] op_sel_hi:[1,1,1]
	v_cvt_scalef32_pk_f32_fp4 v[6:7], v119, 1.0 op_sel:[1,1,0]
	v_pk_fma_f32 v[58:59], v[30:31], s[68:69], v[58:59] op_sel:[0,1,0] op_sel_hi:[1,1,1]
	v_pk_fma_f32 v[60:61], v[2:3], s[68:69], v[60:61] op_sel:[0,1,0] op_sel_hi:[1,1,1]
	v_pk_fma_f32 v[62:63], v[6:7], s[68:69], v[62:63] op_sel:[0,1,0] op_sel_hi:[1,1,1]
	s_waitcnt vmcnt(36)
	v_cvt_scalef32_pk_f32_fp4 v[160:161], v120, 1.0
	v_cvt_scalef32_pk_f32_fp4 v[162:163], v120, 1.0 op_sel:[1,0,0]
	v_cvt_scalef32_pk_f32_fp4 v[18:19], v120, 1.0 op_sel:[0,1,0]
	v_pk_fma_f32 v[32:33], v[160:161], s[70:71], v[32:33] op_sel_hi:[1,0,1]
	v_cvt_scalef32_pk_f32_fp4 v[20:21], v120, 1.0 op_sel:[1,1,0]
	v_pk_fma_f32 v[34:35], v[162:163], s[70:71], v[34:35] op_sel_hi:[1,0,1]
	v_cvt_scalef32_pk_f32_fp4 v[22:23], v121, 1.0
	v_pk_fma_f32 v[36:37], v[18:19], s[70:71], v[36:37] op_sel_hi:[1,0,1]
	v_cvt_scalef32_pk_f32_fp4 v[30:31], v121, 1.0 op_sel:[1,0,0]
	v_pk_fma_f32 v[38:39], v[20:21], s[70:71], v[38:39] op_sel_hi:[1,0,1]
	v_cvt_scalef32_pk_f32_fp4 v[2:3], v121, 1.0 op_sel:[0,1,0]
	v_pk_fma_f32 v[40:41], v[22:23], s[70:71], v[40:41] op_sel_hi:[1,0,1]
	v_cvt_scalef32_pk_f32_fp4 v[6:7], v121, 1.0 op_sel:[1,1,0]
	v_pk_fma_f32 v[42:43], v[30:31], s[70:71], v[42:43] op_sel_hi:[1,0,1]
	v_cvt_scalef32_pk_f32_fp4 v[160:161], v122, 1.0
	v_pk_fma_f32 v[44:45], v[2:3], s[70:71], v[44:45] op_sel_hi:[1,0,1]
	v_cvt_scalef32_pk_f32_fp4 v[162:163], v122, 1.0 op_sel:[1,0,0]
	v_pk_fma_f32 v[46:47], v[6:7], s[70:71], v[46:47] op_sel_hi:[1,0,1]
	v_cvt_scalef32_pk_f32_fp4 v[18:19], v122, 1.0 op_sel:[0,1,0]
	v_pk_fma_f32 v[48:49], v[160:161], s[70:71], v[48:49] op_sel_hi:[1,0,1]
	v_cvt_scalef32_pk_f32_fp4 v[20:21], v122, 1.0 op_sel:[1,1,0]
	v_pk_fma_f32 v[50:51], v[162:163], s[70:71], v[50:51] op_sel_hi:[1,0,1]
	v_cvt_scalef32_pk_f32_fp4 v[22:23], v123, 1.0
	v_pk_fma_f32 v[52:53], v[18:19], s[70:71], v[52:53] op_sel_hi:[1,0,1]
	v_cvt_scalef32_pk_f32_fp4 v[30:31], v123, 1.0 op_sel:[1,0,0]
	v_pk_fma_f32 v[54:55], v[20:21], s[70:71], v[54:55] op_sel_hi:[1,0,1]
	v_cvt_scalef32_pk_f32_fp4 v[2:3], v123, 1.0 op_sel:[0,1,0]
	v_pk_fma_f32 v[56:57], v[22:23], s[70:71], v[56:57] op_sel_hi:[1,0,1]
	v_cvt_scalef32_pk_f32_fp4 v[6:7], v123, 1.0 op_sel:[1,1,0]
	v_pk_fma_f32 v[58:59], v[30:31], s[70:71], v[58:59] op_sel_hi:[1,0,1]
	v_pk_fma_f32 v[60:61], v[2:3], s[70:71], v[60:61] op_sel_hi:[1,0,1]
	v_pk_fma_f32 v[62:63], v[6:7], s[70:71], v[62:63] op_sel_hi:[1,0,1]
	s_waitcnt vmcnt(32)
	v_cvt_scalef32_pk_f32_fp4 v[160:161], v124, 1.0
	v_cvt_scalef32_pk_f32_fp4 v[162:163], v124, 1.0 op_sel:[1,0,0]
	v_cvt_scalef32_pk_f32_fp4 v[18:19], v124, 1.0 op_sel:[0,1,0]
	v_pk_fma_f32 v[32:33], v[160:161], s[70:71], v[32:33] op_sel:[0,1,0] op_sel_hi:[1,1,1]
	v_cvt_scalef32_pk_f32_fp4 v[20:21], v124, 1.0 op_sel:[1,1,0]
	v_pk_fma_f32 v[34:35], v[162:163], s[70:71], v[34:35] op_sel:[0,1,0] op_sel_hi:[1,1,1]
	v_cvt_scalef32_pk_f32_fp4 v[22:23], v125, 1.0
	v_pk_fma_f32 v[36:37], v[18:19], s[70:71], v[36:37] op_sel:[0,1,0] op_sel_hi:[1,1,1]
	v_cvt_scalef32_pk_f32_fp4 v[30:31], v125, 1.0 op_sel:[1,0,0]
	v_pk_fma_f32 v[38:39], v[20:21], s[70:71], v[38:39] op_sel:[0,1,0] op_sel_hi:[1,1,1]
	v_cvt_scalef32_pk_f32_fp4 v[2:3], v125, 1.0 op_sel:[0,1,0]
	v_pk_fma_f32 v[40:41], v[22:23], s[70:71], v[40:41] op_sel:[0,1,0] op_sel_hi:[1,1,1]
	v_cvt_scalef32_pk_f32_fp4 v[6:7], v125, 1.0 op_sel:[1,1,0]
	v_pk_fma_f32 v[42:43], v[30:31], s[70:71], v[42:43] op_sel:[0,1,0] op_sel_hi:[1,1,1]
	v_cvt_scalef32_pk_f32_fp4 v[160:161], v126, 1.0
	v_pk_fma_f32 v[44:45], v[2:3], s[70:71], v[44:45] op_sel:[0,1,0] op_sel_hi:[1,1,1]
	v_cvt_scalef32_pk_f32_fp4 v[162:163], v126, 1.0 op_sel:[1,0,0]
	v_pk_fma_f32 v[46:47], v[6:7], s[70:71], v[46:47] op_sel:[0,1,0] op_sel_hi:[1,1,1]
	v_cvt_scalef32_pk_f32_fp4 v[18:19], v126, 1.0 op_sel:[0,1,0]
	v_pk_fma_f32 v[48:49], v[160:161], s[70:71], v[48:49] op_sel:[0,1,0] op_sel_hi:[1,1,1]
	v_cvt_scalef32_pk_f32_fp4 v[20:21], v126, 1.0 op_sel:[1,1,0]
	v_pk_fma_f32 v[50:51], v[162:163], s[70:71], v[50:51] op_sel:[0,1,0] op_sel_hi:[1,1,1]
	v_cvt_scalef32_pk_f32_fp4 v[22:23], v127, 1.0
	v_pk_fma_f32 v[52:53], v[18:19], s[70:71], v[52:53] op_sel:[0,1,0] op_sel_hi:[1,1,1]
	v_cvt_scalef32_pk_f32_fp4 v[30:31], v127, 1.0 op_sel:[1,0,0]
	v_pk_fma_f32 v[54:55], v[20:21], s[70:71], v[54:55] op_sel:[0,1,0] op_sel_hi:[1,1,1]
	v_cvt_scalef32_pk_f32_fp4 v[2:3], v127, 1.0 op_sel:[0,1,0]
	v_pk_fma_f32 v[56:57], v[22:23], s[70:71], v[56:57] op_sel:[0,1,0] op_sel_hi:[1,1,1]
	v_cvt_scalef32_pk_f32_fp4 v[6:7], v127, 1.0 op_sel:[1,1,0]
	v_pk_fma_f32 v[58:59], v[30:31], s[70:71], v[58:59] op_sel:[0,1,0] op_sel_hi:[1,1,1]
	v_pk_fma_f32 v[60:61], v[2:3], s[70:71], v[60:61] op_sel:[0,1,0] op_sel_hi:[1,1,1]
	v_pk_fma_f32 v[62:63], v[6:7], s[70:71], v[62:63] op_sel:[0,1,0] op_sel_hi:[1,1,1]
	ds_read_b128 v[10:13], v25
	ds_read_b128 v[18:21], v25 offset:16
	v_add_u32_e32 v25, 32, v25
	ds_read_b32 v232, v26
	ds_read_b32 v233, v27
	ds_read_b32 v234, v26 offset:512
	ds_read_b32 v235, v27 offset:512
	v_add_u32_e32 v26, 32, v26
	v_add_u32_e32 v27, 32, v27
	s_waitcnt vmcnt(30)
	v_mov_b32_e32 v216, 0
	v_mov_b32_e32 v224, 0
	v_dot8c_i32_i4_e32 v216, v128, v208
	v_dot8c_i32_i4_e32 v224, v128, v212
	v_dot8c_i32_i4_e32 v216, v129, v209
	v_dot8c_i32_i4_e32 v224, v129, v213
	v_dot8c_i32_i4_e32 v216, v130, v210
	v_dot8c_i32_i4_e32 v224, v130, v214
	v_dot8c_i32_i4_e32 v216, v131, v211
	v_dot8c_i32_i4_e32 v224, v131, v215
	s_waitcnt vmcnt(26)
	v_mov_b32_e32 v217, 0
	v_mov_b32_e32 v225, 0
	v_dot8c_i32_i4_e32 v217, v132, v208
	v_dot8c_i32_i4_e32 v225, v132, v212
	v_dot8c_i32_i4_e32 v217, v133, v209
	v_dot8c_i32_i4_e32 v225, v133, v213
	v_dot8c_i32_i4_e32 v217, v134, v210
	v_dot8c_i32_i4_e32 v225, v134, v214
	v_dot8c_i32_i4_e32 v217, v135, v211
	v_dot8c_i32_i4_e32 v225, v135, v215
	s_waitcnt vmcnt(22)
	v_mov_b32_e32 v218, 0
	v_mov_b32_e32 v226, 0
	v_dot8c_i32_i4_e32 v218, v136, v208
	v_dot8c_i32_i4_e32 v226, v136, v212
	v_dot8c_i32_i4_e32 v218, v137, v209
	v_dot8c_i32_i4_e32 v226, v137, v213
	v_dot8c_i32_i4_e32 v218, v138, v210
	v_dot8c_i32_i4_e32 v226, v138, v214
	v_dot8c_i32_i4_e32 v218, v139, v211
	v_dot8c_i32_i4_e32 v226, v139, v215
	s_waitcnt vmcnt(18)
	v_mov_b32_e32 v219, 0
	v_mov_b32_e32 v227, 0
	v_dot8c_i32_i4_e32 v219, v140, v208
	v_dot8c_i32_i4_e32 v227, v140, v212
	v_dot8c_i32_i4_e32 v219, v141, v209
	v_dot8c_i32_i4_e32 v227, v141, v213
	v_dot8c_i32_i4_e32 v219, v142, v210
	v_dot8c_i32_i4_e32 v227, v142, v214
	v_dot8c_i32_i4_e32 v219, v143, v211
	v_dot8c_i32_i4_e32 v227, v143, v215
	s_waitcnt vmcnt(14)
	v_mov_b32_e32 v220, 0
	v_mov_b32_e32 v228, 0
	v_dot8c_i32_i4_e32 v220, v144, v208
	v_dot8c_i32_i4_e32 v228, v144, v212
	v_dot8c_i32_i4_e32 v220, v145, v209
	v_dot8c_i32_i4_e32 v228, v145, v213
	v_dot8c_i32_i4_e32 v220, v146, v210
	v_dot8c_i32_i4_e32 v228, v146, v214
	v_dot8c_i32_i4_e32 v220, v147, v211
	v_dot8c_i32_i4_e32 v228, v147, v215
	s_waitcnt vmcnt(10)
	v_mov_b32_e32 v221, 0
	v_mov_b32_e32 v229, 0
	v_dot8c_i32_i4_e32 v221, v148, v208
	v_dot8c_i32_i4_e32 v229, v148, v212
	v_dot8c_i32_i4_e32 v221, v149, v209
	v_dot8c_i32_i4_e32 v229, v149, v213
	v_dot8c_i32_i4_e32 v221, v150, v210
	v_dot8c_i32_i4_e32 v229, v150, v214
	v_dot8c_i32_i4_e32 v221, v151, v211
	v_dot8c_i32_i4_e32 v229, v151, v215
	s_waitcnt vmcnt(6)
	v_mov_b32_e32 v222, 0
	v_mov_b32_e32 v230, 0
	v_dot8c_i32_i4_e32 v222, v152, v208
	v_dot8c_i32_i4_e32 v230, v152, v212
	v_dot8c_i32_i4_e32 v222, v153, v209
	v_dot8c_i32_i4_e32 v230, v153, v213
	v_dot8c_i32_i4_e32 v222, v154, v210
	v_dot8c_i32_i4_e32 v230, v154, v214
	v_dot8c_i32_i4_e32 v222, v155, v211
	v_dot8c_i32_i4_e32 v230, v155, v215
	s_waitcnt vmcnt(2)
	v_mov_b32_e32 v223, 0
	v_mov_b32_e32 v231, 0
	v_dot8c_i32_i4_e32 v223, v156, v208
	v_dot8c_i32_i4_e32 v231, v156, v212
	v_dot8c_i32_i4_e32 v223, v157, v209
	v_dot8c_i32_i4_e32 v231, v157, v213
	v_dot8c_i32_i4_e32 v223, v158, v210
	v_dot8c_i32_i4_e32 v231, v158, v214
	v_dot8c_i32_i4_e32 v223, v159, v211
	v_dot8c_i32_i4_e32 v231, v159, v215
	s_nop 2
	v_mad_i32_i24 v216, v216, 14, v224
	v_mad_i32_i24 v217, v217, 14, v225
	v_mad_i32_i24 v218, v218, 14, v226
	v_mad_i32_i24 v219, v219, 14, v227
	v_mad_i32_i24 v220, v220, 14, v228
	v_mad_i32_i24 v221, v221, 14, v229
	v_mad_i32_i24 v222, v222, 14, v230
	v_mad_i32_i24 v223, v223, 14, v231
	s_waitcnt lgkmcnt(4)
	v_readfirstlane_b32 s33, v10
	s_lshl_b32 s33, s33, 11
	s_add_u32 s72, s94, s33
	s_addc_u32 s73, s95, 0
	global_load_dwordx2 v[64:65], v28, s[72:73]
	global_load_dwordx2 v[66:67], v28, s[72:73] offset:512
	global_load_dwordx2 v[96:97], v28, s[72:73] offset:1024
	global_load_dwordx2 v[98:99], v28, s[72:73] offset:1536
	v_readfirstlane_b32 s33, v11
	s_lshl_b32 s33, s33, 11
	s_add_u32 s72, s94, s33
	s_addc_u32 s73, s95, 0
	global_load_dwordx2 v[68:69], v28, s[72:73]
	global_load_dwordx2 v[70:71], v28, s[72:73] offset:512
	global_load_dwordx2 v[100:101], v28, s[72:73] offset:1024
	global_load_dwordx2 v[102:103], v28, s[72:73] offset:1536
	v_readfirstlane_b32 s33, v12
	s_lshl_b32 s33, s33, 11
	s_add_u32 s72, s94, s33
	s_addc_u32 s73, s95, 0
	global_load_dwordx2 v[72:73], v28, s[72:73]
	global_load_dwordx2 v[74:75], v28, s[72:73] offset:512
	global_load_dwordx2 v[104:105], v28, s[72:73] offset:1024
	global_load_dwordx2 v[106:107], v28, s[72:73] offset:1536
	v_readfirstlane_b32 s33, v13
	s_lshl_b32 s33, s33, 11
	s_add_u32 s72, s94, s33
	s_addc_u32 s73, s95, 0
	global_load_dwordx2 v[76:77], v28, s[72:73]
	global_load_dwordx2 v[78:79], v28, s[72:73] offset:512
	global_load_dwordx2 v[108:109], v28, s[72:73] offset:1024
	global_load_dwordx2 v[110:111], v28, s[72:73] offset:1536
	v_readfirstlane_b32 s33, v18
	s_lshl_b32 s33, s33, 11
	s_add_u32 s72, s94, s33
	s_addc_u32 s73, s95, 0
	global_load_dwordx2 v[80:81], v28, s[72:73]
	global_load_dwordx2 v[82:83], v28, s[72:73] offset:512
	global_load_dwordx2 v[112:113], v28, s[72:73] offset:1024
	global_load_dwordx2 v[114:115], v28, s[72:73] offset:1536
	v_readfirstlane_b32 s33, v19
	s_lshl_b32 s33, s33, 11
	s_add_u32 s72, s94, s33
	s_addc_u32 s73, s95, 0
	global_load_dwordx2 v[84:85], v28, s[72:73]
	global_load_dwordx2 v[86:87], v28, s[72:73] offset:512
	global_load_dwordx2 v[116:117], v28, s[72:73] offset:1024
	global_load_dwordx2 v[118:119], v28, s[72:73] offset:1536
	v_readfirstlane_b32 s33, v20
	s_lshl_b32 s33, s33, 11
	s_add_u32 s72, s94, s33
	s_addc_u32 s73, s95, 0
	global_load_dwordx2 v[88:89], v28, s[72:73]
	global_load_dwordx2 v[90:91], v28, s[72:73] offset:512
	global_load_dwordx2 v[120:121], v28, s[72:73] offset:1024
	global_load_dwordx2 v[122:123], v28, s[72:73] offset:1536
	v_readfirstlane_b32 s33, v21
	s_lshl_b32 s33, s33, 11
	s_add_u32 s72, s94, s33
	s_addc_u32 s73, s95, 0
	global_load_dwordx2 v[92:93], v28, s[72:73]
	global_load_dwordx2 v[94:95], v28, s[72:73] offset:512
	global_load_dwordx2 v[124:125], v28, s[72:73] offset:1024
	global_load_dwordx2 v[126:127], v28, s[72:73] offset:1536
	s_nop 1
	v_permlane32_swap_b32_e32 v216, v217
	v_permlane32_swap_b32_e32 v218, v219
	v_permlane32_swap_b32_e32 v220, v221
	v_permlane32_swap_b32_e32 v222, v223
	v_add_u32_e32 v216, v216, v217
	v_add_u32_e32 v218, v218, v219
	v_add_u32_e32 v220, v220, v221
	v_add_u32_e32 v222, v222, v223
	s_nop 1
	v_permlane16_swap_b32_e32 v216, v218
	v_permlane16_swap_b32_e32 v220, v222
	v_add_u32_e32 v216, v216, v218
	v_add_u32_e32 v220, v220, v222
	s_nop 1
	v_add_u32_dpp v216, v216, v216 row_ror:8 row_mask:0xf bank_mask:0xf
	v_add_u32_dpp v220, v220, v220 row_ror:8 row_mask:0xf bank_mask:0xf
	s_nop 1
	v_add_u32_dpp v216, v216, v216 row_ror:4 row_mask:0xf bank_mask:0xf
	v_add_u32_dpp v220, v220, v220 row_ror:4 row_mask:0xf bank_mask:0xf
	s_nop 1
	v_add_u32_dpp v216, v216, v216 row_ror:2 row_mask:0xf bank_mask:0xf
	v_add_u32_dpp v220, v220, v220 row_ror:2 row_mask:0xf bank_mask:0xf
	s_nop 1
	v_add_u32_dpp v216, v216, v216 row_ror:1 row_mask:0xf bank_mask:0xf
	v_add_u32_dpp v220, v220, v220 row_ror:1 row_mask:0xf bank_mask:0xf
	s_waitcnt lgkmcnt(0)
	v_cvt_f32_i32_e32 v216, v216
	v_cvt_f32_i32_e32 v220, v220
	v_mul_f32_e32 v216, v216, v232
	v_mul_f32_e32 v220, v220, v233
	v_fma_f32 v2, |v216|, s83, 1.0
	v_fma_f32 v7, |v220|, s83, 1.0
	v_rcp_f32_e32 v2, v2
	v_rcp_f32_e32 v7, v7
	v_mul_f32_e32 v5, v216, v216
	v_mul_f32_e32 v11, v220, v220
	v_mul_f32_e32 v5, 0xbf38aa3b, v5
	v_mul_f32_e32 v11, 0xbf38aa3b, v11
	v_exp_f32_e32 v5, v5
	v_exp_f32_e32 v11, v11
	v_fmamk_f32 v3, v2, 0x3f07dc22, v172
	v_fmamk_f32 v10, v7, 0x3f07dc22, v172
	v_fmaak_f32 v3, v2, v3, 0x3f35f0e3
	v_fmaak_f32 v10, v7, v10, 0x3f35f0e3
	v_fmaak_f32 v3, v2, v3, 0xbe11a98e
	v_fmaak_f32 v10, v7, v10, 0xbe11a98e
	v_fmaak_f32 v3, v2, v3, 0x3e027906
	v_fmaak_f32 v10, v7, v10, 0x3e027906
	v_mul_f32_e32 v3, v2, v3
	v_mul_f32_e32 v10, v7, v10
	v_mul_f32_e32 v3, v5, v3
	v_mul_f32_e32 v10, v11, v10
	v_mul_f32_e32 v6, v216, v3
	v_mul_f32_e32 v12, v220, v10
	v_fma_f32 v3, -v216, v3, v216
	v_fma_f32 v10, -v220, v10, v220
	v_cmp_gt_f32_e32 vcc, 0, v216
	v_cmp_gt_f32_e64 s[96:97], 0, v220
	s_nop 1
	v_cndmask_b32_e32 v216, v3, v6, vcc
	v_cndmask_b32_e64 v220, v10, v12, s[96:97]
	v_mul_f32_e32 v216, v216, v234
	v_mul_f32_e32 v220, v220, v235
	s_nop 0
	v_readlane_b32 s64, v216, 0
	v_readlane_b32 s65, v216, 32
	v_readlane_b32 s66, v216, 16
	v_readlane_b32 s67, v216, 48
	v_readlane_b32 s68, v220, 0
	v_readlane_b32 s69, v220, 32
	v_readlane_b32 s70, v220, 16
	v_readlane_b32 s71, v220, 48
	s_waitcnt vmcnt(60)
	v_cvt_scalef32_pk_f32_fp4 v[160:161], v176, 1.0
	v_cvt_scalef32_pk_f32_fp4 v[162:163], v176, 1.0 op_sel:[1,0,0]
	v_cvt_scalef32_pk_f32_fp4 v[18:19], v176, 1.0 op_sel:[0,1,0]
	v_pk_fma_f32 v[32:33], v[160:161], s[64:65], v[32:33] op_sel_hi:[1,0,1]
	v_cvt_scalef32_pk_f32_fp4 v[20:21], v176, 1.0 op_sel:[1,1,0]
	v_pk_fma_f32 v[34:35], v[162:163], s[64:65], v[34:35] op_sel_hi:[1,0,1]
	v_cvt_scalef32_pk_f32_fp4 v[22:23], v177, 1.0
	v_pk_fma_f32 v[36:37], v[18:19], s[64:65], v[36:37] op_sel_hi:[1,0,1]
	v_cvt_scalef32_pk_f32_fp4 v[30:31], v177, 1.0 op_sel:[1,0,0]
	v_pk_fma_f32 v[38:39], v[20:21], s[64:65], v[38:39] op_sel_hi:[1,0,1]
	v_cvt_scalef32_pk_f32_fp4 v[2:3], v177, 1.0 op_sel:[0,1,0]
	v_pk_fma_f32 v[40:41], v[22:23], s[64:65], v[40:41] op_sel_hi:[1,0,1]
	v_cvt_scalef32_pk_f32_fp4 v[6:7], v177, 1.0 op_sel:[1,1,0]
	v_pk_fma_f32 v[42:43], v[30:31], s[64:65], v[42:43] op_sel_hi:[1,0,1]
	v_cvt_scalef32_pk_f32_fp4 v[160:161], v178, 1.0
	v_pk_fma_f32 v[44:45], v[2:3], s[64:65], v[44:45] op_sel_hi:[1,0,1]
	v_cvt_scalef32_pk_f32_fp4 v[162:163], v178, 1.0 op_sel:[1,0,0]
	v_pk_fma_f32 v[46:47], v[6:7], s[64:65], v[46:47] op_sel_hi:[1,0,1]
	v_cvt_scalef32_pk_f32_fp4 v[18:19], v178, 1.0 op_sel:[0,1,0]
	v_pk_fma_f32 v[48:49], v[160:161], s[64:65], v[48:49] op_sel_hi:[1,0,1]
	v_cvt_scalef32_pk_f32_fp4 v[20:21], v178, 1.0 op_sel:[1,1,0]
	v_pk_fma_f32 v[50:51], v[162:163], s[64:65], v[50:51] op_sel_hi:[1,0,1]
	v_cvt_scalef32_pk_f32_fp4 v[22:23], v179, 1.0
	v_pk_fma_f32 v[52:53], v[18:19], s[64:65], v[52:53] op_sel_hi:[1,0,1]
	v_cvt_scalef32_pk_f32_fp4 v[30:31], v179, 1.0 op_sel:[1,0,0]
	v_pk_fma_f32 v[54:55], v[20:21], s[64:65], v[54:55] op_sel_hi:[1,0,1]
	v_cvt_scalef32_pk_f32_fp4 v[2:3], v179, 1.0 op_sel:[0,1,0]
	v_pk_fma_f32 v[56:57], v[22:23], s[64:65], v[56:57] op_sel_hi:[1,0,1]
	v_cvt_scalef32_pk_f32_fp4 v[6:7], v179, 1.0 op_sel:[1,1,0]
	v_pk_fma_f32 v[58:59], v[30:31], s[64:65], v[58:59] op_sel_hi:[1,0,1]
	v_pk_fma_f32 v[60:61], v[2:3], s[64:65], v[60:61] op_sel_hi:[1,0,1]
	v_pk_fma_f32 v[62:63], v[6:7], s[64:65], v[62:63] op_sel_hi:[1,0,1]
	s_waitcnt vmcnt(56)
	v_cvt_scalef32_pk_f32_fp4 v[160:161], v180, 1.0
	v_cvt_scalef32_pk_f32_fp4 v[162:163], v180, 1.0 op_sel:[1,0,0]
	v_cvt_scalef32_pk_f32_fp4 v[18:19], v180, 1.0 op_sel:[0,1,0]
	v_pk_fma_f32 v[32:33], v[160:161], s[64:65], v[32:33] op_sel:[0,1,0] op_sel_hi:[1,1,1]
	v_cvt_scalef32_pk_f32_fp4 v[20:21], v180, 1.0 op_sel:[1,1,0]
	v_pk_fma_f32 v[34:35], v[162:163], s[64:65], v[34:35] op_sel:[0,1,0] op_sel_hi:[1,1,1]
	v_cvt_scalef32_pk_f32_fp4 v[22:23], v181, 1.0
	v_pk_fma_f32 v[36:37], v[18:19], s[64:65], v[36:37] op_sel:[0,1,0] op_sel_hi:[1,1,1]
	v_cvt_scalef32_pk_f32_fp4 v[30:31], v181, 1.0 op_sel:[1,0,0]
	v_pk_fma_f32 v[38:39], v[20:21], s[64:65], v[38:39] op_sel:[0,1,0] op_sel_hi:[1,1,1]
	v_cvt_scalef32_pk_f32_fp4 v[2:3], v181, 1.0 op_sel:[0,1,0]
	v_pk_fma_f32 v[40:41], v[22:23], s[64:65], v[40:41] op_sel:[0,1,0] op_sel_hi:[1,1,1]
	v_cvt_scalef32_pk_f32_fp4 v[6:7], v181, 1.0 op_sel:[1,1,0]
	v_pk_fma_f32 v[42:43], v[30:31], s[64:65], v[42:43] op_sel:[0,1,0] op_sel_hi:[1,1,1]
	v_cvt_scalef32_pk_f32_fp4 v[160:161], v182, 1.0
	v_pk_fma_f32 v[44:45], v[2:3], s[64:65], v[44:45] op_sel:[0,1,0] op_sel_hi:[1,1,1]
	v_cvt_scalef32_pk_f32_fp4 v[162:163], v182, 1.0 op_sel:[1,0,0]
	v_pk_fma_f32 v[46:47], v[6:7], s[64:65], v[46:47] op_sel:[0,1,0] op_sel_hi:[1,1,1]
	v_cvt_scalef32_pk_f32_fp4 v[18:19], v182, 1.0 op_sel:[0,1,0]
	v_pk_fma_f32 v[48:49], v[160:161], s[64:65], v[48:49] op_sel:[0,1,0] op_sel_hi:[1,1,1]
	v_cvt_scalef32_pk_f32_fp4 v[20:21], v182, 1.0 op_sel:[1,1,0]
	v_pk_fma_f32 v[50:51], v[162:163], s[64:65], v[50:51] op_sel:[0,1,0] op_sel_hi:[1,1,1]
	v_cvt_scalef32_pk_f32_fp4 v[22:23], v183, 1.0
	v_pk_fma_f32 v[52:53], v[18:19], s[64:65], v[52:53] op_sel:[0,1,0] op_sel_hi:[1,1,1]
	v_cvt_scalef32_pk_f32_fp4 v[30:31], v183, 1.0 op_sel:[1,0,0]
	v_pk_fma_f32 v[54:55], v[20:21], s[64:65], v[54:55] op_sel:[0,1,0] op_sel_hi:[1,1,1]
	v_cvt_scalef32_pk_f32_fp4 v[2:3], v183, 1.0 op_sel:[0,1,0]
	v_pk_fma_f32 v[56:57], v[22:23], s[64:65], v[56:57] op_sel:[0,1,0] op_sel_hi:[1,1,1]
	v_cvt_scalef32_pk_f32_fp4 v[6:7], v183, 1.0 op_sel:[1,1,0]
	v_pk_fma_f32 v[58:59], v[30:31], s[64:65], v[58:59] op_sel:[0,1,0] op_sel_hi:[1,1,1]
	v_pk_fma_f32 v[60:61], v[2:3], s[64:65], v[60:61] op_sel:[0,1,0] op_sel_hi:[1,1,1]
	v_pk_fma_f32 v[62:63], v[6:7], s[64:65], v[62:63] op_sel:[0,1,0] op_sel_hi:[1,1,1]
	s_waitcnt vmcnt(52)
	v_cvt_scalef32_pk_f32_fp4 v[160:161], v184, 1.0
	v_cvt_scalef32_pk_f32_fp4 v[162:163], v184, 1.0 op_sel:[1,0,0]
	v_cvt_scalef32_pk_f32_fp4 v[18:19], v184, 1.0 op_sel:[0,1,0]
	v_pk_fma_f32 v[32:33], v[160:161], s[66:67], v[32:33] op_sel_hi:[1,0,1]
	v_cvt_scalef32_pk_f32_fp4 v[20:21], v184, 1.0 op_sel:[1,1,0]
	v_pk_fma_f32 v[34:35], v[162:163], s[66:67], v[34:35] op_sel_hi:[1,0,1]
	v_cvt_scalef32_pk_f32_fp4 v[22:23], v185, 1.0
	v_pk_fma_f32 v[36:37], v[18:19], s[66:67], v[36:37] op_sel_hi:[1,0,1]
	v_cvt_scalef32_pk_f32_fp4 v[30:31], v185, 1.0 op_sel:[1,0,0]
	v_pk_fma_f32 v[38:39], v[20:21], s[66:67], v[38:39] op_sel_hi:[1,0,1]
	v_cvt_scalef32_pk_f32_fp4 v[2:3], v185, 1.0 op_sel:[0,1,0]
	v_pk_fma_f32 v[40:41], v[22:23], s[66:67], v[40:41] op_sel_hi:[1,0,1]
	v_cvt_scalef32_pk_f32_fp4 v[6:7], v185, 1.0 op_sel:[1,1,0]
	v_pk_fma_f32 v[42:43], v[30:31], s[66:67], v[42:43] op_sel_hi:[1,0,1]
	v_cvt_scalef32_pk_f32_fp4 v[160:161], v186, 1.0
	v_pk_fma_f32 v[44:45], v[2:3], s[66:67], v[44:45] op_sel_hi:[1,0,1]
	v_cvt_scalef32_pk_f32_fp4 v[162:163], v186, 1.0 op_sel:[1,0,0]
	v_pk_fma_f32 v[46:47], v[6:7], s[66:67], v[46:47] op_sel_hi:[1,0,1]
	v_cvt_scalef32_pk_f32_fp4 v[18:19], v186, 1.0 op_sel:[0,1,0]
	v_pk_fma_f32 v[48:49], v[160:161], s[66:67], v[48:49] op_sel_hi:[1,0,1]
	v_cvt_scalef32_pk_f32_fp4 v[20:21], v186, 1.0 op_sel:[1,1,0]
	v_pk_fma_f32 v[50:51], v[162:163], s[66:67], v[50:51] op_sel_hi:[1,0,1]
	v_cvt_scalef32_pk_f32_fp4 v[22:23], v187, 1.0
	v_pk_fma_f32 v[52:53], v[18:19], s[66:67], v[52:53] op_sel_hi:[1,0,1]
	v_cvt_scalef32_pk_f32_fp4 v[30:31], v187, 1.0 op_sel:[1,0,0]
	v_pk_fma_f32 v[54:55], v[20:21], s[66:67], v[54:55] op_sel_hi:[1,0,1]
	v_cvt_scalef32_pk_f32_fp4 v[2:3], v187, 1.0 op_sel:[0,1,0]
	v_pk_fma_f32 v[56:57], v[22:23], s[66:67], v[56:57] op_sel_hi:[1,0,1]
	v_cvt_scalef32_pk_f32_fp4 v[6:7], v187, 1.0 op_sel:[1,1,0]
	v_pk_fma_f32 v[58:59], v[30:31], s[66:67], v[58:59] op_sel_hi:[1,0,1]
	v_pk_fma_f32 v[60:61], v[2:3], s[66:67], v[60:61] op_sel_hi:[1,0,1]
	v_pk_fma_f32 v[62:63], v[6:7], s[66:67], v[62:63] op_sel_hi:[1,0,1]
	s_waitcnt vmcnt(48)
	v_cvt_scalef32_pk_f32_fp4 v[160:161], v188, 1.0
	v_cvt_scalef32_pk_f32_fp4 v[162:163], v188, 1.0 op_sel:[1,0,0]
	v_cvt_scalef32_pk_f32_fp4 v[18:19], v188, 1.0 op_sel:[0,1,0]
	v_pk_fma_f32 v[32:33], v[160:161], s[66:67], v[32:33] op_sel:[0,1,0] op_sel_hi:[1,1,1]
	v_cvt_scalef32_pk_f32_fp4 v[20:21], v188, 1.0 op_sel:[1,1,0]
	v_pk_fma_f32 v[34:35], v[162:163], s[66:67], v[34:35] op_sel:[0,1,0] op_sel_hi:[1,1,1]
	v_cvt_scalef32_pk_f32_fp4 v[22:23], v189, 1.0
	v_pk_fma_f32 v[36:37], v[18:19], s[66:67], v[36:37] op_sel:[0,1,0] op_sel_hi:[1,1,1]
	v_cvt_scalef32_pk_f32_fp4 v[30:31], v189, 1.0 op_sel:[1,0,0]
	v_pk_fma_f32 v[38:39], v[20:21], s[66:67], v[38:39] op_sel:[0,1,0] op_sel_hi:[1,1,1]
	v_cvt_scalef32_pk_f32_fp4 v[2:3], v189, 1.0 op_sel:[0,1,0]
	v_pk_fma_f32 v[40:41], v[22:23], s[66:67], v[40:41] op_sel:[0,1,0] op_sel_hi:[1,1,1]
	v_cvt_scalef32_pk_f32_fp4 v[6:7], v189, 1.0 op_sel:[1,1,0]
	v_pk_fma_f32 v[42:43], v[30:31], s[66:67], v[42:43] op_sel:[0,1,0] op_sel_hi:[1,1,1]
	v_cvt_scalef32_pk_f32_fp4 v[160:161], v190, 1.0
	v_pk_fma_f32 v[44:45], v[2:3], s[66:67], v[44:45] op_sel:[0,1,0] op_sel_hi:[1,1,1]
	v_cvt_scalef32_pk_f32_fp4 v[162:163], v190, 1.0 op_sel:[1,0,0]
	v_pk_fma_f32 v[46:47], v[6:7], s[66:67], v[46:47] op_sel:[0,1,0] op_sel_hi:[1,1,1]
	v_cvt_scalef32_pk_f32_fp4 v[18:19], v190, 1.0 op_sel:[0,1,0]
	v_pk_fma_f32 v[48:49], v[160:161], s[66:67], v[48:49] op_sel:[0,1,0] op_sel_hi:[1,1,1]
	v_cvt_scalef32_pk_f32_fp4 v[20:21], v190, 1.0 op_sel:[1,1,0]
	v_pk_fma_f32 v[50:51], v[162:163], s[66:67], v[50:51] op_sel:[0,1,0] op_sel_hi:[1,1,1]
	v_cvt_scalef32_pk_f32_fp4 v[22:23], v191, 1.0
	v_pk_fma_f32 v[52:53], v[18:19], s[66:67], v[52:53] op_sel:[0,1,0] op_sel_hi:[1,1,1]
	v_cvt_scalef32_pk_f32_fp4 v[30:31], v191, 1.0 op_sel:[1,0,0]
	v_pk_fma_f32 v[54:55], v[20:21], s[66:67], v[54:55] op_sel:[0,1,0] op_sel_hi:[1,1,1]
	v_cvt_scalef32_pk_f32_fp4 v[2:3], v191, 1.0 op_sel:[0,1,0]
	v_pk_fma_f32 v[56:57], v[22:23], s[66:67], v[56:57] op_sel:[0,1,0] op_sel_hi:[1,1,1]
	v_cvt_scalef32_pk_f32_fp4 v[6:7], v191, 1.0 op_sel:[1,1,0]
	v_pk_fma_f32 v[58:59], v[30:31], s[66:67], v[58:59] op_sel:[0,1,0] op_sel_hi:[1,1,1]
	v_pk_fma_f32 v[60:61], v[2:3], s[66:67], v[60:61] op_sel:[0,1,0] op_sel_hi:[1,1,1]
	v_pk_fma_f32 v[62:63], v[6:7], s[66:67], v[62:63] op_sel:[0,1,0] op_sel_hi:[1,1,1]
	s_waitcnt vmcnt(44)
	v_cvt_scalef32_pk_f32_fp4 v[160:161], v192, 1.0
	v_cvt_scalef32_pk_f32_fp4 v[162:163], v192, 1.0 op_sel:[1,0,0]
	v_cvt_scalef32_pk_f32_fp4 v[18:19], v192, 1.0 op_sel:[0,1,0]
	v_pk_fma_f32 v[32:33], v[160:161], s[68:69], v[32:33] op_sel_hi:[1,0,1]
	v_cvt_scalef32_pk_f32_fp4 v[20:21], v192, 1.0 op_sel:[1,1,0]
	v_pk_fma_f32 v[34:35], v[162:163], s[68:69], v[34:35] op_sel_hi:[1,0,1]
	v_cvt_scalef32_pk_f32_fp4 v[22:23], v193, 1.0
	v_pk_fma_f32 v[36:37], v[18:19], s[68:69], v[36:37] op_sel_hi:[1,0,1]
	v_cvt_scalef32_pk_f32_fp4 v[30:31], v193, 1.0 op_sel:[1,0,0]
	v_pk_fma_f32 v[38:39], v[20:21], s[68:69], v[38:39] op_sel_hi:[1,0,1]
	v_cvt_scalef32_pk_f32_fp4 v[2:3], v193, 1.0 op_sel:[0,1,0]
	v_pk_fma_f32 v[40:41], v[22:23], s[68:69], v[40:41] op_sel_hi:[1,0,1]
	v_cvt_scalef32_pk_f32_fp4 v[6:7], v193, 1.0 op_sel:[1,1,0]
	v_pk_fma_f32 v[42:43], v[30:31], s[68:69], v[42:43] op_sel_hi:[1,0,1]
	v_cvt_scalef32_pk_f32_fp4 v[160:161], v194, 1.0
	v_pk_fma_f32 v[44:45], v[2:3], s[68:69], v[44:45] op_sel_hi:[1,0,1]
	v_cvt_scalef32_pk_f32_fp4 v[162:163], v194, 1.0 op_sel:[1,0,0]
	v_pk_fma_f32 v[46:47], v[6:7], s[68:69], v[46:47] op_sel_hi:[1,0,1]
	v_cvt_scalef32_pk_f32_fp4 v[18:19], v194, 1.0 op_sel:[0,1,0]
	v_pk_fma_f32 v[48:49], v[160:161], s[68:69], v[48:49] op_sel_hi:[1,0,1]
	v_cvt_scalef32_pk_f32_fp4 v[20:21], v194, 1.0 op_sel:[1,1,0]
	v_pk_fma_f32 v[50:51], v[162:163], s[68:69], v[50:51] op_sel_hi:[1,0,1]
	v_cvt_scalef32_pk_f32_fp4 v[22:23], v195, 1.0
	v_pk_fma_f32 v[52:53], v[18:19], s[68:69], v[52:53] op_sel_hi:[1,0,1]
	v_cvt_scalef32_pk_f32_fp4 v[30:31], v195, 1.0 op_sel:[1,0,0]
	v_pk_fma_f32 v[54:55], v[20:21], s[68:69], v[54:55] op_sel_hi:[1,0,1]
	v_cvt_scalef32_pk_f32_fp4 v[2:3], v195, 1.0 op_sel:[0,1,0]
	v_pk_fma_f32 v[56:57], v[22:23], s[68:69], v[56:57] op_sel_hi:[1,0,1]
	v_cvt_scalef32_pk_f32_fp4 v[6:7], v195, 1.0 op_sel:[1,1,0]
	v_pk_fma_f32 v[58:59], v[30:31], s[68:69], v[58:59] op_sel_hi:[1,0,1]
	v_pk_fma_f32 v[60:61], v[2:3], s[68:69], v[60:61] op_sel_hi:[1,0,1]
	v_pk_fma_f32 v[62:63], v[6:7], s[68:69], v[62:63] op_sel_hi:[1,0,1]
	s_waitcnt vmcnt(40)
	v_cvt_scalef32_pk_f32_fp4 v[160:161], v196, 1.0
	v_cvt_scalef32_pk_f32_fp4 v[162:163], v196, 1.0 op_sel:[1,0,0]
	v_cvt_scalef32_pk_f32_fp4 v[18:19], v196, 1.0 op_sel:[0,1,0]
	v_pk_fma_f32 v[32:33], v[160:161], s[68:69], v[32:33] op_sel:[0,1,0] op_sel_hi:[1,1,1]
	v_cvt_scalef32_pk_f32_fp4 v[20:21], v196, 1.0 op_sel:[1,1,0]
	v_pk_fma_f32 v[34:35], v[162:163], s[68:69], v[34:35] op_sel:[0,1,0] op_sel_hi:[1,1,1]
	v_cvt_scalef32_pk_f32_fp4 v[22:23], v197, 1.0
	v_pk_fma_f32 v[36:37], v[18:19], s[68:69], v[36:37] op_sel:[0,1,0] op_sel_hi:[1,1,1]
	v_cvt_scalef32_pk_f32_fp4 v[30:31], v197, 1.0 op_sel:[1,0,0]
	v_pk_fma_f32 v[38:39], v[20:21], s[68:69], v[38:39] op_sel:[0,1,0] op_sel_hi:[1,1,1]
	v_cvt_scalef32_pk_f32_fp4 v[2:3], v197, 1.0 op_sel:[0,1,0]
	v_pk_fma_f32 v[40:41], v[22:23], s[68:69], v[40:41] op_sel:[0,1,0] op_sel_hi:[1,1,1]
	v_cvt_scalef32_pk_f32_fp4 v[6:7], v197, 1.0 op_sel:[1,1,0]
	v_pk_fma_f32 v[42:43], v[30:31], s[68:69], v[42:43] op_sel:[0,1,0] op_sel_hi:[1,1,1]
	v_cvt_scalef32_pk_f32_fp4 v[160:161], v198, 1.0
	v_pk_fma_f32 v[44:45], v[2:3], s[68:69], v[44:45] op_sel:[0,1,0] op_sel_hi:[1,1,1]
	v_cvt_scalef32_pk_f32_fp4 v[162:163], v198, 1.0 op_sel:[1,0,0]
	v_pk_fma_f32 v[46:47], v[6:7], s[68:69], v[46:47] op_sel:[0,1,0] op_sel_hi:[1,1,1]
	v_cvt_scalef32_pk_f32_fp4 v[18:19], v198, 1.0 op_sel:[0,1,0]
	v_pk_fma_f32 v[48:49], v[160:161], s[68:69], v[48:49] op_sel:[0,1,0] op_sel_hi:[1,1,1]
	v_cvt_scalef32_pk_f32_fp4 v[20:21], v198, 1.0 op_sel:[1,1,0]
	v_pk_fma_f32 v[50:51], v[162:163], s[68:69], v[50:51] op_sel:[0,1,0] op_sel_hi:[1,1,1]
	v_cvt_scalef32_pk_f32_fp4 v[22:23], v199, 1.0
	v_pk_fma_f32 v[52:53], v[18:19], s[68:69], v[52:53] op_sel:[0,1,0] op_sel_hi:[1,1,1]
	v_cvt_scalef32_pk_f32_fp4 v[30:31], v199, 1.0 op_sel:[1,0,0]
	v_pk_fma_f32 v[54:55], v[20:21], s[68:69], v[54:55] op_sel:[0,1,0] op_sel_hi:[1,1,1]
	v_cvt_scalef32_pk_f32_fp4 v[2:3], v199, 1.0 op_sel:[0,1,0]
	v_pk_fma_f32 v[56:57], v[22:23], s[68:69], v[56:57] op_sel:[0,1,0] op_sel_hi:[1,1,1]
	v_cvt_scalef32_pk_f32_fp4 v[6:7], v199, 1.0 op_sel:[1,1,0]
	v_pk_fma_f32 v[58:59], v[30:31], s[68:69], v[58:59] op_sel:[0,1,0] op_sel_hi:[1,1,1]
	v_pk_fma_f32 v[60:61], v[2:3], s[68:69], v[60:61] op_sel:[0,1,0] op_sel_hi:[1,1,1]
	v_pk_fma_f32 v[62:63], v[6:7], s[68:69], v[62:63] op_sel:[0,1,0] op_sel_hi:[1,1,1]
	s_waitcnt vmcnt(36)
	v_cvt_scalef32_pk_f32_fp4 v[160:161], v200, 1.0
	v_cvt_scalef32_pk_f32_fp4 v[162:163], v200, 1.0 op_sel:[1,0,0]
	v_cvt_scalef32_pk_f32_fp4 v[18:19], v200, 1.0 op_sel:[0,1,0]
	v_pk_fma_f32 v[32:33], v[160:161], s[70:71], v[32:33] op_sel_hi:[1,0,1]
	v_cvt_scalef32_pk_f32_fp4 v[20:21], v200, 1.0 op_sel:[1,1,0]
	v_pk_fma_f32 v[34:35], v[162:163], s[70:71], v[34:35] op_sel_hi:[1,0,1]
	v_cvt_scalef32_pk_f32_fp4 v[22:23], v201, 1.0
	v_pk_fma_f32 v[36:37], v[18:19], s[70:71], v[36:37] op_sel_hi:[1,0,1]
	v_cvt_scalef32_pk_f32_fp4 v[30:31], v201, 1.0 op_sel:[1,0,0]
	v_pk_fma_f32 v[38:39], v[20:21], s[70:71], v[38:39] op_sel_hi:[1,0,1]
	v_cvt_scalef32_pk_f32_fp4 v[2:3], v201, 1.0 op_sel:[0,1,0]
	v_pk_fma_f32 v[40:41], v[22:23], s[70:71], v[40:41] op_sel_hi:[1,0,1]
	v_cvt_scalef32_pk_f32_fp4 v[6:7], v201, 1.0 op_sel:[1,1,0]
	v_pk_fma_f32 v[42:43], v[30:31], s[70:71], v[42:43] op_sel_hi:[1,0,1]
	v_cvt_scalef32_pk_f32_fp4 v[160:161], v202, 1.0
	v_pk_fma_f32 v[44:45], v[2:3], s[70:71], v[44:45] op_sel_hi:[1,0,1]
	v_cvt_scalef32_pk_f32_fp4 v[162:163], v202, 1.0 op_sel:[1,0,0]
	v_pk_fma_f32 v[46:47], v[6:7], s[70:71], v[46:47] op_sel_hi:[1,0,1]
	v_cvt_scalef32_pk_f32_fp4 v[18:19], v202, 1.0 op_sel:[0,1,0]
	v_pk_fma_f32 v[48:49], v[160:161], s[70:71], v[48:49] op_sel_hi:[1,0,1]
	v_cvt_scalef32_pk_f32_fp4 v[20:21], v202, 1.0 op_sel:[1,1,0]
	v_pk_fma_f32 v[50:51], v[162:163], s[70:71], v[50:51] op_sel_hi:[1,0,1]
	v_cvt_scalef32_pk_f32_fp4 v[22:23], v203, 1.0
	v_pk_fma_f32 v[52:53], v[18:19], s[70:71], v[52:53] op_sel_hi:[1,0,1]
	v_cvt_scalef32_pk_f32_fp4 v[30:31], v203, 1.0 op_sel:[1,0,0]
	v_pk_fma_f32 v[54:55], v[20:21], s[70:71], v[54:55] op_sel_hi:[1,0,1]
	v_cvt_scalef32_pk_f32_fp4 v[2:3], v203, 1.0 op_sel:[0,1,0]
	v_pk_fma_f32 v[56:57], v[22:23], s[70:71], v[56:57] op_sel_hi:[1,0,1]
	v_cvt_scalef32_pk_f32_fp4 v[6:7], v203, 1.0 op_sel:[1,1,0]
	v_pk_fma_f32 v[58:59], v[30:31], s[70:71], v[58:59] op_sel_hi:[1,0,1]
	v_pk_fma_f32 v[60:61], v[2:3], s[70:71], v[60:61] op_sel_hi:[1,0,1]
	v_pk_fma_f32 v[62:63], v[6:7], s[70:71], v[62:63] op_sel_hi:[1,0,1]
	s_waitcnt vmcnt(32)
	v_cvt_scalef32_pk_f32_fp4 v[160:161], v240, 1.0
	v_cvt_scalef32_pk_f32_fp4 v[162:163], v240, 1.0 op_sel:[1,0,0]
	v_cvt_scalef32_pk_f32_fp4 v[18:19], v240, 1.0 op_sel:[0,1,0]
	v_pk_fma_f32 v[32:33], v[160:161], s[70:71], v[32:33] op_sel:[0,1,0] op_sel_hi:[1,1,1]
	v_cvt_scalef32_pk_f32_fp4 v[20:21], v240, 1.0 op_sel:[1,1,0]
	v_pk_fma_f32 v[34:35], v[162:163], s[70:71], v[34:35] op_sel:[0,1,0] op_sel_hi:[1,1,1]
	v_cvt_scalef32_pk_f32_fp4 v[22:23], v241, 1.0
	v_pk_fma_f32 v[36:37], v[18:19], s[70:71], v[36:37] op_sel:[0,1,0] op_sel_hi:[1,1,1]
	v_cvt_scalef32_pk_f32_fp4 v[30:31], v241, 1.0 op_sel:[1,0,0]
	v_pk_fma_f32 v[38:39], v[20:21], s[70:71], v[38:39] op_sel:[0,1,0] op_sel_hi:[1,1,1]
	v_cvt_scalef32_pk_f32_fp4 v[2:3], v241, 1.0 op_sel:[0,1,0]
	v_pk_fma_f32 v[40:41], v[22:23], s[70:71], v[40:41] op_sel:[0,1,0] op_sel_hi:[1,1,1]
	v_cvt_scalef32_pk_f32_fp4 v[6:7], v241, 1.0 op_sel:[1,1,0]
	v_pk_fma_f32 v[42:43], v[30:31], s[70:71], v[42:43] op_sel:[0,1,0] op_sel_hi:[1,1,1]
	v_cvt_scalef32_pk_f32_fp4 v[160:161], v242, 1.0
	v_pk_fma_f32 v[44:45], v[2:3], s[70:71], v[44:45] op_sel:[0,1,0] op_sel_hi:[1,1,1]
	v_cvt_scalef32_pk_f32_fp4 v[162:163], v242, 1.0 op_sel:[1,0,0]
	v_pk_fma_f32 v[46:47], v[6:7], s[70:71], v[46:47] op_sel:[0,1,0] op_sel_hi:[1,1,1]
	v_cvt_scalef32_pk_f32_fp4 v[18:19], v242, 1.0 op_sel:[0,1,0]
	v_pk_fma_f32 v[48:49], v[160:161], s[70:71], v[48:49] op_sel:[0,1,0] op_sel_hi:[1,1,1]
	v_cvt_scalef32_pk_f32_fp4 v[20:21], v242, 1.0 op_sel:[1,1,0]
	v_pk_fma_f32 v[50:51], v[162:163], s[70:71], v[50:51] op_sel:[0,1,0] op_sel_hi:[1,1,1]
	v_cvt_scalef32_pk_f32_fp4 v[22:23], v243, 1.0
	v_pk_fma_f32 v[52:53], v[18:19], s[70:71], v[52:53] op_sel:[0,1,0] op_sel_hi:[1,1,1]
	v_cvt_scalef32_pk_f32_fp4 v[30:31], v243, 1.0 op_sel:[1,0,0]
	v_pk_fma_f32 v[54:55], v[20:21], s[70:71], v[54:55] op_sel:[0,1,0] op_sel_hi:[1,1,1]
	v_cvt_scalef32_pk_f32_fp4 v[2:3], v243, 1.0 op_sel:[0,1,0]
	v_pk_fma_f32 v[56:57], v[22:23], s[70:71], v[56:57] op_sel:[0,1,0] op_sel_hi:[1,1,1]
	v_cvt_scalef32_pk_f32_fp4 v[6:7], v243, 1.0 op_sel:[1,1,0]
	v_pk_fma_f32 v[58:59], v[30:31], s[70:71], v[58:59] op_sel:[0,1,0] op_sel_hi:[1,1,1]
	v_pk_fma_f32 v[60:61], v[2:3], s[70:71], v[60:61] op_sel:[0,1,0] op_sel_hi:[1,1,1]
	v_pk_fma_f32 v[62:63], v[6:7], s[70:71], v[62:63] op_sel:[0,1,0] op_sel_hi:[1,1,1]
	s_sub_u32 s86, s86, 1
	s_cmp_lg_u32 s86, 0
	s_cbranch_scc1 .Lp8_eloop
	ds_read_b128 v[10:13], v25
	ds_read_b128 v[18:21], v25 offset:16
	v_add_u32_e32 v25, 32, v25
	ds_read_b32 v232, v26
	ds_read_b32 v233, v27
	ds_read_b32 v234, v26 offset:512
	ds_read_b32 v235, v27 offset:512
	v_add_u32_e32 v26, 32, v26
	v_add_u32_e32 v27, 32, v27
	s_waitcnt vmcnt(30)
	v_mov_b32_e32 v216, 0
	v_mov_b32_e32 v224, 0
	v_dot8c_i32_i4_e32 v216, v64, v208
	v_dot8c_i32_i4_e32 v224, v64, v212
	v_dot8c_i32_i4_e32 v216, v65, v209
	v_dot8c_i32_i4_e32 v224, v65, v213
	v_dot8c_i32_i4_e32 v216, v66, v210
	v_dot8c_i32_i4_e32 v224, v66, v214
	v_dot8c_i32_i4_e32 v216, v67, v211
	v_dot8c_i32_i4_e32 v224, v67, v215
	s_waitcnt vmcnt(26)
	v_mov_b32_e32 v217, 0
	v_mov_b32_e32 v225, 0
	v_dot8c_i32_i4_e32 v217, v68, v208
	v_dot8c_i32_i4_e32 v225, v68, v212
	v_dot8c_i32_i4_e32 v217, v69, v209
	v_dot8c_i32_i4_e32 v225, v69, v213
	v_dot8c_i32_i4_e32 v217, v70, v210
	v_dot8c_i32_i4_e32 v225, v70, v214
	v_dot8c_i32_i4_e32 v217, v71, v211
	v_dot8c_i32_i4_e32 v225, v71, v215
	s_waitcnt vmcnt(22)
	v_mov_b32_e32 v218, 0
	v_mov_b32_e32 v226, 0
	v_dot8c_i32_i4_e32 v218, v72, v208
	v_dot8c_i32_i4_e32 v226, v72, v212
	v_dot8c_i32_i4_e32 v218, v73, v209
	v_dot8c_i32_i4_e32 v226, v73, v213
	v_dot8c_i32_i4_e32 v218, v74, v210
	v_dot8c_i32_i4_e32 v226, v74, v214
	v_dot8c_i32_i4_e32 v218, v75, v211
	v_dot8c_i32_i4_e32 v226, v75, v215
	s_waitcnt vmcnt(18)
	v_mov_b32_e32 v219, 0
	v_mov_b32_e32 v227, 0
	v_dot8c_i32_i4_e32 v219, v76, v208
	v_dot8c_i32_i4_e32 v227, v76, v212
	v_dot8c_i32_i4_e32 v219, v77, v209
	v_dot8c_i32_i4_e32 v227, v77, v213
	v_dot8c_i32_i4_e32 v219, v78, v210
	v_dot8c_i32_i4_e32 v227, v78, v214
	v_dot8c_i32_i4_e32 v219, v79, v211
	v_dot8c_i32_i4_e32 v227, v79, v215
	s_waitcnt vmcnt(14)
	v_mov_b32_e32 v220, 0
	v_mov_b32_e32 v228, 0
	v_dot8c_i32_i4_e32 v220, v80, v208
	v_dot8c_i32_i4_e32 v228, v80, v212
	v_dot8c_i32_i4_e32 v220, v81, v209
	v_dot8c_i32_i4_e32 v228, v81, v213
	v_dot8c_i32_i4_e32 v220, v82, v210
	v_dot8c_i32_i4_e32 v228, v82, v214
	v_dot8c_i32_i4_e32 v220, v83, v211
	v_dot8c_i32_i4_e32 v228, v83, v215
	s_waitcnt vmcnt(10)
	v_mov_b32_e32 v221, 0
	v_mov_b32_e32 v229, 0
	v_dot8c_i32_i4_e32 v221, v84, v208
	v_dot8c_i32_i4_e32 v229, v84, v212
	v_dot8c_i32_i4_e32 v221, v85, v209
	v_dot8c_i32_i4_e32 v229, v85, v213
	v_dot8c_i32_i4_e32 v221, v86, v210
	v_dot8c_i32_i4_e32 v229, v86, v214
	v_dot8c_i32_i4_e32 v221, v87, v211
	v_dot8c_i32_i4_e32 v229, v87, v215
	s_waitcnt vmcnt(6)
	v_mov_b32_e32 v222, 0
	v_mov_b32_e32 v230, 0
	v_dot8c_i32_i4_e32 v222, v88, v208
	v_dot8c_i32_i4_e32 v230, v88, v212
	v_dot8c_i32_i4_e32 v222, v89, v209
	v_dot8c_i32_i4_e32 v230, v89, v213
	v_dot8c_i32_i4_e32 v222, v90, v210
	v_dot8c_i32_i4_e32 v230, v90, v214
	v_dot8c_i32_i4_e32 v222, v91, v211
	v_dot8c_i32_i4_e32 v230, v91, v215
	s_waitcnt vmcnt(2)
	v_mov_b32_e32 v223, 0
	v_mov_b32_e32 v231, 0
	v_dot8c_i32_i4_e32 v223, v92, v208
	v_dot8c_i32_i4_e32 v231, v92, v212
	v_dot8c_i32_i4_e32 v223, v93, v209
	v_dot8c_i32_i4_e32 v231, v93, v213
	v_dot8c_i32_i4_e32 v223, v94, v210
	v_dot8c_i32_i4_e32 v231, v94, v214
	v_dot8c_i32_i4_e32 v223, v95, v211
	v_dot8c_i32_i4_e32 v231, v95, v215
	s_nop 2
	v_mad_i32_i24 v216, v216, 14, v224
	v_mad_i32_i24 v217, v217, 14, v225
	v_mad_i32_i24 v218, v218, 14, v226
	v_mad_i32_i24 v219, v219, 14, v227
	v_mad_i32_i24 v220, v220, 14, v228
	v_mad_i32_i24 v221, v221, 14, v229
	v_mad_i32_i24 v222, v222, 14, v230
	v_mad_i32_i24 v223, v223, 14, v231
	s_waitcnt lgkmcnt(4)
	v_readfirstlane_b32 s33, v10
	s_lshl_b32 s33, s33, 11
	s_add_u32 s72, s94, s33
	s_addc_u32 s73, s95, 0
	global_load_dwordx2 v[128:129], v28, s[72:73]
	global_load_dwordx2 v[130:131], v28, s[72:73] offset:512
	global_load_dwordx2 v[176:177], v28, s[72:73] offset:1024
	global_load_dwordx2 v[178:179], v28, s[72:73] offset:1536
	v_readfirstlane_b32 s33, v11
	s_lshl_b32 s33, s33, 11
	s_add_u32 s72, s94, s33
	s_addc_u32 s73, s95, 0
	global_load_dwordx2 v[132:133], v28, s[72:73]
	global_load_dwordx2 v[134:135], v28, s[72:73] offset:512
	global_load_dwordx2 v[180:181], v28, s[72:73] offset:1024
	global_load_dwordx2 v[182:183], v28, s[72:73] offset:1536
	v_readfirstlane_b32 s33, v12
	s_lshl_b32 s33, s33, 11
	s_add_u32 s72, s94, s33
	s_addc_u32 s73, s95, 0
	global_load_dwordx2 v[136:137], v28, s[72:73]
	global_load_dwordx2 v[138:139], v28, s[72:73] offset:512
	global_load_dwordx2 v[184:185], v28, s[72:73] offset:1024
	global_load_dwordx2 v[186:187], v28, s[72:73] offset:1536
	v_readfirstlane_b32 s33, v13
	s_lshl_b32 s33, s33, 11
	s_add_u32 s72, s94, s33
	s_addc_u32 s73, s95, 0
	global_load_dwordx2 v[140:141], v28, s[72:73]
	global_load_dwordx2 v[142:143], v28, s[72:73] offset:512
	global_load_dwordx2 v[188:189], v28, s[72:73] offset:1024
	global_load_dwordx2 v[190:191], v28, s[72:73] offset:1536
	v_readfirstlane_b32 s33, v18
	s_lshl_b32 s33, s33, 11
	s_add_u32 s72, s94, s33
	s_addc_u32 s73, s95, 0
	global_load_dwordx2 v[144:145], v28, s[72:73]
	global_load_dwordx2 v[146:147], v28, s[72:73] offset:512
	global_load_dwordx2 v[192:193], v28, s[72:73] offset:1024
	global_load_dwordx2 v[194:195], v28, s[72:73] offset:1536
	v_readfirstlane_b32 s33, v19
	s_lshl_b32 s33, s33, 11
	s_add_u32 s72, s94, s33
	s_addc_u32 s73, s95, 0
	global_load_dwordx2 v[148:149], v28, s[72:73]
	global_load_dwordx2 v[150:151], v28, s[72:73] offset:512
	global_load_dwordx2 v[196:197], v28, s[72:73] offset:1024
	global_load_dwordx2 v[198:199], v28, s[72:73] offset:1536
	v_readfirstlane_b32 s33, v20
	s_lshl_b32 s33, s33, 11
	s_add_u32 s72, s94, s33
	s_addc_u32 s73, s95, 0
	global_load_dwordx2 v[152:153], v28, s[72:73]
	global_load_dwordx2 v[154:155], v28, s[72:73] offset:512
	global_load_dwordx2 v[200:201], v28, s[72:73] offset:1024
	global_load_dwordx2 v[202:203], v28, s[72:73] offset:1536
	v_readfirstlane_b32 s33, v21
	s_lshl_b32 s33, s33, 11
	s_add_u32 s72, s94, s33
	s_addc_u32 s73, s95, 0
	global_load_dwordx2 v[156:157], v28, s[72:73]
	global_load_dwordx2 v[158:159], v28, s[72:73] offset:512
	global_load_dwordx2 v[240:241], v28, s[72:73] offset:1024
	global_load_dwordx2 v[242:243], v28, s[72:73] offset:1536
	s_nop 1
	v_permlane32_swap_b32_e32 v216, v217
	v_permlane32_swap_b32_e32 v218, v219
	v_permlane32_swap_b32_e32 v220, v221
	v_permlane32_swap_b32_e32 v222, v223
	v_add_u32_e32 v216, v216, v217
	v_add_u32_e32 v218, v218, v219
	v_add_u32_e32 v220, v220, v221
	v_add_u32_e32 v222, v222, v223
	s_nop 1
	v_permlane16_swap_b32_e32 v216, v218
	v_permlane16_swap_b32_e32 v220, v222
	v_add_u32_e32 v216, v216, v218
	v_add_u32_e32 v220, v220, v222
	s_nop 1
	v_add_u32_dpp v216, v216, v216 row_ror:8 row_mask:0xf bank_mask:0xf
	v_add_u32_dpp v220, v220, v220 row_ror:8 row_mask:0xf bank_mask:0xf
	s_nop 1
	v_add_u32_dpp v216, v216, v216 row_ror:4 row_mask:0xf bank_mask:0xf
	v_add_u32_dpp v220, v220, v220 row_ror:4 row_mask:0xf bank_mask:0xf
	s_nop 1
	v_add_u32_dpp v216, v216, v216 row_ror:2 row_mask:0xf bank_mask:0xf
	v_add_u32_dpp v220, v220, v220 row_ror:2 row_mask:0xf bank_mask:0xf
	s_nop 1
	v_add_u32_dpp v216, v216, v216 row_ror:1 row_mask:0xf bank_mask:0xf
	v_add_u32_dpp v220, v220, v220 row_ror:1 row_mask:0xf bank_mask:0xf
	s_waitcnt lgkmcnt(0)
	v_cvt_f32_i32_e32 v216, v216
	v_cvt_f32_i32_e32 v220, v220
	v_mul_f32_e32 v216, v216, v232
	v_mul_f32_e32 v220, v220, v233
	v_fma_f32 v2, |v216|, s83, 1.0
	v_fma_f32 v7, |v220|, s83, 1.0
	v_rcp_f32_e32 v2, v2
	v_rcp_f32_e32 v7, v7
	v_mul_f32_e32 v5, v216, v216
	v_mul_f32_e32 v11, v220, v220
	v_mul_f32_e32 v5, 0xbf38aa3b, v5
	v_mul_f32_e32 v11, 0xbf38aa3b, v11
	v_exp_f32_e32 v5, v5
	v_exp_f32_e32 v11, v11
	v_fmamk_f32 v3, v2, 0x3f07dc22, v172
	v_fmamk_f32 v10, v7, 0x3f07dc22, v172
	v_fmaak_f32 v3, v2, v3, 0x3f35f0e3
	v_fmaak_f32 v10, v7, v10, 0x3f35f0e3
	v_fmaak_f32 v3, v2, v3, 0xbe11a98e
	v_fmaak_f32 v10, v7, v10, 0xbe11a98e
	v_fmaak_f32 v3, v2, v3, 0x3e027906
	v_fmaak_f32 v10, v7, v10, 0x3e027906
	v_mul_f32_e32 v3, v2, v3
	v_mul_f32_e32 v10, v7, v10
	v_mul_f32_e32 v3, v5, v3
	v_mul_f32_e32 v10, v11, v10
	v_mul_f32_e32 v6, v216, v3
	v_mul_f32_e32 v12, v220, v10
	v_fma_f32 v3, -v216, v3, v216
	v_fma_f32 v10, -v220, v10, v220
	v_cmp_gt_f32_e32 vcc, 0, v216
	v_cmp_gt_f32_e64 s[96:97], 0, v220
	s_nop 1
	v_cndmask_b32_e32 v216, v3, v6, vcc
	v_cndmask_b32_e64 v220, v10, v12, s[96:97]
	v_mul_f32_e32 v216, v216, v234
	v_mul_f32_e32 v220, v220, v235
	s_nop 0
	v_readlane_b32 s64, v216, 0
	v_readlane_b32 s65, v216, 32
	v_readlane_b32 s66, v216, 16
	v_readlane_b32 s67, v216, 48
	v_readlane_b32 s68, v220, 0
	v_readlane_b32 s69, v220, 32
	v_readlane_b32 s70, v220, 16
	v_readlane_b32 s71, v220, 48
	s_waitcnt vmcnt(60)
	v_cvt_scalef32_pk_f32_fp4 v[160:161], v96, 1.0
	v_cvt_scalef32_pk_f32_fp4 v[162:163], v96, 1.0 op_sel:[1,0,0]
	v_cvt_scalef32_pk_f32_fp4 v[18:19], v96, 1.0 op_sel:[0,1,0]
	v_pk_fma_f32 v[32:33], v[160:161], s[64:65], v[32:33] op_sel_hi:[1,0,1]
	v_cvt_scalef32_pk_f32_fp4 v[20:21], v96, 1.0 op_sel:[1,1,0]
	v_pk_fma_f32 v[34:35], v[162:163], s[64:65], v[34:35] op_sel_hi:[1,0,1]
	v_cvt_scalef32_pk_f32_fp4 v[22:23], v97, 1.0
	v_pk_fma_f32 v[36:37], v[18:19], s[64:65], v[36:37] op_sel_hi:[1,0,1]
	v_cvt_scalef32_pk_f32_fp4 v[30:31], v97, 1.0 op_sel:[1,0,0]
	v_pk_fma_f32 v[38:39], v[20:21], s[64:65], v[38:39] op_sel_hi:[1,0,1]
	v_cvt_scalef32_pk_f32_fp4 v[2:3], v97, 1.0 op_sel:[0,1,0]
	v_pk_fma_f32 v[40:41], v[22:23], s[64:65], v[40:41] op_sel_hi:[1,0,1]
	v_cvt_scalef32_pk_f32_fp4 v[6:7], v97, 1.0 op_sel:[1,1,0]
	v_pk_fma_f32 v[42:43], v[30:31], s[64:65], v[42:43] op_sel_hi:[1,0,1]
	v_cvt_scalef32_pk_f32_fp4 v[160:161], v98, 1.0
	v_pk_fma_f32 v[44:45], v[2:3], s[64:65], v[44:45] op_sel_hi:[1,0,1]
	v_cvt_scalef32_pk_f32_fp4 v[162:163], v98, 1.0 op_sel:[1,0,0]
	v_pk_fma_f32 v[46:47], v[6:7], s[64:65], v[46:47] op_sel_hi:[1,0,1]
	v_cvt_scalef32_pk_f32_fp4 v[18:19], v98, 1.0 op_sel:[0,1,0]
	v_pk_fma_f32 v[48:49], v[160:161], s[64:65], v[48:49] op_sel_hi:[1,0,1]
	v_cvt_scalef32_pk_f32_fp4 v[20:21], v98, 1.0 op_sel:[1,1,0]
	v_pk_fma_f32 v[50:51], v[162:163], s[64:65], v[50:51] op_sel_hi:[1,0,1]
	v_cvt_scalef32_pk_f32_fp4 v[22:23], v99, 1.0
	v_pk_fma_f32 v[52:53], v[18:19], s[64:65], v[52:53] op_sel_hi:[1,0,1]
	v_cvt_scalef32_pk_f32_fp4 v[30:31], v99, 1.0 op_sel:[1,0,0]
	v_pk_fma_f32 v[54:55], v[20:21], s[64:65], v[54:55] op_sel_hi:[1,0,1]
	v_cvt_scalef32_pk_f32_fp4 v[2:3], v99, 1.0 op_sel:[0,1,0]
	v_pk_fma_f32 v[56:57], v[22:23], s[64:65], v[56:57] op_sel_hi:[1,0,1]
	v_cvt_scalef32_pk_f32_fp4 v[6:7], v99, 1.0 op_sel:[1,1,0]
	v_pk_fma_f32 v[58:59], v[30:31], s[64:65], v[58:59] op_sel_hi:[1,0,1]
	v_pk_fma_f32 v[60:61], v[2:3], s[64:65], v[60:61] op_sel_hi:[1,0,1]
	v_pk_fma_f32 v[62:63], v[6:7], s[64:65], v[62:63] op_sel_hi:[1,0,1]
	s_waitcnt vmcnt(56)
	v_cvt_scalef32_pk_f32_fp4 v[160:161], v100, 1.0
	v_cvt_scalef32_pk_f32_fp4 v[162:163], v100, 1.0 op_sel:[1,0,0]
	v_cvt_scalef32_pk_f32_fp4 v[18:19], v100, 1.0 op_sel:[0,1,0]
	v_pk_fma_f32 v[32:33], v[160:161], s[64:65], v[32:33] op_sel:[0,1,0] op_sel_hi:[1,1,1]
	v_cvt_scalef32_pk_f32_fp4 v[20:21], v100, 1.0 op_sel:[1,1,0]
	v_pk_fma_f32 v[34:35], v[162:163], s[64:65], v[34:35] op_sel:[0,1,0] op_sel_hi:[1,1,1]
	v_cvt_scalef32_pk_f32_fp4 v[22:23], v101, 1.0
	v_pk_fma_f32 v[36:37], v[18:19], s[64:65], v[36:37] op_sel:[0,1,0] op_sel_hi:[1,1,1]
	v_cvt_scalef32_pk_f32_fp4 v[30:31], v101, 1.0 op_sel:[1,0,0]
	v_pk_fma_f32 v[38:39], v[20:21], s[64:65], v[38:39] op_sel:[0,1,0] op_sel_hi:[1,1,1]
	v_cvt_scalef32_pk_f32_fp4 v[2:3], v101, 1.0 op_sel:[0,1,0]
	v_pk_fma_f32 v[40:41], v[22:23], s[64:65], v[40:41] op_sel:[0,1,0] op_sel_hi:[1,1,1]
	v_cvt_scalef32_pk_f32_fp4 v[6:7], v101, 1.0 op_sel:[1,1,0]
	v_pk_fma_f32 v[42:43], v[30:31], s[64:65], v[42:43] op_sel:[0,1,0] op_sel_hi:[1,1,1]
	v_cvt_scalef32_pk_f32_fp4 v[160:161], v102, 1.0
	v_pk_fma_f32 v[44:45], v[2:3], s[64:65], v[44:45] op_sel:[0,1,0] op_sel_hi:[1,1,1]
	v_cvt_scalef32_pk_f32_fp4 v[162:163], v102, 1.0 op_sel:[1,0,0]
	v_pk_fma_f32 v[46:47], v[6:7], s[64:65], v[46:47] op_sel:[0,1,0] op_sel_hi:[1,1,1]
	v_cvt_scalef32_pk_f32_fp4 v[18:19], v102, 1.0 op_sel:[0,1,0]
	v_pk_fma_f32 v[48:49], v[160:161], s[64:65], v[48:49] op_sel:[0,1,0] op_sel_hi:[1,1,1]
	v_cvt_scalef32_pk_f32_fp4 v[20:21], v102, 1.0 op_sel:[1,1,0]
	v_pk_fma_f32 v[50:51], v[162:163], s[64:65], v[50:51] op_sel:[0,1,0] op_sel_hi:[1,1,1]
	v_cvt_scalef32_pk_f32_fp4 v[22:23], v103, 1.0
	v_pk_fma_f32 v[52:53], v[18:19], s[64:65], v[52:53] op_sel:[0,1,0] op_sel_hi:[1,1,1]
	v_cvt_scalef32_pk_f32_fp4 v[30:31], v103, 1.0 op_sel:[1,0,0]
	v_pk_fma_f32 v[54:55], v[20:21], s[64:65], v[54:55] op_sel:[0,1,0] op_sel_hi:[1,1,1]
	v_cvt_scalef32_pk_f32_fp4 v[2:3], v103, 1.0 op_sel:[0,1,0]
	v_pk_fma_f32 v[56:57], v[22:23], s[64:65], v[56:57] op_sel:[0,1,0] op_sel_hi:[1,1,1]
	v_cvt_scalef32_pk_f32_fp4 v[6:7], v103, 1.0 op_sel:[1,1,0]
	v_pk_fma_f32 v[58:59], v[30:31], s[64:65], v[58:59] op_sel:[0,1,0] op_sel_hi:[1,1,1]
	v_pk_fma_f32 v[60:61], v[2:3], s[64:65], v[60:61] op_sel:[0,1,0] op_sel_hi:[1,1,1]
	v_pk_fma_f32 v[62:63], v[6:7], s[64:65], v[62:63] op_sel:[0,1,0] op_sel_hi:[1,1,1]
	s_waitcnt vmcnt(52)
	v_cvt_scalef32_pk_f32_fp4 v[160:161], v104, 1.0
	v_cvt_scalef32_pk_f32_fp4 v[162:163], v104, 1.0 op_sel:[1,0,0]
	v_cvt_scalef32_pk_f32_fp4 v[18:19], v104, 1.0 op_sel:[0,1,0]
	v_pk_fma_f32 v[32:33], v[160:161], s[66:67], v[32:33] op_sel_hi:[1,0,1]
	v_cvt_scalef32_pk_f32_fp4 v[20:21], v104, 1.0 op_sel:[1,1,0]
	v_pk_fma_f32 v[34:35], v[162:163], s[66:67], v[34:35] op_sel_hi:[1,0,1]
	v_cvt_scalef32_pk_f32_fp4 v[22:23], v105, 1.0
	v_pk_fma_f32 v[36:37], v[18:19], s[66:67], v[36:37] op_sel_hi:[1,0,1]
	v_cvt_scalef32_pk_f32_fp4 v[30:31], v105, 1.0 op_sel:[1,0,0]
	v_pk_fma_f32 v[38:39], v[20:21], s[66:67], v[38:39] op_sel_hi:[1,0,1]
	v_cvt_scalef32_pk_f32_fp4 v[2:3], v105, 1.0 op_sel:[0,1,0]
	v_pk_fma_f32 v[40:41], v[22:23], s[66:67], v[40:41] op_sel_hi:[1,0,1]
	v_cvt_scalef32_pk_f32_fp4 v[6:7], v105, 1.0 op_sel:[1,1,0]
	v_pk_fma_f32 v[42:43], v[30:31], s[66:67], v[42:43] op_sel_hi:[1,0,1]
	v_cvt_scalef32_pk_f32_fp4 v[160:161], v106, 1.0
	v_pk_fma_f32 v[44:45], v[2:3], s[66:67], v[44:45] op_sel_hi:[1,0,1]
	v_cvt_scalef32_pk_f32_fp4 v[162:163], v106, 1.0 op_sel:[1,0,0]
	v_pk_fma_f32 v[46:47], v[6:7], s[66:67], v[46:47] op_sel_hi:[1,0,1]
	v_cvt_scalef32_pk_f32_fp4 v[18:19], v106, 1.0 op_sel:[0,1,0]
	v_pk_fma_f32 v[48:49], v[160:161], s[66:67], v[48:49] op_sel_hi:[1,0,1]
	v_cvt_scalef32_pk_f32_fp4 v[20:21], v106, 1.0 op_sel:[1,1,0]
	v_pk_fma_f32 v[50:51], v[162:163], s[66:67], v[50:51] op_sel_hi:[1,0,1]
	v_cvt_scalef32_pk_f32_fp4 v[22:23], v107, 1.0
	v_pk_fma_f32 v[52:53], v[18:19], s[66:67], v[52:53] op_sel_hi:[1,0,1]
	v_cvt_scalef32_pk_f32_fp4 v[30:31], v107, 1.0 op_sel:[1,0,0]
	v_pk_fma_f32 v[54:55], v[20:21], s[66:67], v[54:55] op_sel_hi:[1,0,1]
	v_cvt_scalef32_pk_f32_fp4 v[2:3], v107, 1.0 op_sel:[0,1,0]
	v_pk_fma_f32 v[56:57], v[22:23], s[66:67], v[56:57] op_sel_hi:[1,0,1]
	v_cvt_scalef32_pk_f32_fp4 v[6:7], v107, 1.0 op_sel:[1,1,0]
	v_pk_fma_f32 v[58:59], v[30:31], s[66:67], v[58:59] op_sel_hi:[1,0,1]
	v_pk_fma_f32 v[60:61], v[2:3], s[66:67], v[60:61] op_sel_hi:[1,0,1]
	v_pk_fma_f32 v[62:63], v[6:7], s[66:67], v[62:63] op_sel_hi:[1,0,1]
	s_waitcnt vmcnt(48)
	v_cvt_scalef32_pk_f32_fp4 v[160:161], v108, 1.0
	v_cvt_scalef32_pk_f32_fp4 v[162:163], v108, 1.0 op_sel:[1,0,0]
	v_cvt_scalef32_pk_f32_fp4 v[18:19], v108, 1.0 op_sel:[0,1,0]
	v_pk_fma_f32 v[32:33], v[160:161], s[66:67], v[32:33] op_sel:[0,1,0] op_sel_hi:[1,1,1]
	v_cvt_scalef32_pk_f32_fp4 v[20:21], v108, 1.0 op_sel:[1,1,0]
	v_pk_fma_f32 v[34:35], v[162:163], s[66:67], v[34:35] op_sel:[0,1,0] op_sel_hi:[1,1,1]
	v_cvt_scalef32_pk_f32_fp4 v[22:23], v109, 1.0
	v_pk_fma_f32 v[36:37], v[18:19], s[66:67], v[36:37] op_sel:[0,1,0] op_sel_hi:[1,1,1]
	v_cvt_scalef32_pk_f32_fp4 v[30:31], v109, 1.0 op_sel:[1,0,0]
	v_pk_fma_f32 v[38:39], v[20:21], s[66:67], v[38:39] op_sel:[0,1,0] op_sel_hi:[1,1,1]
	v_cvt_scalef32_pk_f32_fp4 v[2:3], v109, 1.0 op_sel:[0,1,0]
	v_pk_fma_f32 v[40:41], v[22:23], s[66:67], v[40:41] op_sel:[0,1,0] op_sel_hi:[1,1,1]
	v_cvt_scalef32_pk_f32_fp4 v[6:7], v109, 1.0 op_sel:[1,1,0]
	v_pk_fma_f32 v[42:43], v[30:31], s[66:67], v[42:43] op_sel:[0,1,0] op_sel_hi:[1,1,1]
	v_cvt_scalef32_pk_f32_fp4 v[160:161], v110, 1.0
	v_pk_fma_f32 v[44:45], v[2:3], s[66:67], v[44:45] op_sel:[0,1,0] op_sel_hi:[1,1,1]
	v_cvt_scalef32_pk_f32_fp4 v[162:163], v110, 1.0 op_sel:[1,0,0]
	v_pk_fma_f32 v[46:47], v[6:7], s[66:67], v[46:47] op_sel:[0,1,0] op_sel_hi:[1,1,1]
	v_cvt_scalef32_pk_f32_fp4 v[18:19], v110, 1.0 op_sel:[0,1,0]
	v_pk_fma_f32 v[48:49], v[160:161], s[66:67], v[48:49] op_sel:[0,1,0] op_sel_hi:[1,1,1]
	v_cvt_scalef32_pk_f32_fp4 v[20:21], v110, 1.0 op_sel:[1,1,0]
	v_pk_fma_f32 v[50:51], v[162:163], s[66:67], v[50:51] op_sel:[0,1,0] op_sel_hi:[1,1,1]
	v_cvt_scalef32_pk_f32_fp4 v[22:23], v111, 1.0
	v_pk_fma_f32 v[52:53], v[18:19], s[66:67], v[52:53] op_sel:[0,1,0] op_sel_hi:[1,1,1]
	v_cvt_scalef32_pk_f32_fp4 v[30:31], v111, 1.0 op_sel:[1,0,0]
	v_pk_fma_f32 v[54:55], v[20:21], s[66:67], v[54:55] op_sel:[0,1,0] op_sel_hi:[1,1,1]
	v_cvt_scalef32_pk_f32_fp4 v[2:3], v111, 1.0 op_sel:[0,1,0]
	v_pk_fma_f32 v[56:57], v[22:23], s[66:67], v[56:57] op_sel:[0,1,0] op_sel_hi:[1,1,1]
	v_cvt_scalef32_pk_f32_fp4 v[6:7], v111, 1.0 op_sel:[1,1,0]
	v_pk_fma_f32 v[58:59], v[30:31], s[66:67], v[58:59] op_sel:[0,1,0] op_sel_hi:[1,1,1]
	v_pk_fma_f32 v[60:61], v[2:3], s[66:67], v[60:61] op_sel:[0,1,0] op_sel_hi:[1,1,1]
	v_pk_fma_f32 v[62:63], v[6:7], s[66:67], v[62:63] op_sel:[0,1,0] op_sel_hi:[1,1,1]
	s_waitcnt vmcnt(44)
	v_cvt_scalef32_pk_f32_fp4 v[160:161], v112, 1.0
	v_cvt_scalef32_pk_f32_fp4 v[162:163], v112, 1.0 op_sel:[1,0,0]
	v_cvt_scalef32_pk_f32_fp4 v[18:19], v112, 1.0 op_sel:[0,1,0]
	v_pk_fma_f32 v[32:33], v[160:161], s[68:69], v[32:33] op_sel_hi:[1,0,1]
	v_cvt_scalef32_pk_f32_fp4 v[20:21], v112, 1.0 op_sel:[1,1,0]
	v_pk_fma_f32 v[34:35], v[162:163], s[68:69], v[34:35] op_sel_hi:[1,0,1]
	v_cvt_scalef32_pk_f32_fp4 v[22:23], v113, 1.0
	v_pk_fma_f32 v[36:37], v[18:19], s[68:69], v[36:37] op_sel_hi:[1,0,1]
	v_cvt_scalef32_pk_f32_fp4 v[30:31], v113, 1.0 op_sel:[1,0,0]
	v_pk_fma_f32 v[38:39], v[20:21], s[68:69], v[38:39] op_sel_hi:[1,0,1]
	v_cvt_scalef32_pk_f32_fp4 v[2:3], v113, 1.0 op_sel:[0,1,0]
	v_pk_fma_f32 v[40:41], v[22:23], s[68:69], v[40:41] op_sel_hi:[1,0,1]
	v_cvt_scalef32_pk_f32_fp4 v[6:7], v113, 1.0 op_sel:[1,1,0]
	v_pk_fma_f32 v[42:43], v[30:31], s[68:69], v[42:43] op_sel_hi:[1,0,1]
	v_cvt_scalef32_pk_f32_fp4 v[160:161], v114, 1.0
	v_pk_fma_f32 v[44:45], v[2:3], s[68:69], v[44:45] op_sel_hi:[1,0,1]
	v_cvt_scalef32_pk_f32_fp4 v[162:163], v114, 1.0 op_sel:[1,0,0]
	v_pk_fma_f32 v[46:47], v[6:7], s[68:69], v[46:47] op_sel_hi:[1,0,1]
	v_cvt_scalef32_pk_f32_fp4 v[18:19], v114, 1.0 op_sel:[0,1,0]
	v_pk_fma_f32 v[48:49], v[160:161], s[68:69], v[48:49] op_sel_hi:[1,0,1]
	v_cvt_scalef32_pk_f32_fp4 v[20:21], v114, 1.0 op_sel:[1,1,0]
	v_pk_fma_f32 v[50:51], v[162:163], s[68:69], v[50:51] op_sel_hi:[1,0,1]
	v_cvt_scalef32_pk_f32_fp4 v[22:23], v115, 1.0
	v_pk_fma_f32 v[52:53], v[18:19], s[68:69], v[52:53] op_sel_hi:[1,0,1]
	v_cvt_scalef32_pk_f32_fp4 v[30:31], v115, 1.0 op_sel:[1,0,0]
	v_pk_fma_f32 v[54:55], v[20:21], s[68:69], v[54:55] op_sel_hi:[1,0,1]
	v_cvt_scalef32_pk_f32_fp4 v[2:3], v115, 1.0 op_sel:[0,1,0]
	v_pk_fma_f32 v[56:57], v[22:23], s[68:69], v[56:57] op_sel_hi:[1,0,1]
	v_cvt_scalef32_pk_f32_fp4 v[6:7], v115, 1.0 op_sel:[1,1,0]
	v_pk_fma_f32 v[58:59], v[30:31], s[68:69], v[58:59] op_sel_hi:[1,0,1]
	v_pk_fma_f32 v[60:61], v[2:3], s[68:69], v[60:61] op_sel_hi:[1,0,1]
	v_pk_fma_f32 v[62:63], v[6:7], s[68:69], v[62:63] op_sel_hi:[1,0,1]
	s_waitcnt vmcnt(40)
	v_cvt_scalef32_pk_f32_fp4 v[160:161], v116, 1.0
	v_cvt_scalef32_pk_f32_fp4 v[162:163], v116, 1.0 op_sel:[1,0,0]
	v_cvt_scalef32_pk_f32_fp4 v[18:19], v116, 1.0 op_sel:[0,1,0]
	v_pk_fma_f32 v[32:33], v[160:161], s[68:69], v[32:33] op_sel:[0,1,0] op_sel_hi:[1,1,1]
	v_cvt_scalef32_pk_f32_fp4 v[20:21], v116, 1.0 op_sel:[1,1,0]
	v_pk_fma_f32 v[34:35], v[162:163], s[68:69], v[34:35] op_sel:[0,1,0] op_sel_hi:[1,1,1]
	v_cvt_scalef32_pk_f32_fp4 v[22:23], v117, 1.0
	v_pk_fma_f32 v[36:37], v[18:19], s[68:69], v[36:37] op_sel:[0,1,0] op_sel_hi:[1,1,1]
	v_cvt_scalef32_pk_f32_fp4 v[30:31], v117, 1.0 op_sel:[1,0,0]
	v_pk_fma_f32 v[38:39], v[20:21], s[68:69], v[38:39] op_sel:[0,1,0] op_sel_hi:[1,1,1]
	v_cvt_scalef32_pk_f32_fp4 v[2:3], v117, 1.0 op_sel:[0,1,0]
	v_pk_fma_f32 v[40:41], v[22:23], s[68:69], v[40:41] op_sel:[0,1,0] op_sel_hi:[1,1,1]
	v_cvt_scalef32_pk_f32_fp4 v[6:7], v117, 1.0 op_sel:[1,1,0]
	v_pk_fma_f32 v[42:43], v[30:31], s[68:69], v[42:43] op_sel:[0,1,0] op_sel_hi:[1,1,1]
	v_cvt_scalef32_pk_f32_fp4 v[160:161], v118, 1.0
	v_pk_fma_f32 v[44:45], v[2:3], s[68:69], v[44:45] op_sel:[0,1,0] op_sel_hi:[1,1,1]
	v_cvt_scalef32_pk_f32_fp4 v[162:163], v118, 1.0 op_sel:[1,0,0]
	v_pk_fma_f32 v[46:47], v[6:7], s[68:69], v[46:47] op_sel:[0,1,0] op_sel_hi:[1,1,1]
	v_cvt_scalef32_pk_f32_fp4 v[18:19], v118, 1.0 op_sel:[0,1,0]
	v_pk_fma_f32 v[48:49], v[160:161], s[68:69], v[48:49] op_sel:[0,1,0] op_sel_hi:[1,1,1]
	v_cvt_scalef32_pk_f32_fp4 v[20:21], v118, 1.0 op_sel:[1,1,0]
	v_pk_fma_f32 v[50:51], v[162:163], s[68:69], v[50:51] op_sel:[0,1,0] op_sel_hi:[1,1,1]
	v_cvt_scalef32_pk_f32_fp4 v[22:23], v119, 1.0
	v_pk_fma_f32 v[52:53], v[18:19], s[68:69], v[52:53] op_sel:[0,1,0] op_sel_hi:[1,1,1]
	v_cvt_scalef32_pk_f32_fp4 v[30:31], v119, 1.0 op_sel:[1,0,0]
	v_pk_fma_f32 v[54:55], v[20:21], s[68:69], v[54:55] op_sel:[0,1,0] op_sel_hi:[1,1,1]
	v_cvt_scalef32_pk_f32_fp4 v[2:3], v119, 1.0 op_sel:[0,1,0]
	v_pk_fma_f32 v[56:57], v[22:23], s[68:69], v[56:57] op_sel:[0,1,0] op_sel_hi:[1,1,1]
	v_cvt_scalef32_pk_f32_fp4 v[6:7], v119, 1.0 op_sel:[1,1,0]
	v_pk_fma_f32 v[58:59], v[30:31], s[68:69], v[58:59] op_sel:[0,1,0] op_sel_hi:[1,1,1]
	v_pk_fma_f32 v[60:61], v[2:3], s[68:69], v[60:61] op_sel:[0,1,0] op_sel_hi:[1,1,1]
	v_pk_fma_f32 v[62:63], v[6:7], s[68:69], v[62:63] op_sel:[0,1,0] op_sel_hi:[1,1,1]
	s_waitcnt vmcnt(36)
	v_cvt_scalef32_pk_f32_fp4 v[160:161], v120, 1.0
	v_cvt_scalef32_pk_f32_fp4 v[162:163], v120, 1.0 op_sel:[1,0,0]
	v_cvt_scalef32_pk_f32_fp4 v[18:19], v120, 1.0 op_sel:[0,1,0]
	v_pk_fma_f32 v[32:33], v[160:161], s[70:71], v[32:33] op_sel_hi:[1,0,1]
	v_cvt_scalef32_pk_f32_fp4 v[20:21], v120, 1.0 op_sel:[1,1,0]
	v_pk_fma_f32 v[34:35], v[162:163], s[70:71], v[34:35] op_sel_hi:[1,0,1]
	v_cvt_scalef32_pk_f32_fp4 v[22:23], v121, 1.0
	v_pk_fma_f32 v[36:37], v[18:19], s[70:71], v[36:37] op_sel_hi:[1,0,1]
	v_cvt_scalef32_pk_f32_fp4 v[30:31], v121, 1.0 op_sel:[1,0,0]
	v_pk_fma_f32 v[38:39], v[20:21], s[70:71], v[38:39] op_sel_hi:[1,0,1]
	v_cvt_scalef32_pk_f32_fp4 v[2:3], v121, 1.0 op_sel:[0,1,0]
	v_pk_fma_f32 v[40:41], v[22:23], s[70:71], v[40:41] op_sel_hi:[1,0,1]
	v_cvt_scalef32_pk_f32_fp4 v[6:7], v121, 1.0 op_sel:[1,1,0]
	v_pk_fma_f32 v[42:43], v[30:31], s[70:71], v[42:43] op_sel_hi:[1,0,1]
	v_cvt_scalef32_pk_f32_fp4 v[160:161], v122, 1.0
	v_pk_fma_f32 v[44:45], v[2:3], s[70:71], v[44:45] op_sel_hi:[1,0,1]
	v_cvt_scalef32_pk_f32_fp4 v[162:163], v122, 1.0 op_sel:[1,0,0]
	v_pk_fma_f32 v[46:47], v[6:7], s[70:71], v[46:47] op_sel_hi:[1,0,1]
	v_cvt_scalef32_pk_f32_fp4 v[18:19], v122, 1.0 op_sel:[0,1,0]
	v_pk_fma_f32 v[48:49], v[160:161], s[70:71], v[48:49] op_sel_hi:[1,0,1]
	v_cvt_scalef32_pk_f32_fp4 v[20:21], v122, 1.0 op_sel:[1,1,0]
	v_pk_fma_f32 v[50:51], v[162:163], s[70:71], v[50:51] op_sel_hi:[1,0,1]
	v_cvt_scalef32_pk_f32_fp4 v[22:23], v123, 1.0
	v_pk_fma_f32 v[52:53], v[18:19], s[70:71], v[52:53] op_sel_hi:[1,0,1]
	v_cvt_scalef32_pk_f32_fp4 v[30:31], v123, 1.0 op_sel:[1,0,0]
	v_pk_fma_f32 v[54:55], v[20:21], s[70:71], v[54:55] op_sel_hi:[1,0,1]
	v_cvt_scalef32_pk_f32_fp4 v[2:3], v123, 1.0 op_sel:[0,1,0]
	v_pk_fma_f32 v[56:57], v[22:23], s[70:71], v[56:57] op_sel_hi:[1,0,1]
	v_cvt_scalef32_pk_f32_fp4 v[6:7], v123, 1.0 op_sel:[1,1,0]
	v_pk_fma_f32 v[58:59], v[30:31], s[70:71], v[58:59] op_sel_hi:[1,0,1]
	v_pk_fma_f32 v[60:61], v[2:3], s[70:71], v[60:61] op_sel_hi:[1,0,1]
	v_pk_fma_f32 v[62:63], v[6:7], s[70:71], v[62:63] op_sel_hi:[1,0,1]
	s_waitcnt vmcnt(32)
	v_cvt_scalef32_pk_f32_fp4 v[160:161], v124, 1.0
	v_cvt_scalef32_pk_f32_fp4 v[162:163], v124, 1.0 op_sel:[1,0,0]
	v_cvt_scalef32_pk_f32_fp4 v[18:19], v124, 1.0 op_sel:[0,1,0]
	v_pk_fma_f32 v[32:33], v[160:161], s[70:71], v[32:33] op_sel:[0,1,0] op_sel_hi:[1,1,1]
	v_cvt_scalef32_pk_f32_fp4 v[20:21], v124, 1.0 op_sel:[1,1,0]
	v_pk_fma_f32 v[34:35], v[162:163], s[70:71], v[34:35] op_sel:[0,1,0] op_sel_hi:[1,1,1]
	v_cvt_scalef32_pk_f32_fp4 v[22:23], v125, 1.0
	v_pk_fma_f32 v[36:37], v[18:19], s[70:71], v[36:37] op_sel:[0,1,0] op_sel_hi:[1,1,1]
	v_cvt_scalef32_pk_f32_fp4 v[30:31], v125, 1.0 op_sel:[1,0,0]
	v_pk_fma_f32 v[38:39], v[20:21], s[70:71], v[38:39] op_sel:[0,1,0] op_sel_hi:[1,1,1]
	v_cvt_scalef32_pk_f32_fp4 v[2:3], v125, 1.0 op_sel:[0,1,0]
	v_pk_fma_f32 v[40:41], v[22:23], s[70:71], v[40:41] op_sel:[0,1,0] op_sel_hi:[1,1,1]
	v_cvt_scalef32_pk_f32_fp4 v[6:7], v125, 1.0 op_sel:[1,1,0]
	v_pk_fma_f32 v[42:43], v[30:31], s[70:71], v[42:43] op_sel:[0,1,0] op_sel_hi:[1,1,1]
	v_cvt_scalef32_pk_f32_fp4 v[160:161], v126, 1.0
	v_pk_fma_f32 v[44:45], v[2:3], s[70:71], v[44:45] op_sel:[0,1,0] op_sel_hi:[1,1,1]
	v_cvt_scalef32_pk_f32_fp4 v[162:163], v126, 1.0 op_sel:[1,0,0]
	v_pk_fma_f32 v[46:47], v[6:7], s[70:71], v[46:47] op_sel:[0,1,0] op_sel_hi:[1,1,1]
	v_cvt_scalef32_pk_f32_fp4 v[18:19], v126, 1.0 op_sel:[0,1,0]
	v_pk_fma_f32 v[48:49], v[160:161], s[70:71], v[48:49] op_sel:[0,1,0] op_sel_hi:[1,1,1]
	v_cvt_scalef32_pk_f32_fp4 v[20:21], v126, 1.0 op_sel:[1,1,0]
	v_pk_fma_f32 v[50:51], v[162:163], s[70:71], v[50:51] op_sel:[0,1,0] op_sel_hi:[1,1,1]
	v_cvt_scalef32_pk_f32_fp4 v[22:23], v127, 1.0
	v_pk_fma_f32 v[52:53], v[18:19], s[70:71], v[52:53] op_sel:[0,1,0] op_sel_hi:[1,1,1]
	v_cvt_scalef32_pk_f32_fp4 v[30:31], v127, 1.0 op_sel:[1,0,0]
	v_pk_fma_f32 v[54:55], v[20:21], s[70:71], v[54:55] op_sel:[0,1,0] op_sel_hi:[1,1,1]
	v_cvt_scalef32_pk_f32_fp4 v[2:3], v127, 1.0 op_sel:[0,1,0]
	v_pk_fma_f32 v[56:57], v[22:23], s[70:71], v[56:57] op_sel:[0,1,0] op_sel_hi:[1,1,1]
	v_cvt_scalef32_pk_f32_fp4 v[6:7], v127, 1.0 op_sel:[1,1,0]
	v_pk_fma_f32 v[58:59], v[30:31], s[70:71], v[58:59] op_sel:[0,1,0] op_sel_hi:[1,1,1]
	v_pk_fma_f32 v[60:61], v[2:3], s[70:71], v[60:61] op_sel:[0,1,0] op_sel_hi:[1,1,1]
	v_pk_fma_f32 v[62:63], v[6:7], s[70:71], v[62:63] op_sel:[0,1,0] op_sel_hi:[1,1,1]
	ds_read_b32 v232, v26
	ds_read_b32 v233, v27
	ds_read_b32 v234, v26 offset:512
	ds_read_b32 v235, v27 offset:512
	v_add_u32_e32 v26, 32, v26
	v_add_u32_e32 v27, 32, v27
	s_waitcnt vmcnt(30)
	v_mov_b32_e32 v216, 0
	v_mov_b32_e32 v224, 0
	v_dot8c_i32_i4_e32 v216, v128, v208
	v_dot8c_i32_i4_e32 v224, v128, v212
	v_dot8c_i32_i4_e32 v216, v129, v209
	v_dot8c_i32_i4_e32 v224, v129, v213
	v_dot8c_i32_i4_e32 v216, v130, v210
	v_dot8c_i32_i4_e32 v224, v130, v214
	v_dot8c_i32_i4_e32 v216, v131, v211
	v_dot8c_i32_i4_e32 v224, v131, v215
	s_waitcnt vmcnt(26)
	v_mov_b32_e32 v217, 0
	v_mov_b32_e32 v225, 0
	v_dot8c_i32_i4_e32 v217, v132, v208
	v_dot8c_i32_i4_e32 v225, v132, v212
	v_dot8c_i32_i4_e32 v217, v133, v209
	v_dot8c_i32_i4_e32 v225, v133, v213
	v_dot8c_i32_i4_e32 v217, v134, v210
	v_dot8c_i32_i4_e32 v225, v134, v214
	v_dot8c_i32_i4_e32 v217, v135, v211
	v_dot8c_i32_i4_e32 v225, v135, v215
	s_waitcnt vmcnt(22)
	v_mov_b32_e32 v218, 0
	v_mov_b32_e32 v226, 0
	v_dot8c_i32_i4_e32 v218, v136, v208
	v_dot8c_i32_i4_e32 v226, v136, v212
	v_dot8c_i32_i4_e32 v218, v137, v209
	v_dot8c_i32_i4_e32 v226, v137, v213
	v_dot8c_i32_i4_e32 v218, v138, v210
	v_dot8c_i32_i4_e32 v226, v138, v214
	v_dot8c_i32_i4_e32 v218, v139, v211
	v_dot8c_i32_i4_e32 v226, v139, v215
	s_waitcnt vmcnt(18)
	v_mov_b32_e32 v219, 0
	v_mov_b32_e32 v227, 0
	v_dot8c_i32_i4_e32 v219, v140, v208
	v_dot8c_i32_i4_e32 v227, v140, v212
	v_dot8c_i32_i4_e32 v219, v141, v209
	v_dot8c_i32_i4_e32 v227, v141, v213
	v_dot8c_i32_i4_e32 v219, v142, v210
	v_dot8c_i32_i4_e32 v227, v142, v214
	v_dot8c_i32_i4_e32 v219, v143, v211
	v_dot8c_i32_i4_e32 v227, v143, v215
	s_waitcnt vmcnt(14)
	v_mov_b32_e32 v220, 0
	v_mov_b32_e32 v228, 0
	v_dot8c_i32_i4_e32 v220, v144, v208
	v_dot8c_i32_i4_e32 v228, v144, v212
	v_dot8c_i32_i4_e32 v220, v145, v209
	v_dot8c_i32_i4_e32 v228, v145, v213
	v_dot8c_i32_i4_e32 v220, v146, v210
	v_dot8c_i32_i4_e32 v228, v146, v214
	v_dot8c_i32_i4_e32 v220, v147, v211
	v_dot8c_i32_i4_e32 v228, v147, v215
	s_waitcnt vmcnt(10)
	v_mov_b32_e32 v221, 0
	v_mov_b32_e32 v229, 0
	v_dot8c_i32_i4_e32 v221, v148, v208
	v_dot8c_i32_i4_e32 v229, v148, v212
	v_dot8c_i32_i4_e32 v221, v149, v209
	v_dot8c_i32_i4_e32 v229, v149, v213
	v_dot8c_i32_i4_e32 v221, v150, v210
	v_dot8c_i32_i4_e32 v229, v150, v214
	v_dot8c_i32_i4_e32 v221, v151, v211
	v_dot8c_i32_i4_e32 v229, v151, v215
	s_waitcnt vmcnt(6)
	v_mov_b32_e32 v222, 0
	v_mov_b32_e32 v230, 0
	v_dot8c_i32_i4_e32 v222, v152, v208
	v_dot8c_i32_i4_e32 v230, v152, v212
	v_dot8c_i32_i4_e32 v222, v153, v209
	v_dot8c_i32_i4_e32 v230, v153, v213
	v_dot8c_i32_i4_e32 v222, v154, v210
	v_dot8c_i32_i4_e32 v230, v154, v214
	v_dot8c_i32_i4_e32 v222, v155, v211
	v_dot8c_i32_i4_e32 v230, v155, v215
	s_waitcnt vmcnt(2)
	v_mov_b32_e32 v223, 0
	v_mov_b32_e32 v231, 0
	v_dot8c_i32_i4_e32 v223, v156, v208
	v_dot8c_i32_i4_e32 v231, v156, v212
	v_dot8c_i32_i4_e32 v223, v157, v209
	v_dot8c_i32_i4_e32 v231, v157, v213
	v_dot8c_i32_i4_e32 v223, v158, v210
	v_dot8c_i32_i4_e32 v231, v158, v214
	v_dot8c_i32_i4_e32 v223, v159, v211
	v_dot8c_i32_i4_e32 v231, v159, v215
	s_nop 2
	v_mad_i32_i24 v216, v216, 14, v224
	v_mad_i32_i24 v217, v217, 14, v225
	v_mad_i32_i24 v218, v218, 14, v226
	v_mad_i32_i24 v219, v219, 14, v227
	v_mad_i32_i24 v220, v220, 14, v228
	v_mad_i32_i24 v221, v221, 14, v229
	v_mad_i32_i24 v222, v222, 14, v230
	v_mad_i32_i24 v223, v223, 14, v231
	s_nop 1
	v_permlane32_swap_b32_e32 v216, v217
	v_permlane32_swap_b32_e32 v218, v219
	v_permlane32_swap_b32_e32 v220, v221
	v_permlane32_swap_b32_e32 v222, v223
	v_add_u32_e32 v216, v216, v217
	v_add_u32_e32 v218, v218, v219
	v_add_u32_e32 v220, v220, v221
	v_add_u32_e32 v222, v222, v223
	s_nop 1
	v_permlane16_swap_b32_e32 v216, v218
	v_permlane16_swap_b32_e32 v220, v222
	v_add_u32_e32 v216, v216, v218
	v_add_u32_e32 v220, v220, v222
	s_nop 1
	v_add_u32_dpp v216, v216, v216 row_ror:8 row_mask:0xf bank_mask:0xf
	v_add_u32_dpp v220, v220, v220 row_ror:8 row_mask:0xf bank_mask:0xf
	s_nop 1
	v_add_u32_dpp v216, v216, v216 row_ror:4 row_mask:0xf bank_mask:0xf
	v_add_u32_dpp v220, v220, v220 row_ror:4 row_mask:0xf bank_mask:0xf
	s_nop 1
	v_add_u32_dpp v216, v216, v216 row_ror:2 row_mask:0xf bank_mask:0xf
	v_add_u32_dpp v220, v220, v220 row_ror:2 row_mask:0xf bank_mask:0xf
	s_nop 1
	v_add_u32_dpp v216, v216, v216 row_ror:1 row_mask:0xf bank_mask:0xf
	v_add_u32_dpp v220, v220, v220 row_ror:1 row_mask:0xf bank_mask:0xf
	s_waitcnt lgkmcnt(0)
	v_cvt_f32_i32_e32 v216, v216
	v_cvt_f32_i32_e32 v220, v220
	v_mul_f32_e32 v216, v216, v232
	v_mul_f32_e32 v220, v220, v233
	v_fma_f32 v2, |v216|, s83, 1.0
	v_fma_f32 v7, |v220|, s83, 1.0
	v_rcp_f32_e32 v2, v2
	v_rcp_f32_e32 v7, v7
	v_mul_f32_e32 v5, v216, v216
	v_mul_f32_e32 v11, v220, v220
	v_mul_f32_e32 v5, 0xbf38aa3b, v5
	v_mul_f32_e32 v11, 0xbf38aa3b, v11
	v_exp_f32_e32 v5, v5
	v_exp_f32_e32 v11, v11
	v_fmamk_f32 v3, v2, 0x3f07dc22, v172
	v_fmamk_f32 v10, v7, 0x3f07dc22, v172
	v_fmaak_f32 v3, v2, v3, 0x3f35f0e3
	v_fmaak_f32 v10, v7, v10, 0x3f35f0e3
	v_fmaak_f32 v3, v2, v3, 0xbe11a98e
	v_fmaak_f32 v10, v7, v10, 0xbe11a98e
	v_fmaak_f32 v3, v2, v3, 0x3e027906
	v_fmaak_f32 v10, v7, v10, 0x3e027906
	v_mul_f32_e32 v3, v2, v3
	v_mul_f32_e32 v10, v7, v10
	v_mul_f32_e32 v3, v5, v3
	v_mul_f32_e32 v10, v11, v10
	v_mul_f32_e32 v6, v216, v3
	v_mul_f32_e32 v12, v220, v10
	v_fma_f32 v3, -v216, v3, v216
	v_fma_f32 v10, -v220, v10, v220
	v_cmp_gt_f32_e32 vcc, 0, v216
	v_cmp_gt_f32_e64 s[96:97], 0, v220
	s_nop 1
	v_cndmask_b32_e32 v216, v3, v6, vcc
	v_cndmask_b32_e64 v220, v10, v12, s[96:97]
	v_mul_f32_e32 v216, v216, v234
	v_mul_f32_e32 v220, v220, v235
	s_nop 0
	v_readlane_b32 s64, v216, 0
	v_readlane_b32 s65, v216, 32
	v_readlane_b32 s66, v216, 16
	v_readlane_b32 s67, v216, 48
	v_readlane_b32 s68, v220, 0
	v_readlane_b32 s69, v220, 32
	v_readlane_b32 s70, v220, 16
	v_readlane_b32 s71, v220, 48
	s_waitcnt vmcnt(28)
	v_cvt_scalef32_pk_f32_fp4 v[160:161], v176, 1.0
	v_cvt_scalef32_pk_f32_fp4 v[162:163], v176, 1.0 op_sel:[1,0,0]
	v_cvt_scalef32_pk_f32_fp4 v[18:19], v176, 1.0 op_sel:[0,1,0]
	v_pk_fma_f32 v[32:33], v[160:161], s[64:65], v[32:33] op_sel_hi:[1,0,1]
	v_cvt_scalef32_pk_f32_fp4 v[20:21], v176, 1.0 op_sel:[1,1,0]
	v_pk_fma_f32 v[34:35], v[162:163], s[64:65], v[34:35] op_sel_hi:[1,0,1]
	v_cvt_scalef32_pk_f32_fp4 v[22:23], v177, 1.0
	v_pk_fma_f32 v[36:37], v[18:19], s[64:65], v[36:37] op_sel_hi:[1,0,1]
	v_cvt_scalef32_pk_f32_fp4 v[30:31], v177, 1.0 op_sel:[1,0,0]
	v_pk_fma_f32 v[38:39], v[20:21], s[64:65], v[38:39] op_sel_hi:[1,0,1]
	v_cvt_scalef32_pk_f32_fp4 v[2:3], v177, 1.0 op_sel:[0,1,0]
	v_pk_fma_f32 v[40:41], v[22:23], s[64:65], v[40:41] op_sel_hi:[1,0,1]
	v_cvt_scalef32_pk_f32_fp4 v[6:7], v177, 1.0 op_sel:[1,1,0]
	v_pk_fma_f32 v[42:43], v[30:31], s[64:65], v[42:43] op_sel_hi:[1,0,1]
	v_cvt_scalef32_pk_f32_fp4 v[160:161], v178, 1.0
	v_pk_fma_f32 v[44:45], v[2:3], s[64:65], v[44:45] op_sel_hi:[1,0,1]
	v_cvt_scalef32_pk_f32_fp4 v[162:163], v178, 1.0 op_sel:[1,0,0]
	v_pk_fma_f32 v[46:47], v[6:7], s[64:65], v[46:47] op_sel_hi:[1,0,1]
	v_cvt_scalef32_pk_f32_fp4 v[18:19], v178, 1.0 op_sel:[0,1,0]
	v_pk_fma_f32 v[48:49], v[160:161], s[64:65], v[48:49] op_sel_hi:[1,0,1]
	v_cvt_scalef32_pk_f32_fp4 v[20:21], v178, 1.0 op_sel:[1,1,0]
	v_pk_fma_f32 v[50:51], v[162:163], s[64:65], v[50:51] op_sel_hi:[1,0,1]
	v_cvt_scalef32_pk_f32_fp4 v[22:23], v179, 1.0
	v_pk_fma_f32 v[52:53], v[18:19], s[64:65], v[52:53] op_sel_hi:[1,0,1]
	v_cvt_scalef32_pk_f32_fp4 v[30:31], v179, 1.0 op_sel:[1,0,0]
	v_pk_fma_f32 v[54:55], v[20:21], s[64:65], v[54:55] op_sel_hi:[1,0,1]
	v_cvt_scalef32_pk_f32_fp4 v[2:3], v179, 1.0 op_sel:[0,1,0]
	v_pk_fma_f32 v[56:57], v[22:23], s[64:65], v[56:57] op_sel_hi:[1,0,1]
	v_cvt_scalef32_pk_f32_fp4 v[6:7], v179, 1.0 op_sel:[1,1,0]
	v_pk_fma_f32 v[58:59], v[30:31], s[64:65], v[58:59] op_sel_hi:[1,0,1]
	v_pk_fma_f32 v[60:61], v[2:3], s[64:65], v[60:61] op_sel_hi:[1,0,1]
	v_pk_fma_f32 v[62:63], v[6:7], s[64:65], v[62:63] op_sel_hi:[1,0,1]
	s_waitcnt vmcnt(24)
	v_cvt_scalef32_pk_f32_fp4 v[160:161], v180, 1.0
	v_cvt_scalef32_pk_f32_fp4 v[162:163], v180, 1.0 op_sel:[1,0,0]
	v_cvt_scalef32_pk_f32_fp4 v[18:19], v180, 1.0 op_sel:[0,1,0]
	v_pk_fma_f32 v[32:33], v[160:161], s[64:65], v[32:33] op_sel:[0,1,0] op_sel_hi:[1,1,1]
	v_cvt_scalef32_pk_f32_fp4 v[20:21], v180, 1.0 op_sel:[1,1,0]
	v_pk_fma_f32 v[34:35], v[162:163], s[64:65], v[34:35] op_sel:[0,1,0] op_sel_hi:[1,1,1]
	v_cvt_scalef32_pk_f32_fp4 v[22:23], v181, 1.0
	v_pk_fma_f32 v[36:37], v[18:19], s[64:65], v[36:37] op_sel:[0,1,0] op_sel_hi:[1,1,1]
	v_cvt_scalef32_pk_f32_fp4 v[30:31], v181, 1.0 op_sel:[1,0,0]
	v_pk_fma_f32 v[38:39], v[20:21], s[64:65], v[38:39] op_sel:[0,1,0] op_sel_hi:[1,1,1]
	v_cvt_scalef32_pk_f32_fp4 v[2:3], v181, 1.0 op_sel:[0,1,0]
	v_pk_fma_f32 v[40:41], v[22:23], s[64:65], v[40:41] op_sel:[0,1,0] op_sel_hi:[1,1,1]
	v_cvt_scalef32_pk_f32_fp4 v[6:7], v181, 1.0 op_sel:[1,1,0]
	v_pk_fma_f32 v[42:43], v[30:31], s[64:65], v[42:43] op_sel:[0,1,0] op_sel_hi:[1,1,1]
	v_cvt_scalef32_pk_f32_fp4 v[160:161], v182, 1.0
	v_pk_fma_f32 v[44:45], v[2:3], s[64:65], v[44:45] op_sel:[0,1,0] op_sel_hi:[1,1,1]
	v_cvt_scalef32_pk_f32_fp4 v[162:163], v182, 1.0 op_sel:[1,0,0]
	v_pk_fma_f32 v[46:47], v[6:7], s[64:65], v[46:47] op_sel:[0,1,0] op_sel_hi:[1,1,1]
	v_cvt_scalef32_pk_f32_fp4 v[18:19], v182, 1.0 op_sel:[0,1,0]
	v_pk_fma_f32 v[48:49], v[160:161], s[64:65], v[48:49] op_sel:[0,1,0] op_sel_hi:[1,1,1]
	v_cvt_scalef32_pk_f32_fp4 v[20:21], v182, 1.0 op_sel:[1,1,0]
	v_pk_fma_f32 v[50:51], v[162:163], s[64:65], v[50:51] op_sel:[0,1,0] op_sel_hi:[1,1,1]
	v_cvt_scalef32_pk_f32_fp4 v[22:23], v183, 1.0
	v_pk_fma_f32 v[52:53], v[18:19], s[64:65], v[52:53] op_sel:[0,1,0] op_sel_hi:[1,1,1]
	v_cvt_scalef32_pk_f32_fp4 v[30:31], v183, 1.0 op_sel:[1,0,0]
	v_pk_fma_f32 v[54:55], v[20:21], s[64:65], v[54:55] op_sel:[0,1,0] op_sel_hi:[1,1,1]
	v_cvt_scalef32_pk_f32_fp4 v[2:3], v183, 1.0 op_sel:[0,1,0]
	v_pk_fma_f32 v[56:57], v[22:23], s[64:65], v[56:57] op_sel:[0,1,0] op_sel_hi:[1,1,1]
	v_cvt_scalef32_pk_f32_fp4 v[6:7], v183, 1.0 op_sel:[1,1,0]
	v_pk_fma_f32 v[58:59], v[30:31], s[64:65], v[58:59] op_sel:[0,1,0] op_sel_hi:[1,1,1]
	v_pk_fma_f32 v[60:61], v[2:3], s[64:65], v[60:61] op_sel:[0,1,0] op_sel_hi:[1,1,1]
	v_pk_fma_f32 v[62:63], v[6:7], s[64:65], v[62:63] op_sel:[0,1,0] op_sel_hi:[1,1,1]
	s_waitcnt vmcnt(20)
	v_cvt_scalef32_pk_f32_fp4 v[160:161], v184, 1.0
	v_cvt_scalef32_pk_f32_fp4 v[162:163], v184, 1.0 op_sel:[1,0,0]
	v_cvt_scalef32_pk_f32_fp4 v[18:19], v184, 1.0 op_sel:[0,1,0]
	v_pk_fma_f32 v[32:33], v[160:161], s[66:67], v[32:33] op_sel_hi:[1,0,1]
	v_cvt_scalef32_pk_f32_fp4 v[20:21], v184, 1.0 op_sel:[1,1,0]
	v_pk_fma_f32 v[34:35], v[162:163], s[66:67], v[34:35] op_sel_hi:[1,0,1]
	v_cvt_scalef32_pk_f32_fp4 v[22:23], v185, 1.0
	v_pk_fma_f32 v[36:37], v[18:19], s[66:67], v[36:37] op_sel_hi:[1,0,1]
	v_cvt_scalef32_pk_f32_fp4 v[30:31], v185, 1.0 op_sel:[1,0,0]
	v_pk_fma_f32 v[38:39], v[20:21], s[66:67], v[38:39] op_sel_hi:[1,0,1]
	v_cvt_scalef32_pk_f32_fp4 v[2:3], v185, 1.0 op_sel:[0,1,0]
	v_pk_fma_f32 v[40:41], v[22:23], s[66:67], v[40:41] op_sel_hi:[1,0,1]
	v_cvt_scalef32_pk_f32_fp4 v[6:7], v185, 1.0 op_sel:[1,1,0]
	v_pk_fma_f32 v[42:43], v[30:31], s[66:67], v[42:43] op_sel_hi:[1,0,1]
	v_cvt_scalef32_pk_f32_fp4 v[160:161], v186, 1.0
	v_pk_fma_f32 v[44:45], v[2:3], s[66:67], v[44:45] op_sel_hi:[1,0,1]
	v_cvt_scalef32_pk_f32_fp4 v[162:163], v186, 1.0 op_sel:[1,0,0]
	v_pk_fma_f32 v[46:47], v[6:7], s[66:67], v[46:47] op_sel_hi:[1,0,1]
	v_cvt_scalef32_pk_f32_fp4 v[18:19], v186, 1.0 op_sel:[0,1,0]
	v_pk_fma_f32 v[48:49], v[160:161], s[66:67], v[48:49] op_sel_hi:[1,0,1]
	v_cvt_scalef32_pk_f32_fp4 v[20:21], v186, 1.0 op_sel:[1,1,0]
	v_pk_fma_f32 v[50:51], v[162:163], s[66:67], v[50:51] op_sel_hi:[1,0,1]
	v_cvt_scalef32_pk_f32_fp4 v[22:23], v187, 1.0
	v_pk_fma_f32 v[52:53], v[18:19], s[66:67], v[52:53] op_sel_hi:[1,0,1]
	v_cvt_scalef32_pk_f32_fp4 v[30:31], v187, 1.0 op_sel:[1,0,0]
	v_pk_fma_f32 v[54:55], v[20:21], s[66:67], v[54:55] op_sel_hi:[1,0,1]
	v_cvt_scalef32_pk_f32_fp4 v[2:3], v187, 1.0 op_sel:[0,1,0]
	v_pk_fma_f32 v[56:57], v[22:23], s[66:67], v[56:57] op_sel_hi:[1,0,1]
	v_cvt_scalef32_pk_f32_fp4 v[6:7], v187, 1.0 op_sel:[1,1,0]
	v_pk_fma_f32 v[58:59], v[30:31], s[66:67], v[58:59] op_sel_hi:[1,0,1]
	v_pk_fma_f32 v[60:61], v[2:3], s[66:67], v[60:61] op_sel_hi:[1,0,1]
	v_pk_fma_f32 v[62:63], v[6:7], s[66:67], v[62:63] op_sel_hi:[1,0,1]
	s_waitcnt vmcnt(16)
	v_cvt_scalef32_pk_f32_fp4 v[160:161], v188, 1.0
	v_cvt_scalef32_pk_f32_fp4 v[162:163], v188, 1.0 op_sel:[1,0,0]
	v_cvt_scalef32_pk_f32_fp4 v[18:19], v188, 1.0 op_sel:[0,1,0]
	v_pk_fma_f32 v[32:33], v[160:161], s[66:67], v[32:33] op_sel:[0,1,0] op_sel_hi:[1,1,1]
	v_cvt_scalef32_pk_f32_fp4 v[20:21], v188, 1.0 op_sel:[1,1,0]
	v_pk_fma_f32 v[34:35], v[162:163], s[66:67], v[34:35] op_sel:[0,1,0] op_sel_hi:[1,1,1]
	v_cvt_scalef32_pk_f32_fp4 v[22:23], v189, 1.0
	v_pk_fma_f32 v[36:37], v[18:19], s[66:67], v[36:37] op_sel:[0,1,0] op_sel_hi:[1,1,1]
	v_cvt_scalef32_pk_f32_fp4 v[30:31], v189, 1.0 op_sel:[1,0,0]
	v_pk_fma_f32 v[38:39], v[20:21], s[66:67], v[38:39] op_sel:[0,1,0] op_sel_hi:[1,1,1]
	v_cvt_scalef32_pk_f32_fp4 v[2:3], v189, 1.0 op_sel:[0,1,0]
	v_pk_fma_f32 v[40:41], v[22:23], s[66:67], v[40:41] op_sel:[0,1,0] op_sel_hi:[1,1,1]
	v_cvt_scalef32_pk_f32_fp4 v[6:7], v189, 1.0 op_sel:[1,1,0]
	v_pk_fma_f32 v[42:43], v[30:31], s[66:67], v[42:43] op_sel:[0,1,0] op_sel_hi:[1,1,1]
	v_cvt_scalef32_pk_f32_fp4 v[160:161], v190, 1.0
	v_pk_fma_f32 v[44:45], v[2:3], s[66:67], v[44:45] op_sel:[0,1,0] op_sel_hi:[1,1,1]
	v_cvt_scalef32_pk_f32_fp4 v[162:163], v190, 1.0 op_sel:[1,0,0]
	v_pk_fma_f32 v[46:47], v[6:7], s[66:67], v[46:47] op_sel:[0,1,0] op_sel_hi:[1,1,1]
	v_cvt_scalef32_pk_f32_fp4 v[18:19], v190, 1.0 op_sel:[0,1,0]
	v_pk_fma_f32 v[48:49], v[160:161], s[66:67], v[48:49] op_sel:[0,1,0] op_sel_hi:[1,1,1]
	v_cvt_scalef32_pk_f32_fp4 v[20:21], v190, 1.0 op_sel:[1,1,0]
	v_pk_fma_f32 v[50:51], v[162:163], s[66:67], v[50:51] op_sel:[0,1,0] op_sel_hi:[1,1,1]
	v_cvt_scalef32_pk_f32_fp4 v[22:23], v191, 1.0
	v_pk_fma_f32 v[52:53], v[18:19], s[66:67], v[52:53] op_sel:[0,1,0] op_sel_hi:[1,1,1]
	v_cvt_scalef32_pk_f32_fp4 v[30:31], v191, 1.0 op_sel:[1,0,0]
	v_pk_fma_f32 v[54:55], v[20:21], s[66:67], v[54:55] op_sel:[0,1,0] op_sel_hi:[1,1,1]
	v_cvt_scalef32_pk_f32_fp4 v[2:3], v191, 1.0 op_sel:[0,1,0]
	v_pk_fma_f32 v[56:57], v[22:23], s[66:67], v[56:57] op_sel:[0,1,0] op_sel_hi:[1,1,1]
	v_cvt_scalef32_pk_f32_fp4 v[6:7], v191, 1.0 op_sel:[1,1,0]
	v_pk_fma_f32 v[58:59], v[30:31], s[66:67], v[58:59] op_sel:[0,1,0] op_sel_hi:[1,1,1]
	v_pk_fma_f32 v[60:61], v[2:3], s[66:67], v[60:61] op_sel:[0,1,0] op_sel_hi:[1,1,1]
	v_pk_fma_f32 v[62:63], v[6:7], s[66:67], v[62:63] op_sel:[0,1,0] op_sel_hi:[1,1,1]
	s_waitcnt vmcnt(12)
	v_cvt_scalef32_pk_f32_fp4 v[160:161], v192, 1.0
	v_cvt_scalef32_pk_f32_fp4 v[162:163], v192, 1.0 op_sel:[1,0,0]
	v_cvt_scalef32_pk_f32_fp4 v[18:19], v192, 1.0 op_sel:[0,1,0]
	v_pk_fma_f32 v[32:33], v[160:161], s[68:69], v[32:33] op_sel_hi:[1,0,1]
	v_cvt_scalef32_pk_f32_fp4 v[20:21], v192, 1.0 op_sel:[1,1,0]
	v_pk_fma_f32 v[34:35], v[162:163], s[68:69], v[34:35] op_sel_hi:[1,0,1]
	v_cvt_scalef32_pk_f32_fp4 v[22:23], v193, 1.0
	v_pk_fma_f32 v[36:37], v[18:19], s[68:69], v[36:37] op_sel_hi:[1,0,1]
	v_cvt_scalef32_pk_f32_fp4 v[30:31], v193, 1.0 op_sel:[1,0,0]
	v_pk_fma_f32 v[38:39], v[20:21], s[68:69], v[38:39] op_sel_hi:[1,0,1]
	v_cvt_scalef32_pk_f32_fp4 v[2:3], v193, 1.0 op_sel:[0,1,0]
	v_pk_fma_f32 v[40:41], v[22:23], s[68:69], v[40:41] op_sel_hi:[1,0,1]
	v_cvt_scalef32_pk_f32_fp4 v[6:7], v193, 1.0 op_sel:[1,1,0]
	v_pk_fma_f32 v[42:43], v[30:31], s[68:69], v[42:43] op_sel_hi:[1,0,1]
	v_cvt_scalef32_pk_f32_fp4 v[160:161], v194, 1.0
	v_pk_fma_f32 v[44:45], v[2:3], s[68:69], v[44:45] op_sel_hi:[1,0,1]
	v_cvt_scalef32_pk_f32_fp4 v[162:163], v194, 1.0 op_sel:[1,0,0]
	v_pk_fma_f32 v[46:47], v[6:7], s[68:69], v[46:47] op_sel_hi:[1,0,1]
	v_cvt_scalef32_pk_f32_fp4 v[18:19], v194, 1.0 op_sel:[0,1,0]
	v_pk_fma_f32 v[48:49], v[160:161], s[68:69], v[48:49] op_sel_hi:[1,0,1]
	v_cvt_scalef32_pk_f32_fp4 v[20:21], v194, 1.0 op_sel:[1,1,0]
	v_pk_fma_f32 v[50:51], v[162:163], s[68:69], v[50:51] op_sel_hi:[1,0,1]
	v_cvt_scalef32_pk_f32_fp4 v[22:23], v195, 1.0
	v_pk_fma_f32 v[52:53], v[18:19], s[68:69], v[52:53] op_sel_hi:[1,0,1]
	v_cvt_scalef32_pk_f32_fp4 v[30:31], v195, 1.0 op_sel:[1,0,0]
	v_pk_fma_f32 v[54:55], v[20:21], s[68:69], v[54:55] op_sel_hi:[1,0,1]
	v_cvt_scalef32_pk_f32_fp4 v[2:3], v195, 1.0 op_sel:[0,1,0]
	v_pk_fma_f32 v[56:57], v[22:23], s[68:69], v[56:57] op_sel_hi:[1,0,1]
	v_cvt_scalef32_pk_f32_fp4 v[6:7], v195, 1.0 op_sel:[1,1,0]
	v_pk_fma_f32 v[58:59], v[30:31], s[68:69], v[58:59] op_sel_hi:[1,0,1]
	v_pk_fma_f32 v[60:61], v[2:3], s[68:69], v[60:61] op_sel_hi:[1,0,1]
	v_pk_fma_f32 v[62:63], v[6:7], s[68:69], v[62:63] op_sel_hi:[1,0,1]
	s_waitcnt vmcnt(8)
	v_cvt_scalef32_pk_f32_fp4 v[160:161], v196, 1.0
	v_cvt_scalef32_pk_f32_fp4 v[162:163], v196, 1.0 op_sel:[1,0,0]
	v_cvt_scalef32_pk_f32_fp4 v[18:19], v196, 1.0 op_sel:[0,1,0]
	v_pk_fma_f32 v[32:33], v[160:161], s[68:69], v[32:33] op_sel:[0,1,0] op_sel_hi:[1,1,1]
	v_cvt_scalef32_pk_f32_fp4 v[20:21], v196, 1.0 op_sel:[1,1,0]
	v_pk_fma_f32 v[34:35], v[162:163], s[68:69], v[34:35] op_sel:[0,1,0] op_sel_hi:[1,1,1]
	v_cvt_scalef32_pk_f32_fp4 v[22:23], v197, 1.0
	v_pk_fma_f32 v[36:37], v[18:19], s[68:69], v[36:37] op_sel:[0,1,0] op_sel_hi:[1,1,1]
	v_cvt_scalef32_pk_f32_fp4 v[30:31], v197, 1.0 op_sel:[1,0,0]
	v_pk_fma_f32 v[38:39], v[20:21], s[68:69], v[38:39] op_sel:[0,1,0] op_sel_hi:[1,1,1]
	v_cvt_scalef32_pk_f32_fp4 v[2:3], v197, 1.0 op_sel:[0,1,0]
	v_pk_fma_f32 v[40:41], v[22:23], s[68:69], v[40:41] op_sel:[0,1,0] op_sel_hi:[1,1,1]
	v_cvt_scalef32_pk_f32_fp4 v[6:7], v197, 1.0 op_sel:[1,1,0]
	v_pk_fma_f32 v[42:43], v[30:31], s[68:69], v[42:43] op_sel:[0,1,0] op_sel_hi:[1,1,1]
	v_cvt_scalef32_pk_f32_fp4 v[160:161], v198, 1.0
	v_pk_fma_f32 v[44:45], v[2:3], s[68:69], v[44:45] op_sel:[0,1,0] op_sel_hi:[1,1,1]
	v_cvt_scalef32_pk_f32_fp4 v[162:163], v198, 1.0 op_sel:[1,0,0]
	v_pk_fma_f32 v[46:47], v[6:7], s[68:69], v[46:47] op_sel:[0,1,0] op_sel_hi:[1,1,1]
	v_cvt_scalef32_pk_f32_fp4 v[18:19], v198, 1.0 op_sel:[0,1,0]
	v_pk_fma_f32 v[48:49], v[160:161], s[68:69], v[48:49] op_sel:[0,1,0] op_sel_hi:[1,1,1]
	v_cvt_scalef32_pk_f32_fp4 v[20:21], v198, 1.0 op_sel:[1,1,0]
	v_pk_fma_f32 v[50:51], v[162:163], s[68:69], v[50:51] op_sel:[0,1,0] op_sel_hi:[1,1,1]
	v_cvt_scalef32_pk_f32_fp4 v[22:23], v199, 1.0
	v_pk_fma_f32 v[52:53], v[18:19], s[68:69], v[52:53] op_sel:[0,1,0] op_sel_hi:[1,1,1]
	v_cvt_scalef32_pk_f32_fp4 v[30:31], v199, 1.0 op_sel:[1,0,0]
	v_pk_fma_f32 v[54:55], v[20:21], s[68:69], v[54:55] op_sel:[0,1,0] op_sel_hi:[1,1,1]
	v_cvt_scalef32_pk_f32_fp4 v[2:3], v199, 1.0 op_sel:[0,1,0]
	v_pk_fma_f32 v[56:57], v[22:23], s[68:69], v[56:57] op_sel:[0,1,0] op_sel_hi:[1,1,1]
	v_cvt_scalef32_pk_f32_fp4 v[6:7], v199, 1.0 op_sel:[1,1,0]
	v_pk_fma_f32 v[58:59], v[30:31], s[68:69], v[58:59] op_sel:[0,1,0] op_sel_hi:[1,1,1]
	v_pk_fma_f32 v[60:61], v[2:3], s[68:69], v[60:61] op_sel:[0,1,0] op_sel_hi:[1,1,1]
	v_pk_fma_f32 v[62:63], v[6:7], s[68:69], v[62:63] op_sel:[0,1,0] op_sel_hi:[1,1,1]
	s_waitcnt vmcnt(4)
	v_cvt_scalef32_pk_f32_fp4 v[160:161], v200, 1.0
	v_cvt_scalef32_pk_f32_fp4 v[162:163], v200, 1.0 op_sel:[1,0,0]
	v_cvt_scalef32_pk_f32_fp4 v[18:19], v200, 1.0 op_sel:[0,1,0]
	v_pk_fma_f32 v[32:33], v[160:161], s[70:71], v[32:33] op_sel_hi:[1,0,1]
	v_cvt_scalef32_pk_f32_fp4 v[20:21], v200, 1.0 op_sel:[1,1,0]
	v_pk_fma_f32 v[34:35], v[162:163], s[70:71], v[34:35] op_sel_hi:[1,0,1]
	v_cvt_scalef32_pk_f32_fp4 v[22:23], v201, 1.0
	v_pk_fma_f32 v[36:37], v[18:19], s[70:71], v[36:37] op_sel_hi:[1,0,1]
	v_cvt_scalef32_pk_f32_fp4 v[30:31], v201, 1.0 op_sel:[1,0,0]
	v_pk_fma_f32 v[38:39], v[20:21], s[70:71], v[38:39] op_sel_hi:[1,0,1]
	v_cvt_scalef32_pk_f32_fp4 v[2:3], v201, 1.0 op_sel:[0,1,0]
	v_pk_fma_f32 v[40:41], v[22:23], s[70:71], v[40:41] op_sel_hi:[1,0,1]
	v_cvt_scalef32_pk_f32_fp4 v[6:7], v201, 1.0 op_sel:[1,1,0]
	v_pk_fma_f32 v[42:43], v[30:31], s[70:71], v[42:43] op_sel_hi:[1,0,1]
	v_cvt_scalef32_pk_f32_fp4 v[160:161], v202, 1.0
	v_pk_fma_f32 v[44:45], v[2:3], s[70:71], v[44:45] op_sel_hi:[1,0,1]
	v_cvt_scalef32_pk_f32_fp4 v[162:163], v202, 1.0 op_sel:[1,0,0]
	v_pk_fma_f32 v[46:47], v[6:7], s[70:71], v[46:47] op_sel_hi:[1,0,1]
	v_cvt_scalef32_pk_f32_fp4 v[18:19], v202, 1.0 op_sel:[0,1,0]
	v_pk_fma_f32 v[48:49], v[160:161], s[70:71], v[48:49] op_sel_hi:[1,0,1]
	v_cvt_scalef32_pk_f32_fp4 v[20:21], v202, 1.0 op_sel:[1,1,0]
	v_pk_fma_f32 v[50:51], v[162:163], s[70:71], v[50:51] op_sel_hi:[1,0,1]
	v_cvt_scalef32_pk_f32_fp4 v[22:23], v203, 1.0
	v_pk_fma_f32 v[52:53], v[18:19], s[70:71], v[52:53] op_sel_hi:[1,0,1]
	v_cvt_scalef32_pk_f32_fp4 v[30:31], v203, 1.0 op_sel:[1,0,0]
	v_pk_fma_f32 v[54:55], v[20:21], s[70:71], v[54:55] op_sel_hi:[1,0,1]
	v_cvt_scalef32_pk_f32_fp4 v[2:3], v203, 1.0 op_sel:[0,1,0]
	v_pk_fma_f32 v[56:57], v[22:23], s[70:71], v[56:57] op_sel_hi:[1,0,1]
	v_cvt_scalef32_pk_f32_fp4 v[6:7], v203, 1.0 op_sel:[1,1,0]
	v_pk_fma_f32 v[58:59], v[30:31], s[70:71], v[58:59] op_sel_hi:[1,0,1]
	v_pk_fma_f32 v[60:61], v[2:3], s[70:71], v[60:61] op_sel_hi:[1,0,1]
	v_pk_fma_f32 v[62:63], v[6:7], s[70:71], v[62:63] op_sel_hi:[1,0,1]
	s_waitcnt vmcnt(0)
	v_cvt_scalef32_pk_f32_fp4 v[160:161], v240, 1.0
	v_cvt_scalef32_pk_f32_fp4 v[162:163], v240, 1.0 op_sel:[1,0,0]
	v_cvt_scalef32_pk_f32_fp4 v[18:19], v240, 1.0 op_sel:[0,1,0]
	v_pk_fma_f32 v[32:33], v[160:161], s[70:71], v[32:33] op_sel:[0,1,0] op_sel_hi:[1,1,1]
	v_cvt_scalef32_pk_f32_fp4 v[20:21], v240, 1.0 op_sel:[1,1,0]
	v_pk_fma_f32 v[34:35], v[162:163], s[70:71], v[34:35] op_sel:[0,1,0] op_sel_hi:[1,1,1]
	v_cvt_scalef32_pk_f32_fp4 v[22:23], v241, 1.0
	v_pk_fma_f32 v[36:37], v[18:19], s[70:71], v[36:37] op_sel:[0,1,0] op_sel_hi:[1,1,1]
	v_cvt_scalef32_pk_f32_fp4 v[30:31], v241, 1.0 op_sel:[1,0,0]
	v_pk_fma_f32 v[38:39], v[20:21], s[70:71], v[38:39] op_sel:[0,1,0] op_sel_hi:[1,1,1]
	v_cvt_scalef32_pk_f32_fp4 v[2:3], v241, 1.0 op_sel:[0,1,0]
	v_pk_fma_f32 v[40:41], v[22:23], s[70:71], v[40:41] op_sel:[0,1,0] op_sel_hi:[1,1,1]
	v_cvt_scalef32_pk_f32_fp4 v[6:7], v241, 1.0 op_sel:[1,1,0]
	v_pk_fma_f32 v[42:43], v[30:31], s[70:71], v[42:43] op_sel:[0,1,0] op_sel_hi:[1,1,1]
	v_cvt_scalef32_pk_f32_fp4 v[160:161], v242, 1.0
	v_pk_fma_f32 v[44:45], v[2:3], s[70:71], v[44:45] op_sel:[0,1,0] op_sel_hi:[1,1,1]
	v_cvt_scalef32_pk_f32_fp4 v[162:163], v242, 1.0 op_sel:[1,0,0]
	v_pk_fma_f32 v[46:47], v[6:7], s[70:71], v[46:47] op_sel:[0,1,0] op_sel_hi:[1,1,1]
	v_cvt_scalef32_pk_f32_fp4 v[18:19], v242, 1.0 op_sel:[0,1,0]
	v_pk_fma_f32 v[48:49], v[160:161], s[70:71], v[48:49] op_sel:[0,1,0] op_sel_hi:[1,1,1]
	v_cvt_scalef32_pk_f32_fp4 v[20:21], v242, 1.0 op_sel:[1,1,0]
	v_pk_fma_f32 v[50:51], v[162:163], s[70:71], v[50:51] op_sel:[0,1,0] op_sel_hi:[1,1,1]
	v_cvt_scalef32_pk_f32_fp4 v[22:23], v243, 1.0
	v_pk_fma_f32 v[52:53], v[18:19], s[70:71], v[52:53] op_sel:[0,1,0] op_sel_hi:[1,1,1]
	v_cvt_scalef32_pk_f32_fp4 v[30:31], v243, 1.0 op_sel:[1,0,0]
	v_pk_fma_f32 v[54:55], v[20:21], s[70:71], v[54:55] op_sel:[0,1,0] op_sel_hi:[1,1,1]
	v_cvt_scalef32_pk_f32_fp4 v[2:3], v243, 1.0 op_sel:[0,1,0]
	v_pk_fma_f32 v[56:57], v[22:23], s[70:71], v[56:57] op_sel:[0,1,0] op_sel_hi:[1,1,1]
	v_cvt_scalef32_pk_f32_fp4 v[6:7], v243, 1.0 op_sel:[1,1,0]
	v_pk_fma_f32 v[58:59], v[30:31], s[70:71], v[58:59] op_sel:[0,1,0] op_sel_hi:[1,1,1]
	v_pk_fma_f32 v[60:61], v[2:3], s[70:71], v[60:61] op_sel:[0,1,0] op_sel_hi:[1,1,1]
	v_pk_fma_f32 v[62:63], v[6:7], s[70:71], v[62:63] op_sel:[0,1,0] op_sel_hi:[1,1,1]
	v_lshlrev_b32_e32 v1, 13, v4
	v_lshl_add_u32 v1, v0, 6, v1
	v_add_u32_e32 v2, 0x1000, v1
	global_load_dwordx4 v[64:67], v1, s[92:93] offset:0
	global_load_dwordx4 v[68:71], v1, s[92:93] offset:16
	global_load_dwordx4 v[72:75], v1, s[92:93] offset:32
	global_load_dwordx4 v[76:79], v1, s[92:93] offset:48
	global_load_dwordx4 v[80:83], v2, s[92:93] offset:0
	global_load_dwordx4 v[84:87], v2, s[92:93] offset:16
	global_load_dwordx4 v[88:91], v2, s[92:93] offset:32
	global_load_dwordx4 v[92:95], v2, s[92:93] offset:48
	v_add_u32_e32 v4, s79, v4
	v_cmp_lt_i32_e32 vcc, s84, v4
	s_or_b64 s[60:61], vcc, s[60:61]
	s_waitcnt vmcnt(7)
	v_pk_add_f32 v[64:65], v[64:65], v[32:33]
	v_pk_add_f32 v[66:67], v[66:67], v[34:35]
	s_waitcnt vmcnt(6)
	v_pk_add_f32 v[68:69], v[68:69], v[36:37]
	v_pk_add_f32 v[70:71], v[70:71], v[38:39]
	s_waitcnt vmcnt(5)
	v_pk_add_f32 v[72:73], v[72:73], v[40:41]
	v_pk_add_f32 v[74:75], v[74:75], v[42:43]
	s_waitcnt vmcnt(4)
	v_pk_add_f32 v[76:77], v[76:77], v[44:45]
	v_pk_add_f32 v[78:79], v[78:79], v[46:47]
	s_waitcnt vmcnt(3)
	v_pk_add_f32 v[80:81], v[80:81], v[48:49]
	v_pk_add_f32 v[82:83], v[82:83], v[50:51]
	s_waitcnt vmcnt(2)
	v_pk_add_f32 v[84:85], v[84:85], v[52:53]
	v_pk_add_f32 v[86:87], v[86:87], v[54:55]
	s_waitcnt vmcnt(1)
	v_pk_add_f32 v[88:89], v[88:89], v[56:57]
	v_pk_add_f32 v[90:91], v[90:91], v[58:59]
	s_waitcnt vmcnt(0)
	v_pk_add_f32 v[92:93], v[92:93], v[60:61]
	v_pk_add_f32 v[94:95], v[94:95], v[62:63]
	global_store_dwordx4 v1, v[64:67], s[92:93] offset:0
	global_store_dwordx4 v1, v[68:71], s[92:93] offset:16
	global_store_dwordx4 v1, v[72:75], s[92:93] offset:32
	global_store_dwordx4 v1, v[76:79], s[92:93] offset:48
	global_store_dwordx4 v2, v[80:83], s[92:93] offset:0
	global_store_dwordx4 v2, v[84:87], s[92:93] offset:16
	global_store_dwordx4 v2, v[88:91], s[92:93] offset:32
	global_store_dwordx4 v2, v[92:95], s[92:93] offset:48
	s_andn2_b64 exec, exec, s[60:61]
	s_cbranch_execz .LBB0_930
	s_branch .LBB0_920
